# split v_pk_fma_f32 into 2x v_fmac_f32 in the mm64 f32 LDS matmul loops (DN1 chunk prep + DN3), bit-identical math
# baseline (speedup 1.0000x reference)
; __device__ __forceinline__ void mm64(const float* At, const float* B, float (&acc)[4][4], int ty, int tx) {
;     f32x2 c2[4][2];
; #pragma unroll
;     for (int rr = 0; rr < 4; ++rr) { c2[rr][0] = (f32x2){acc[rr][0], acc[rr][1]}; c2[rr][1] = (f32x2){acc[rr][2], acc[rr][3]}; }
; #pragma unroll 8
;     for (int k = 0; k < 64; ++k) {
;         const f32x4 a = *(const f32x4*)(At + k * DLD + 4 * ty);
;         const f32x4 b = *(const f32x4*)(B + k * DLD + 4 * tx);
;         const f32x2 b01 = {b.x, b.y}, b23 = {b.z, b.w};
; #pragma unroll
;         for (int rr = 0; rr < 4; ++rr) {
;             const f32x2 a2 = {a[rr], a[rr]};
;             c2[rr][0] = __builtin_elementwise_fma(a2, b01, c2[rr][0]);
;             c2[rr][1] = __builtin_elementwise_fma(a2, b23, c2[rr][1]);
;         }
;     }
; #pragma unroll
;     for (int rr = 0; rr < 4; ++rr) { acc[rr][0] = c2[rr][0].x; acc[rr][1] = c2[rr][0].y; acc[rr][2] = c2[rr][1].x; acc[rr][3] = c2[rr][1].y; }
; }
; __device__ __forceinline__ void dn3_item(const Params& p, int l, int item, unsigned char* lds) {
;     ...
;     float acc[4][4];
; #pragma unroll
;     for (int rr = 0; rr < 4; ++rr) { const f32x4 o = *(const f32x4*)(DNO + (4 * ty + rr) * 64 + 4 * tx); acc[rr][0] = o.x; acc[rr][1] = o.y; acc[rr][2] = o.z; acc[rr][3] = o.w; }
;     mm64(B0, B1, acc, ty, tx);
.LBB0_181:
	ds_read_b128 v[238:241], v21 offset:272
	ds_read_b128 v[242:245], v34 offset:272
	s_waitcnt lgkmcnt(2)
	v_fmac_f32_e32 v14, v22, v26
	v_fmac_f32_e32 v15, v22, v27
	v_fmac_f32_e32 v16, v22, v28
	v_fmac_f32_e32 v17, v22, v29
	v_fmac_f32_e32 v10, v23, v26
	v_fmac_f32_e32 v11, v23, v27
	v_fmac_f32_e32 v12, v23, v28
	v_fmac_f32_e32 v13, v23, v29
	v_fmac_f32_e32 v6, v24, v26
	v_fmac_f32_e32 v7, v24, v27
	v_fmac_f32_e32 v8, v24, v28
	v_fmac_f32_e32 v9, v24, v29
	v_fmac_f32_e32 v2, v25, v26
	v_fmac_f32_e32 v3, v25, v27
	v_fmac_f32_e32 v4, v25, v28
	v_fmac_f32_e32 v5, v25, v29
	ds_read_b128 v[22:25], v21 offset:544
	ds_read_b128 v[26:29], v34 offset:544
	s_waitcnt lgkmcnt(2)
	v_fmac_f32_e32 v14, v238, v242
	v_fmac_f32_e32 v15, v238, v243
	v_fmac_f32_e32 v16, v238, v244
	v_fmac_f32_e32 v17, v238, v245
	v_fmac_f32_e32 v10, v239, v242
	v_fmac_f32_e32 v11, v239, v243
	v_fmac_f32_e32 v12, v239, v244
	v_fmac_f32_e32 v13, v239, v245
	v_fmac_f32_e32 v6, v240, v242
	v_fmac_f32_e32 v7, v240, v243
	v_fmac_f32_e32 v8, v240, v244
	v_fmac_f32_e32 v9, v240, v245
	v_fmac_f32_e32 v2, v241, v242
	v_fmac_f32_e32 v3, v241, v243
	v_fmac_f32_e32 v4, v241, v244
	v_fmac_f32_e32 v5, v241, v245
	ds_read_b128 v[238:241], v21 offset:816
	ds_read_b128 v[242:245], v34 offset:816
	s_waitcnt lgkmcnt(2)
	v_fmac_f32_e32 v14, v22, v26
	v_fmac_f32_e32 v15, v22, v27
	v_fmac_f32_e32 v16, v22, v28
	v_fmac_f32_e32 v17, v22, v29
	v_fmac_f32_e32 v10, v23, v26
	v_fmac_f32_e32 v11, v23, v27
	v_fmac_f32_e32 v12, v23, v28
	v_fmac_f32_e32 v13, v23, v29
	v_fmac_f32_e32 v6, v24, v26
	v_fmac_f32_e32 v7, v24, v27
	v_fmac_f32_e32 v8, v24, v28
	v_fmac_f32_e32 v9, v24, v29
	v_fmac_f32_e32 v2, v25, v26
	v_fmac_f32_e32 v3, v25, v27
	v_fmac_f32_e32 v4, v25, v28
	v_fmac_f32_e32 v5, v25, v29
	ds_read_b128 v[22:25], v21 offset:1088
	ds_read_b128 v[26:29], v34 offset:1088
	s_waitcnt lgkmcnt(2)
	v_fmac_f32_e32 v14, v238, v242
	v_fmac_f32_e32 v15, v238, v243
	v_fmac_f32_e32 v16, v238, v244
	v_fmac_f32_e32 v17, v238, v245
	v_fmac_f32_e32 v10, v239, v242
	v_fmac_f32_e32 v11, v239, v243
	v_fmac_f32_e32 v12, v239, v244
	v_fmac_f32_e32 v13, v239, v245
	v_fmac_f32_e32 v6, v240, v242
	v_fmac_f32_e32 v7, v240, v243
	v_fmac_f32_e32 v8, v240, v244
	v_fmac_f32_e32 v9, v240, v245
	v_fmac_f32_e32 v2, v241, v242
	v_fmac_f32_e32 v3, v241, v243
	v_fmac_f32_e32 v4, v241, v244
	v_fmac_f32_e32 v5, v241, v245
	ds_read_b128 v[238:241], v21 offset:1360
	ds_read_b128 v[242:245], v34 offset:1360
	s_waitcnt lgkmcnt(2)
	v_fmac_f32_e32 v14, v22, v26
	v_fmac_f32_e32 v15, v22, v27
	v_fmac_f32_e32 v16, v22, v28
	v_fmac_f32_e32 v17, v22, v29
	v_fmac_f32_e32 v10, v23, v26
	v_fmac_f32_e32 v11, v23, v27
	v_fmac_f32_e32 v12, v23, v28
	v_fmac_f32_e32 v13, v23, v29
	v_fmac_f32_e32 v6, v24, v26
	v_fmac_f32_e32 v7, v24, v27
	v_fmac_f32_e32 v8, v24, v28
	v_fmac_f32_e32 v9, v24, v29
	v_fmac_f32_e32 v2, v25, v26
	v_fmac_f32_e32 v3, v25, v27
	v_fmac_f32_e32 v4, v25, v28
	v_fmac_f32_e32 v5, v25, v29
	ds_read_b128 v[22:25], v21 offset:1632
	ds_read_b128 v[26:29], v34 offset:1632
	s_waitcnt lgkmcnt(2)
	v_fmac_f32_e32 v14, v238, v242
	v_fmac_f32_e32 v15, v238, v243
	v_fmac_f32_e32 v16, v238, v244
	v_fmac_f32_e32 v17, v238, v245
	v_fmac_f32_e32 v10, v239, v242
	v_fmac_f32_e32 v11, v239, v243
	v_fmac_f32_e32 v12, v239, v244
	v_fmac_f32_e32 v13, v239, v245
	v_fmac_f32_e32 v6, v240, v242
	v_fmac_f32_e32 v7, v240, v243
	v_fmac_f32_e32 v8, v240, v244
	v_fmac_f32_e32 v9, v240, v245
	v_fmac_f32_e32 v2, v241, v242
	v_fmac_f32_e32 v3, v241, v243
	v_fmac_f32_e32 v4, v241, v244
	v_fmac_f32_e32 v5, v241, v245
	ds_read_b128 v[238:241], v21 offset:1904
	ds_read_b128 v[242:245], v34 offset:1904
	s_waitcnt lgkmcnt(2)
	v_fmac_f32_e32 v14, v22, v26
	v_fmac_f32_e32 v15, v22, v27
	v_fmac_f32_e32 v16, v22, v28
	v_fmac_f32_e32 v17, v22, v29
	v_fmac_f32_e32 v10, v23, v26
	v_fmac_f32_e32 v11, v23, v27
	v_fmac_f32_e32 v12, v23, v28
	v_fmac_f32_e32 v13, v23, v29
	v_fmac_f32_e32 v6, v24, v26
	v_fmac_f32_e32 v7, v24, v27
	v_fmac_f32_e32 v8, v24, v28
	v_fmac_f32_e32 v9, v24, v29
	v_fmac_f32_e32 v2, v25, v26
	v_fmac_f32_e32 v3, v25, v27
	v_fmac_f32_e32 v4, v25, v28
	v_fmac_f32_e32 v5, v25, v29
	s_addk_i32 s0, 0x880
	v_add_u32_e32 v21, s0, v19
	v_add_u32_e32 v34, s0, v20
	ds_read_b128 v[22:25], v21
	ds_read_b128 v[26:29], v34
	s_waitcnt lgkmcnt(2)
	v_fmac_f32_e32 v14, v238, v242
	v_fmac_f32_e32 v15, v238, v243
	v_fmac_f32_e32 v16, v238, v244
	v_fmac_f32_e32 v17, v238, v245
	v_fmac_f32_e32 v10, v239, v242
	v_fmac_f32_e32 v11, v239, v243
	v_fmac_f32_e32 v12, v239, v244
	v_fmac_f32_e32 v13, v239, v245
	v_fmac_f32_e32 v6, v240, v242
	v_fmac_f32_e32 v7, v240, v243
	v_fmac_f32_e32 v8, v240, v244
	v_fmac_f32_e32 v9, v240, v245
	v_fmac_f32_e32 v2, v241, v242
	v_fmac_f32_e32 v3, v241, v243
	v_fmac_f32_e32 v4, v241, v244
	v_fmac_f32_e32 v5, v241, v245
	s_cmpk_lg_i32 s0, 0x4400
	s_cbranch_scc1 .LBB0_181
; __device__ __forceinline__ uint32_t pk2(float lo, float hi) { typedef float f2 __attribute__((ext_vector_type(2))); const f2 v = {lo, hi}; return __builtin_bit_cast(uint32_t, __builtin_convertvector(v, bf16x2_t)); }
; __device__ __forceinline__ float bflo(uint32_t u) { return __uint_as_float(u << 16); }
; __device__ __forceinline__ float bfhi(uint32_t u) { return __uint_as_float(u & 0xffff0000u); }
; __device__ __forceinline__ float siluf(float x) { return x * __builtin_amdgcn_rcpf(1.f + __expf(-x)); }
; __device__ __forceinline__ void dn3_item(const Params& p, int l, int item, unsigned char* lds) {
;     ...
;     const f32x4 gn = *(const f32x4*)(p.dn_onorm + l * 64 + 4 * tx);
; #pragma unroll
;     for (int rr = 0; rr < 4; ++rr) {
;         float ss = acc[rr][0] * acc[rr][0] + acc[rr][1] * acc[rr][1] + acc[rr][2] * acc[rr][2] + acc[rr][3] * acc[rr][3];
;         ss += __shfl_xor(ss, 1); ss += __shfl_xor(ss, 2); ss += __shfl_xor(ss, 4); ss += __shfl_xor(ss, 8);
;         const float rs = rsqrtf(ss * (1.f / 64.f) + EPS);
;         const size_t rowoff = (size_t)(t0 + 4 * ty + rr) * PBW + PB_DN + hd * 64 + 4 * tx;
;         const u32x2 z = *(const u32x2*)(PB + rowoff + 1536);
;         const float o0 = acc[rr][0] * rs * gn.x * siluf(bflo(z.x)), o1 = acc[rr][1] * rs * gn.y * siluf(bfhi(z.x));
;         const float o2 = acc[rr][2] * rs * gn.z * siluf(bflo(z.y)), o3 = acc[rr][3] * rs * gn.w * siluf(bfhi(z.y));
;         u32x2 w = {pk2(o0, o1), pk2(o2, o3)};
;         *(u32x2*)(PB + rowoff) = w;
;     }
	s_waitcnt lgkmcnt(0)
	s_lshl_b32 s0, s88, 3
	s_and_b32 s0, s0, 0x3ffffc0
	v_add_u32_e32 v44, s0, v0
	s_lshl_b32 s0, s88, 7
	s_and_b32 s0, s0, 0x380
	s_add_u32 s0, s71, s0
	s_addc_u32 s1, s72, 0
	v_lshlrev_b32_e32 v0, 1, v18
	v_lshl_add_u64 v[30:31], s[0:1], 0, v[0:1]
	v_mad_i64_i32 v[24:25], s[0:1], v44, s60, v[30:31]
	global_load_dwordx2 v[26:27], v[24:25], off offset:3072
	v_lshlrev_b32_e32 v0, 2, v18
	v_and_b32_e32 v38, 64, v228
	v_pk_mul_f32 v[28:29], v[10:11], v[10:11]
	global_load_dwordx4 v[18:21], v0, s[24:25]
	v_pk_mul_f32 v[32:33], v[14:15], v[14:15]
	s_mov_b32 s0, 0x358637bd
	v_add_u32_e32 v0, 64, v38
	v_mov_b32_e32 v38, v28
	v_or_b32_e32 v28, 1, v44
	v_mov_b64_e32 v[22:23], s[0:1]
	v_mov_b32_e32 v39, v32
	v_mov_b32_e32 v32, v29
	v_mad_i64_i32 v[28:29], s[0:1], v28, s60, v[30:31]
	global_load_dwordx2 v[42:43], v[28:29], off offset:3072
	v_xor_b32_e32 v45, 1, v228
	v_xor_b32_e32 v46, 2, v228
	v_pk_mul_f32 v[36:37], v[12:13], v[12:13]
	v_cmp_lt_i32_e32 vcc, v45, v0
	v_xor_b32_e32 v47, 4, v228
	v_mov_b32_e32 v40, v36
	v_cndmask_b32_e32 v36, v228, v45, vcc
	v_cmp_lt_i32_e32 vcc, v46, v0
	v_xor_b32_e32 v48, 8, v228
	v_pk_mul_f32 v[34:35], v[16:17], v[16:17]
	v_lshlrev_b32_e32 v49, 2, v36
	v_cndmask_b32_e32 v36, v228, v46, vcc
	v_cmp_lt_i32_e32 vcc, v47, v0
	v_mov_b32_e32 v41, v34
	v_mov_b32_e32 v34, v37
	v_cndmask_b32_e32 v37, v228, v47, vcc
	v_cmp_lt_i32_e32 vcc, v48, v0
	v_pk_add_f32 v[32:33], v[38:39], v[32:33]
	v_lshlrev_b32_e32 v50, 2, v36
	v_cndmask_b32_e32 v0, v228, v48, vcc
	v_lshlrev_b32_e32 v51, 2, v0
	v_or_b32_e32 v0, 2, v44
	v_lshlrev_b32_e32 v48, 2, v37
	v_or_b32_e32 v38, 3, v44
	v_mad_i64_i32 v[36:37], s[0:1], v0, s60, v[30:31]
	v_pk_add_f32 v[32:33], v[40:41], v[32:33]
	v_mad_i64_i32 v[30:31], s[0:1], v38, s60, v[30:31]
	global_load_dwordx2 v[38:39], v[36:37], off offset:3072
	global_load_dwordx2 v[40:41], v[30:31], off offset:3072
	v_pk_add_f32 v[32:33], v[34:35], v[32:33]
	ds_bpermute_b32 v35, v49, v33
	ds_bpermute_b32 v34, v49, v32
	s_mov_b32 s4, 0x3c800000
	s_mov_b32 s0, 0x800000
	s_waitcnt lgkmcnt(0)
	v_pk_add_f32 v[32:33], v[32:33], v[34:35]
	ds_bpermute_b32 v35, v50, v33
	ds_bpermute_b32 v34, v50, v32
	s_waitcnt lgkmcnt(0)
	v_pk_add_f32 v[32:33], v[32:33], v[34:35]
	ds_bpermute_b32 v35, v48, v33
	ds_bpermute_b32 v34, v48, v32
	s_waitcnt lgkmcnt(0)
	v_pk_add_f32 v[32:33], v[32:33], v[34:35]
	ds_bpermute_b32 v35, v51, v33
	ds_bpermute_b32 v34, v51, v32
	s_waitcnt lgkmcnt(0)
	v_pk_add_f32 v[32:33], v[32:33], v[34:35]
	s_nop 0
	v_pk_fma_f32 v[32:33], v[32:33], s[4:5], v[22:23] op_sel_hi:[1,0,0]
	s_waitcnt vmcnt(4)
	v_lshlrev_b32_e32 v34, 16, v26
	v_mul_f32_e32 v0, 0x4b800000, v33
	v_cmp_gt_f32_e32 vcc, s0, v33
	v_and_b32_e32 v35, 0xffff0000, v26
	v_lshlrev_b32_e32 v26, 16, v27
	v_and_b32_e32 v27, 0xffff0000, v27
	v_cndmask_b32_e32 v0, v33, v0, vcc
	v_mul_f32_e32 v33, 0xbfb8aa3b, v34
	v_mul_f32_e32 v44, 0xbfb8aa3b, v35
	v_mul_f32_e32 v45, 0xbfb8aa3b, v26
	v_mul_f32_e32 v46, 0xbfb8aa3b, v27
	v_exp_f32_e32 v33, v33
	v_exp_f32_e32 v44, v44
	v_exp_f32_e32 v45, v45
	v_exp_f32_e32 v46, v46
	v_rsq_f32_e32 v0, v0
	v_add_f32_e32 v33, 1.0, v33
	v_add_f32_e32 v47, 1.0, v44
	v_add_f32_e32 v52, 1.0, v45
	v_add_f32_e32 v53, 1.0, v46
	v_rcp_f32_e32 v44, v33
	v_rcp_f32_e32 v45, v47
	v_rcp_f32_e32 v46, v52
	v_rcp_f32_e32 v47, v53
	v_mul_f32_e32 v33, 0x45800000, v0
	v_cndmask_b32_e32 v0, v0, v33, vcc
	v_pk_mul_f32 v[14:15], v[14:15], v[0:1] op_sel_hi:[1,0]
	v_pk_mul_f32 v[16:17], v[16:17], v[0:1] op_sel_hi:[1,0]
	v_mul_f32_e32 v0, 0x4b800000, v32
	v_cmp_gt_f32_e32 vcc, s0, v32
	v_pk_mul_f32 v[34:35], v[44:45], v[34:35]
	v_pk_mul_f32 v[26:27], v[46:47], v[26:27]
	s_waitcnt vmcnt(3)
	v_pk_mul_f32 v[14:15], v[18:19], v[14:15]
	v_pk_mul_f32 v[16:17], v[20:21], v[16:17]
	v_cndmask_b32_e32 v0, v32, v0, vcc
	v_pk_mul_f32 v[14:15], v[34:35], v[14:15]
	v_pk_mul_f32 v[16:17], v[26:27], v[16:17]
	v_rsq_f32_e32 v0, v0
	v_cvt_pk_bf16_f32 v14, v14, v15
	v_cvt_pk_bf16_f32 v15, v16, v17
	global_store_dwordx2 v[24:25], v[14:15], off
	s_waitcnt vmcnt(3)
; __device__ __forceinline__ uint32_t pk2(float lo, float hi) { typedef float f2 __attribute__((ext_vector_type(2))); const f2 v = {lo, hi}; return __builtin_bit_cast(uint32_t, __builtin_convertvector(v, bf16x2_t)); }
; __device__ __forceinline__ float bflo(uint32_t u) { return __uint_as_float(u << 16); }
; __device__ __forceinline__ float bfhi(uint32_t u) { return __uint_as_float(u & 0xffff0000u); }
; __device__ __forceinline__ float siluf(float x) { return x * __builtin_amdgcn_rcpf(1.f + __expf(-x)); }
; __device__ __forceinline__ void dn3_item(const Params& p, int l, int item, unsigned char* lds) {
;     ...
;     const f32x4 gn = *(const f32x4*)(p.dn_onorm + l * 64 + 4 * tx);
; #pragma unroll
;     for (int rr = 0; rr < 4; ++rr) {
;         float ss = acc[rr][0] * acc[rr][0] + acc[rr][1] * acc[rr][1] + acc[rr][2] * acc[rr][2] + acc[rr][3] * acc[rr][3];
;         ss += __shfl_xor(ss, 1); ss += __shfl_xor(ss, 2); ss += __shfl_xor(ss, 4); ss += __shfl_xor(ss, 8);
;         const float rs = rsqrtf(ss * (1.f / 64.f) + EPS);
;         const size_t rowoff = (size_t)(t0 + 4 * ty + rr) * PBW + PB_DN + hd * 64 + 4 * tx;
;         const u32x2 z = *(const u32x2*)(PB + rowoff + 1536);
;         const float o0 = acc[rr][0] * rs * gn.x * siluf(bflo(z.x)), o1 = acc[rr][1] * rs * gn.y * siluf(bfhi(z.x));
;         const float o2 = acc[rr][2] * rs * gn.z * siluf(bflo(z.y)), o3 = acc[rr][3] * rs * gn.w * siluf(bfhi(z.y));
;         u32x2 w = {pk2(o0, o1), pk2(o2, o3)};
;         *(u32x2*)(PB + rowoff) = w;
;     }
	v_lshlrev_b32_e32 v14, 16, v42
	v_mul_f32_e32 v15, 0xbfb8aa3b, v14
	v_exp_f32_e32 v16, v15
	v_mul_f32_e32 v15, 0x45800000, v0
	v_cndmask_b32_e32 v0, v0, v15, vcc
	v_and_b32_e32 v15, 0xffff0000, v42
	v_mul_f32_e32 v17, 0xbfb8aa3b, v15
	v_exp_f32_e32 v17, v17
	v_lshlrev_b32_e32 v24, 16, v43
	v_and_b32_e32 v25, 0xffff0000, v43
	v_add_f32_e32 v16, 1.0, v16
	v_add_f32_e32 v17, 1.0, v17
	v_mul_f32_e32 v26, 0xbfb8aa3b, v24
	v_mul_f32_e32 v27, 0xbfb8aa3b, v25
	v_rcp_f32_e32 v16, v16
	v_rcp_f32_e32 v17, v17
	v_exp_f32_e32 v26, v26
	v_exp_f32_e32 v27, v27
	v_pk_mul_f32 v[10:11], v[10:11], v[0:1] op_sel_hi:[1,0]
	v_pk_mul_f32 v[14:15], v[16:17], v[14:15]
	v_add_f32_e32 v16, 1.0, v26
	v_add_f32_e32 v17, 1.0, v27
	v_rcp_f32_e32 v16, v16
	v_rcp_f32_e32 v17, v17
	v_pk_mul_f32 v[10:11], v[18:19], v[10:11]
	v_pk_mul_f32 v[12:13], v[12:13], v[0:1] op_sel_hi:[1,0]
	v_pk_mul_f32 v[10:11], v[14:15], v[10:11]
	v_pk_mul_f32 v[12:13], v[20:21], v[12:13]
	v_pk_mul_f32 v[14:15], v[16:17], v[24:25]
	v_cvt_pk_bf16_f32 v10, v10, v11
	v_pk_mul_f32 v[12:13], v[14:15], v[12:13]
	v_pk_mul_f32 v[24:25], v[2:3], v[2:3]
	v_cvt_pk_bf16_f32 v11, v12, v13
	v_pk_mul_f32 v[12:13], v[6:7], v[6:7]
	v_pk_mul_f32 v[14:15], v[8:9], v[8:9]
	v_pk_mul_f32 v[26:27], v[4:5], v[4:5]
	v_mov_b32_e32 v32, v24
	v_mov_b32_e32 v33, v12
	v_mov_b32_e32 v12, v25
	v_pk_add_f32 v[12:13], v[32:33], v[12:13]
	v_mov_b32_e32 v24, v26
	v_mov_b32_e32 v25, v14
	v_pk_add_f32 v[12:13], v[24:25], v[12:13]
	v_mov_b32_e32 v14, v27
	v_pk_add_f32 v[12:13], v[14:15], v[12:13]
	ds_bpermute_b32 v15, v49, v13
	ds_bpermute_b32 v14, v49, v12
	s_waitcnt vmcnt(2)
	v_lshlrev_b32_e32 v16, 16, v38
	v_mul_f32_e32 v0, 0xbfb8aa3b, v16
	v_exp_f32_e32 v0, v0
	v_and_b32_e32 v17, 0xffff0000, v38
	s_waitcnt lgkmcnt(0)
	v_pk_add_f32 v[12:13], v[12:13], v[14:15]
	ds_bpermute_b32 v15, v50, v13
	ds_bpermute_b32 v14, v50, v12
	v_add_f32_e32 v0, 1.0, v0
	v_rcp_f32_e32 v24, v0
	v_mul_f32_e32 v0, 0xbfb8aa3b, v17
	v_exp_f32_e32 v0, v0
	s_waitcnt lgkmcnt(0)
	v_pk_add_f32 v[12:13], v[12:13], v[14:15]
	ds_bpermute_b32 v15, v48, v13
	ds_bpermute_b32 v14, v48, v12
	v_add_f32_e32 v0, 1.0, v0
	v_lshlrev_b32_e32 v26, 16, v39
	v_rcp_f32_e32 v25, v0
	v_and_b32_e32 v27, 0xffff0000, v39
	s_waitcnt lgkmcnt(0)
	v_pk_add_f32 v[12:13], v[12:13], v[14:15]
	v_mul_f32_e32 v0, 0xbfb8aa3b, v26
	ds_bpermute_b32 v15, v51, v13
	ds_bpermute_b32 v14, v51, v12
	v_exp_f32_e32 v0, v0
	v_mul_f32_e32 v32, 0xbfb8aa3b, v27
	v_exp_f32_e32 v33, v32
	global_store_dwordx2 v[28:29], v[10:11], off
	v_add_f32_e32 v0, 1.0, v0
	s_waitcnt lgkmcnt(0)
	v_pk_add_f32 v[12:13], v[12:13], v[14:15]
	v_rcp_f32_e32 v32, v0
	v_add_f32_e32 v0, 1.0, v33
	v_pk_fma_f32 v[12:13], v[12:13], s[4:5], v[22:23] op_sel_hi:[1,0,0]
	v_rcp_f32_e32 v33, v0
	v_mul_f32_e32 v0, 0x4b800000, v13
	v_cmp_gt_f32_e32 vcc, s0, v13
	v_pk_mul_f32 v[10:11], v[24:25], v[16:17]
	v_pk_mul_f32 v[14:15], v[32:33], v[26:27]
	v_cndmask_b32_e32 v0, v13, v0, vcc
	v_rsq_f32_e32 v0, v0
	s_nop 0
	v_mul_f32_e32 v13, 0x45800000, v0
	v_cndmask_b32_e32 v0, v0, v13, vcc
	v_pk_mul_f32 v[6:7], v[6:7], v[0:1] op_sel_hi:[1,0]
	v_pk_mul_f32 v[8:9], v[8:9], v[0:1] op_sel_hi:[1,0]
	v_mul_f32_e32 v0, 0x4b800000, v12
	v_cmp_gt_f32_e32 vcc, s0, v12
	v_pk_mul_f32 v[6:7], v[18:19], v[6:7]
	v_pk_mul_f32 v[8:9], v[20:21], v[8:9]
	v_cndmask_b32_e32 v0, v12, v0, vcc
	v_pk_mul_f32 v[6:7], v[10:11], v[6:7]
	v_pk_mul_f32 v[8:9], v[14:15], v[8:9]
	v_rsq_f32_e32 v0, v0
	v_cvt_pk_bf16_f32 v6, v6, v7
	v_cvt_pk_bf16_f32 v7, v8, v9
	global_store_dwordx2 v[36:37], v[6:7], off
	s_waitcnt vmcnt(3)
	v_lshlrev_b32_e32 v6, 16, v40
	v_mul_f32_e32 v7, 0xbfb8aa3b, v6
	v_exp_f32_e32 v8, v7
	v_mul_f32_e32 v7, 0x45800000, v0
	v_cndmask_b32_e32 v0, v0, v7, vcc
	v_and_b32_e32 v7, 0xffff0000, v40
	v_mul_f32_e32 v9, 0xbfb8aa3b, v7
	v_exp_f32_e32 v9, v9
	v_lshlrev_b32_e32 v10, 16, v41
	v_and_b32_e32 v11, 0xffff0000, v41
	v_add_f32_e32 v8, 1.0, v8
	v_add_f32_e32 v9, 1.0, v9
	v_mul_f32_e32 v12, 0xbfb8aa3b, v10
	v_mul_f32_e32 v13, 0xbfb8aa3b, v11
	v_rcp_f32_e32 v8, v8
	v_rcp_f32_e32 v9, v9
	v_exp_f32_e32 v12, v12
	v_exp_f32_e32 v13, v13
	v_pk_mul_f32 v[2:3], v[2:3], v[0:1] op_sel_hi:[1,0]
	v_pk_mul_f32 v[6:7], v[8:9], v[6:7]
	v_add_f32_e32 v8, 1.0, v12
	v_add_f32_e32 v9, 1.0, v13
	v_rcp_f32_e32 v8, v8
	v_rcp_f32_e32 v9, v9
	v_pk_mul_f32 v[2:3], v[18:19], v[2:3]
	v_pk_mul_f32 v[4:5], v[4:5], v[0:1] op_sel_hi:[1,0]
	v_pk_mul_f32 v[2:3], v[6:7], v[2:3]
	v_pk_mul_f32 v[4:5], v[20:21], v[4:5]
	v_pk_mul_f32 v[6:7], v[8:9], v[10:11]
	v_cvt_pk_bf16_f32 v2, v2, v3
	v_pk_mul_f32 v[4:5], v[6:7], v[4:5]
	s_nop 0
	v_cvt_pk_bf16_f32 v3, v4, v5
	global_store_dwordx2 v[30:31], v[2:3], off
	s_branch .LBB0_136

; __device__ __forceinline__ float bflo(uint32_t u) { return __uint_as_float(u << 16); }
; __device__ __forceinline__ float bfhi(uint32_t u) { return __uint_as_float(u & 0xffff0000u); }
; __device__ __forceinline__ void dn_conv16(const bf16_t* PB, const float* cw, int t0, int i, int col, int ch, float (&o)[16]) {
;     ...
;     for (int tap = 0; tap < 4; ++tap) {
;         const int mm = t0 + i - 3 + tap;
;         if (mm >= 0) {
;             const u32x4 x0 = *(const u32x4*)(PB + (size_t)mm * PBW + col);
;             const u32x4 x1 = *(const u32x4*)(PB + (size_t)mm * PBW + col + 8);
;             const float* w = cw + tap * 1536 + ch;
;             const f32x4 w0 = *(const f32x4*)w, w1 = *(const f32x4*)(w + 4), w2 = *(const f32x4*)(w + 8), w3 = *(const f32x4*)(w + 12);
;             o[0] += w0.x * bflo(x0.x); o[1] += w0.y * bfhi(x0.x); o[2] += w0.z * bflo(x0.y); o[3] += w0.w * bfhi(x0.y);
;             o[4] += w1.x * bflo(x0.z); o[5] += w1.y * bfhi(x0.z); o[6] += w1.z * bflo(x0.w); o[7] += w1.w * bfhi(x0.w);
;             o[8] += w2.x * bflo(x1.x); o[9] += w2.y * bfhi(x1.x); o[10] += w2.z * bflo(x1.y); o[11] += w2.w * bfhi(x1.y);
;             o[12] += w3.x * bflo(x1.z); o[13] += w3.y * bfhi(x1.z); o[14] += w3.z * bflo(x1.w); o[15] += w3.w * bfhi(x1.w);
;         }
;     }
.LBB0_559:
	s_or_b64 exec, exec, s[0:1]
	v_cmp_lt_i32_e64 s[40:41], 1, v2
	v_add_u32_e32 v65, -2, v2
	s_and_saveexec_b64 s[0:1], s[40:41]
	s_cbranch_execz .LBB0_561
	v_mov_b64_e32 v[18:19], s[28:29]
	v_mad_u64_u32 v[18:19], s[6:7], v65, s60, v[18:19]
	v_mov_b32_e32 v17, v1
	v_lshl_add_u64 v[22:23], v[18:19], 0, v[16:17]
	global_load_dwordx4 v[18:21], v[22:23], off offset:16
	s_nop 0
	global_load_dwordx4 v[22:25], v[22:23], off
	s_mov_b64 s[6:7], 0x1800
	v_add_co_u32_e32 v26, vcc, s19, v52
	v_lshl_add_u64 v[38:39], v[52:53], 0, s[6:7]
	s_nop 0
	v_addc_co_u32_e32 v27, vcc, 0, v53, vcc
	global_load_dwordx4 v[26:29], v[26:27], off offset:2048
	s_nop 0
	global_load_dwordx4 v[30:33], v[38:39], off offset:48
	global_load_dwordx4 v[34:37], v[38:39], off offset:32
	s_nop 0
	global_load_dwordx4 v[38:41], v[38:39], off offset:16
	s_waitcnt vmcnt(4)
	v_lshlrev_b32_e32 v42, 16, v22
	v_and_b32_e32 v43, 0xffff0000, v22
	v_lshlrev_b32_e32 v22, 16, v23
	v_and_b32_e32 v23, 0xffff0000, v23
	s_waitcnt vmcnt(3)
	v_fmac_f32_e32 v48, v28, v22
	v_fmac_f32_e32 v49, v29, v23
	v_lshlrev_b32_e32 v22, 16, v24
	v_and_b32_e32 v23, 0xffff0000, v24
	s_waitcnt vmcnt(0)
	v_fmac_f32_e32 v12, v38, v22
	v_fmac_f32_e32 v13, v39, v23
	v_lshlrev_b32_e32 v22, 16, v25
	v_and_b32_e32 v23, 0xffff0000, v25
	v_fmac_f32_e32 v10, v40, v22
	v_fmac_f32_e32 v11, v41, v23
	v_lshlrev_b32_e32 v22, 16, v18
	v_and_b32_e32 v23, 0xffff0000, v18
	v_lshlrev_b32_e32 v18, 16, v19
	v_and_b32_e32 v19, 0xffff0000, v19
	v_fmac_f32_e32 v4, v36, v18
	v_fmac_f32_e32 v5, v37, v19
	v_lshlrev_b32_e32 v18, 16, v20
	v_and_b32_e32 v19, 0xffff0000, v20
	v_fmac_f32_e32 v6, v30, v18
	v_fmac_f32_e32 v7, v31, v19
	v_and_b32_e32 v19, 0xffff0000, v21
	v_lshlrev_b32_e32 v18, 16, v21
	v_fma_f32 v30, v32, v18, v14
	v_fma_f32 v31, v33, v19, v15
	v_fmac_f32_e32 v50, v26, v42
	v_fmac_f32_e32 v51, v27, v43
	v_fmac_f32_e32 v8, v34, v22
	v_fmac_f32_e32 v9, v35, v23
	v_mov_b64_e32 v[14:15], v[30:31]
.LBB0_561:
	s_or_b64 exec, exec, s[0:1]
	v_cmp_lt_i32_e64 s[44:45], 0, v2
	v_add_u32_e32 v66, -1, v2
	s_and_saveexec_b64 s[0:1], s[44:45]
	s_cbranch_execz .LBB0_563
	v_mov_b64_e32 v[18:19], s[28:29]
	v_mad_u64_u32 v[18:19], s[6:7], v66, s60, v[18:19]
	v_mov_b32_e32 v17, v1
	s_mov_b64 s[6:7], 0x3000
	v_lshl_add_u64 v[22:23], v[18:19], 0, v[16:17]
	v_lshl_add_u64 v[38:39], v[52:53], 0, s[6:7]
	s_movk_i32 s6, 0x3000
	global_load_dwordx4 v[18:21], v[22:23], off offset:16
	s_nop 0
	global_load_dwordx4 v[22:25], v[22:23], off
	v_add_co_u32_e32 v26, vcc, s6, v52
	s_waitcnt vmcnt(0)
	v_lshlrev_b32_e32 v42, 16, v22
	v_addc_co_u32_e32 v27, vcc, 0, v53, vcc
	global_load_dwordx4 v[26:29], v[26:27], off
	s_nop 0
	global_load_dwordx4 v[30:33], v[38:39], off offset:48
	global_load_dwordx4 v[34:37], v[38:39], off offset:32
	s_nop 0
	global_load_dwordx4 v[38:41], v[38:39], off offset:16
	v_and_b32_e32 v43, 0xffff0000, v22
	v_lshlrev_b32_e32 v22, 16, v23
	v_and_b32_e32 v23, 0xffff0000, v23
	s_waitcnt vmcnt(3)
	v_fmac_f32_e32 v48, v28, v22
	v_fmac_f32_e32 v49, v29, v23
	v_lshlrev_b32_e32 v22, 16, v24
	v_and_b32_e32 v23, 0xffff0000, v24
	s_waitcnt vmcnt(0)
	v_fmac_f32_e32 v12, v38, v22
	v_fmac_f32_e32 v13, v39, v23
	v_lshlrev_b32_e32 v22, 16, v25
	v_and_b32_e32 v23, 0xffff0000, v25
	v_fmac_f32_e32 v10, v40, v22
	v_fmac_f32_e32 v11, v41, v23
	v_lshlrev_b32_e32 v22, 16, v18
	v_and_b32_e32 v23, 0xffff0000, v18
	v_lshlrev_b32_e32 v18, 16, v19
	v_and_b32_e32 v19, 0xffff0000, v19
	v_fmac_f32_e32 v4, v36, v18
	v_fmac_f32_e32 v5, v37, v19
	v_lshlrev_b32_e32 v18, 16, v20
	v_and_b32_e32 v19, 0xffff0000, v20
	v_fmac_f32_e32 v6, v30, v18
	v_fmac_f32_e32 v7, v31, v19
	v_and_b32_e32 v19, 0xffff0000, v21
	v_lshlrev_b32_e32 v18, 16, v21
	v_fma_f32 v30, v32, v18, v14
	v_fma_f32 v31, v33, v19, v15
	v_fmac_f32_e32 v50, v26, v42
	v_fmac_f32_e32 v51, v27, v43
	v_fmac_f32_e32 v8, v34, v22
	v_fmac_f32_e32 v9, v35, v23
	v_mov_b64_e32 v[14:15], v[30:31]
.LBB0_563:
	s_or_b64 exec, exec, s[0:1]
	v_cmp_lt_i32_e64 s[46:47], -1, v2
	s_and_saveexec_b64 s[0:1], s[46:47]
	s_cbranch_execz .LBB0_565
	v_mov_b64_e32 v[18:19], s[28:29]
	v_mad_u64_u32 v[18:19], s[6:7], v2, s60, v[18:19]
	v_mov_b32_e32 v17, v1
	v_lshl_add_u64 v[20:21], v[18:19], 0, v[16:17]
	global_load_dwordx4 v[16:19], v[20:21], off offset:16
	s_nop 0
	global_load_dwordx4 v[20:23], v[20:21], off
	s_mov_b64 s[6:7], 0x4800
	v_add_co_u32_e32 v24, vcc, s33, v52
	v_lshl_add_u64 v[36:37], v[52:53], 0, s[6:7]
	s_nop 0
	v_addc_co_u32_e32 v25, vcc, 0, v53, vcc
	global_load_dwordx4 v[24:27], v[24:25], off offset:2048
	s_nop 0
	global_load_dwordx4 v[28:31], v[36:37], off offset:48
	global_load_dwordx4 v[32:35], v[36:37], off offset:32
	s_nop 0
	global_load_dwordx4 v[36:39], v[36:37], off offset:16
	s_waitcnt vmcnt(5)
	v_lshlrev_b32_e32 v0, 16, v19
	s_waitcnt vmcnt(4)
	v_lshlrev_b32_e32 v40, 16, v20
	v_and_b32_e32 v41, 0xffff0000, v20
	v_lshlrev_b32_e32 v20, 16, v21
	v_and_b32_e32 v21, 0xffff0000, v21
	s_waitcnt vmcnt(3)
	v_fmac_f32_e32 v48, v26, v20
	v_fmac_f32_e32 v49, v27, v21
	v_lshlrev_b32_e32 v20, 16, v22
	v_and_b32_e32 v21, 0xffff0000, v22
	s_waitcnt vmcnt(0)
	v_fmac_f32_e32 v12, v36, v20
	v_fmac_f32_e32 v13, v37, v21
	v_lshlrev_b32_e32 v20, 16, v23
	v_and_b32_e32 v21, 0xffff0000, v23
	v_fmac_f32_e32 v10, v38, v20
	v_fmac_f32_e32 v11, v39, v21
	v_lshlrev_b32_e32 v20, 16, v16
	v_and_b32_e32 v21, 0xffff0000, v16
	v_lshlrev_b32_e32 v16, 16, v17
	v_and_b32_e32 v17, 0xffff0000, v17
	v_fma_f32 v14, v30, v0, v14
	v_and_b32_e32 v0, 0xffff0000, v19
	v_fmac_f32_e32 v4, v34, v16
	v_fmac_f32_e32 v5, v35, v17
	v_lshlrev_b32_e32 v16, 16, v18
	v_and_b32_e32 v17, 0xffff0000, v18
	v_fmac_f32_e32 v15, v31, v0
	v_fmac_f32_e32 v50, v24, v40
	v_fmac_f32_e32 v51, v25, v41
	v_fmac_f32_e32 v8, v32, v20
	v_fmac_f32_e32 v9, v33, v21
	v_fmac_f32_e32 v6, v28, v16
	v_fmac_f32_e32 v7, v29, v17
	s_nop 0
	v_mov_b64_e32 v[30:31], v[14:15]
	v_mov_b64_e32 v[28:29], v[12:13]
	v_mov_b64_e32 v[26:27], v[10:11]
	v_mov_b64_e32 v[24:25], v[8:9]
	v_mov_b64_e32 v[22:23], v[6:7]
	v_mov_b64_e32 v[20:21], v[4:5]
	v_mov_b64_e32 v[18:19], v[2:3]
	v_mov_b64_e32 v[16:17], v[0:1]

; __device__ __forceinline__ float bflo(uint32_t u) { return __uint_as_float(u << 16); }
; __device__ __forceinline__ float bfhi(uint32_t u) { return __uint_as_float(u & 0xffff0000u); }
; __device__ __forceinline__ void dn_conv16(const bf16_t* PB, const float* cw, int t0, int i, int col, int ch, float (&o)[16]) {
;     ...
;     for (int tap = 0; tap < 4; ++tap) {
;         const int mm = t0 + i - 3 + tap;
;         if (mm >= 0) {
;             const u32x4 x0 = *(const u32x4*)(PB + (size_t)mm * PBW + col);
;             const u32x4 x1 = *(const u32x4*)(PB + (size_t)mm * PBW + col + 8);
;             const float* w = cw + tap * 1536 + ch;
;             const f32x4 w0 = *(const f32x4*)w, w1 = *(const f32x4*)(w + 4), w2 = *(const f32x4*)(w + 8), w3 = *(const f32x4*)(w + 12);
;             o[0] += w0.x * bflo(x0.x); o[1] += w0.y * bfhi(x0.x); o[2] += w0.z * bflo(x0.y); o[3] += w0.w * bfhi(x0.y);
;             o[4] += w1.x * bflo(x0.z); o[5] += w1.y * bfhi(x0.z); o[6] += w1.z * bflo(x0.w); o[7] += w1.w * bfhi(x0.w);
;             o[8] += w2.x * bflo(x1.x); o[9] += w2.y * bfhi(x1.x); o[10] += w2.z * bflo(x1.y); o[11] += w2.w * bfhi(x1.y);
;             o[12] += w3.x * bflo(x1.z); o[13] += w3.y * bfhi(x1.z); o[14] += w3.z * bflo(x1.w); o[15] += w3.w * bfhi(x1.w);
;         }
;     }
.LBB0_568:
	v_mad_u64_u32 v[28:29], s[6:7], v66, s60, v[22:23]
	global_load_dwordx4 v[24:27], v[28:29], off offset:16
	global_load_dwordx4 v[32:35], v[28:29], off
	v_add_co_u32_e32 v36, vcc, 0x3000, v52
	s_mov_b64 s[6:7], 0x3800
	s_nop 0
	v_addc_co_u32_e32 v37, vcc, 0, v53, vcc
	v_lshl_add_u64 v[28:29], v[52:53], 0, s[6:7]
	global_load_dwordx4 v[36:39], v[36:37], off offset:2048
	s_nop 0
	global_load_dwordx4 v[40:43], v[28:29], off offset:48
	global_load_dwordx4 v[44:47], v[28:29], off offset:32
	global_load_dwordx4 v[68:71], v[28:29], off offset:16
	s_waitcnt vmcnt(4)
	v_lshlrev_b32_e32 v28, 16, v32
	v_and_b32_e32 v29, 0xffff0000, v32
	s_waitcnt vmcnt(3)
	v_fmac_f32_e32 v62, v36, v28
	v_fmac_f32_e32 v63, v37, v29
	v_lshlrev_b32_e32 v28, 16, v33
	v_and_b32_e32 v29, 0xffff0000, v33
	v_fmac_f32_e32 v60, v38, v28
	v_fmac_f32_e32 v61, v39, v29
	v_lshlrev_b32_e32 v28, 16, v34
	v_and_b32_e32 v29, 0xffff0000, v34
	s_waitcnt vmcnt(0)
	v_fmac_f32_e32 v58, v68, v28
	v_fmac_f32_e32 v59, v69, v29
	v_lshlrev_b32_e32 v28, 16, v35
	v_and_b32_e32 v29, 0xffff0000, v35
	v_fmac_f32_e32 v56, v70, v28
	v_fmac_f32_e32 v57, v71, v29
	v_lshlrev_b32_e32 v28, 16, v24
	v_and_b32_e32 v29, 0xffff0000, v24
	v_lshlrev_b32_e32 v24, 16, v25
	v_and_b32_e32 v25, 0xffff0000, v25
	v_fmac_f32_e32 v20, v46, v24
	v_fmac_f32_e32 v21, v47, v25
	v_lshlrev_b32_e32 v24, 16, v26
	v_and_b32_e32 v25, 0xffff0000, v26
	v_fmac_f32_e32 v18, v40, v24
	v_fmac_f32_e32 v19, v41, v25
	v_and_b32_e32 v25, 0xffff0000, v27
	v_lshlrev_b32_e32 v24, 16, v27
	v_fma_f32 v46, v42, v24, v16
	v_fma_f32 v47, v43, v25, v17
	v_fmac_f32_e32 v54, v44, v28
	v_fmac_f32_e32 v55, v45, v29
	v_mov_b64_e32 v[16:17], v[46:47]
	s_or_b64 exec, exec, s[0:1]
	s_and_saveexec_b64 s[0:1], s[46:47]
	s_cbranch_execnz .LBB0_572
	s_branch .LBB0_573

; __device__ __forceinline__ float bflo(uint32_t u) { return __uint_as_float(u << 16); }
; __device__ __forceinline__ float bfhi(uint32_t u) { return __uint_as_float(u & 0xffff0000u); }
; __device__ __forceinline__ void dn_conv16(const bf16_t* PB, const float* cw, int t0, int i, int col, int ch, float (&o)[16]) {
;     ...
;     for (int tap = 0; tap < 4; ++tap) {
;         const int mm = t0 + i - 3 + tap;
;         if (mm >= 0) {
;             const u32x4 x0 = *(const u32x4*)(PB + (size_t)mm * PBW + col);
;             const u32x4 x1 = *(const u32x4*)(PB + (size_t)mm * PBW + col + 8);
;             const float* w = cw + tap * 1536 + ch;
;             const f32x4 w0 = *(const f32x4*)w, w1 = *(const f32x4*)(w + 4), w2 = *(const f32x4*)(w + 8), w3 = *(const f32x4*)(w + 12);
;             o[0] += w0.x * bflo(x0.x); o[1] += w0.y * bfhi(x0.x); o[2] += w0.z * bflo(x0.y); o[3] += w0.w * bfhi(x0.y);
;             o[4] += w1.x * bflo(x0.z); o[5] += w1.y * bfhi(x0.z); o[6] += w1.z * bflo(x0.w); o[7] += w1.w * bfhi(x0.w);
;             o[8] += w2.x * bflo(x1.x); o[9] += w2.y * bfhi(x1.x); o[10] += w2.z * bflo(x1.y); o[11] += w2.w * bfhi(x1.y);
;             o[12] += w3.x * bflo(x1.z); o[13] += w3.y * bfhi(x1.z); o[14] += w3.z * bflo(x1.w); o[15] += w3.w * bfhi(x1.w);
;         }
;     }
.LBB0_570:
	v_mad_u64_u32 v[28:29], s[6:7], v65, s60, v[22:23]
	global_load_dwordx4 v[24:27], v[28:29], off offset:16
	global_load_dwordx4 v[32:35], v[28:29], off
	v_add_co_u32_e32 v36, vcc, 0x2000, v52
	s_mov_b64 s[6:7], 0x2000
	s_nop 0
	v_addc_co_u32_e32 v37, vcc, 0, v53, vcc
	v_lshl_add_u64 v[28:29], v[52:53], 0, s[6:7]
	global_load_dwordx4 v[36:39], v[36:37], off
	s_nop 0
	global_load_dwordx4 v[40:43], v[28:29], off offset:48
	global_load_dwordx4 v[44:47], v[28:29], off offset:32
	global_load_dwordx4 v[68:71], v[28:29], off offset:16
	s_waitcnt vmcnt(4)
	v_lshlrev_b32_e32 v28, 16, v32
	v_and_b32_e32 v29, 0xffff0000, v32
	s_waitcnt vmcnt(3)
	v_fmac_f32_e32 v62, v36, v28
	v_fmac_f32_e32 v63, v37, v29
	v_lshlrev_b32_e32 v28, 16, v33
	v_and_b32_e32 v29, 0xffff0000, v33
	v_fmac_f32_e32 v60, v38, v28
	v_fmac_f32_e32 v61, v39, v29
	v_lshlrev_b32_e32 v28, 16, v34
	v_and_b32_e32 v29, 0xffff0000, v34
	s_waitcnt vmcnt(0)
	v_fmac_f32_e32 v58, v68, v28
	v_fmac_f32_e32 v59, v69, v29
	v_lshlrev_b32_e32 v28, 16, v35
	v_and_b32_e32 v29, 0xffff0000, v35
	v_fmac_f32_e32 v56, v70, v28
	v_fmac_f32_e32 v57, v71, v29
	v_lshlrev_b32_e32 v28, 16, v24
	v_and_b32_e32 v29, 0xffff0000, v24
	v_lshlrev_b32_e32 v24, 16, v25
	v_and_b32_e32 v25, 0xffff0000, v25
	v_fmac_f32_e32 v20, v46, v24
	v_fmac_f32_e32 v21, v47, v25
	v_lshlrev_b32_e32 v24, 16, v26
	v_and_b32_e32 v25, 0xffff0000, v26
	v_fmac_f32_e32 v18, v40, v24
	v_fmac_f32_e32 v19, v41, v25
	v_and_b32_e32 v25, 0xffff0000, v27
	v_lshlrev_b32_e32 v24, 16, v27
	v_fma_f32 v46, v42, v24, v16
	v_fma_f32 v47, v43, v25, v17
	v_fmac_f32_e32 v54, v44, v28
	v_fmac_f32_e32 v55, v45, v29
	v_mov_b64_e32 v[16:17], v[46:47]
	s_or_b64 exec, exec, s[0:1]
	s_and_saveexec_b64 s[0:1], s[44:45]
	s_cbranch_execnz .LBB0_568

; __device__ __forceinline__ float bflo(uint32_t u) { return __uint_as_float(u << 16); }
; __device__ __forceinline__ float bfhi(uint32_t u) { return __uint_as_float(u & 0xffff0000u); }
; __device__ __forceinline__ void dn_conv16(const bf16_t* PB, const float* cw, int t0, int i, int col, int ch, float (&o)[16]) {
;     ...
;     for (int tap = 0; tap < 4; ++tap) {
;         const int mm = t0 + i - 3 + tap;
;         if (mm >= 0) {
;             const u32x4 x0 = *(const u32x4*)(PB + (size_t)mm * PBW + col);
;             const u32x4 x1 = *(const u32x4*)(PB + (size_t)mm * PBW + col + 8);
;             const float* w = cw + tap * 1536 + ch;
;             const f32x4 w0 = *(const f32x4*)w, w1 = *(const f32x4*)(w + 4), w2 = *(const f32x4*)(w + 8), w3 = *(const f32x4*)(w + 12);
;             o[0] += w0.x * bflo(x0.x); o[1] += w0.y * bfhi(x0.x); o[2] += w0.z * bflo(x0.y); o[3] += w0.w * bfhi(x0.y);
;             o[4] += w1.x * bflo(x0.z); o[5] += w1.y * bfhi(x0.z); o[6] += w1.z * bflo(x0.w); o[7] += w1.w * bfhi(x0.w);
;             o[8] += w2.x * bflo(x1.x); o[9] += w2.y * bfhi(x1.x); o[10] += w2.z * bflo(x1.y); o[11] += w2.w * bfhi(x1.y);
;             o[12] += w3.x * bflo(x1.z); o[13] += w3.y * bfhi(x1.z); o[14] += w3.z * bflo(x1.w); o[15] += w3.w * bfhi(x1.w);
;         }
;     }
.LBB0_572:
	v_mad_u64_u32 v[26:27], s[6:7], v2, s60, v[22:23]
	global_load_dwordx4 v[22:25], v[26:27], off offset:16
	s_nop 0
	global_load_dwordx4 v[26:29], v[26:27], off
	s_mov_b64 s[6:7], 0x5000
	v_add_co_u32_e32 v32, vcc, 0x5000, v52
	v_lshl_add_u64 v[44:45], v[52:53], 0, s[6:7]
	s_nop 0
	v_addc_co_u32_e32 v33, vcc, 0, v53, vcc
	global_load_dwordx4 v[32:35], v[32:33], off
	s_nop 0
	global_load_dwordx4 v[36:39], v[44:45], off offset:48
	global_load_dwordx4 v[40:43], v[44:45], off offset:32
	s_nop 0
	global_load_dwordx4 v[44:47], v[44:45], off offset:16
	s_waitcnt vmcnt(5)
	v_lshlrev_b32_e32 v0, 16, v25
	s_waitcnt vmcnt(4)
	v_lshlrev_b32_e32 v68, 16, v26
	v_and_b32_e32 v69, 0xffff0000, v26
	v_lshlrev_b32_e32 v26, 16, v27
	v_and_b32_e32 v27, 0xffff0000, v27
	s_waitcnt vmcnt(3)
	v_fmac_f32_e32 v60, v34, v26
	v_fmac_f32_e32 v61, v35, v27
	v_lshlrev_b32_e32 v26, 16, v28
	v_and_b32_e32 v27, 0xffff0000, v28
	s_waitcnt vmcnt(0)
	v_fmac_f32_e32 v58, v44, v26
	v_fmac_f32_e32 v59, v45, v27
	v_lshlrev_b32_e32 v26, 16, v29
	v_and_b32_e32 v27, 0xffff0000, v29
	v_fmac_f32_e32 v56, v46, v26
	v_fmac_f32_e32 v57, v47, v27
	v_lshlrev_b32_e32 v26, 16, v22
	v_and_b32_e32 v27, 0xffff0000, v22
	v_lshlrev_b32_e32 v22, 16, v23
	v_and_b32_e32 v23, 0xffff0000, v23
	v_fma_f32 v16, v38, v0, v16
	v_and_b32_e32 v0, 0xffff0000, v25
	v_fmac_f32_e32 v20, v42, v22
	v_fmac_f32_e32 v21, v43, v23
	v_lshlrev_b32_e32 v22, 16, v24
	v_and_b32_e32 v23, 0xffff0000, v24
	v_fmac_f32_e32 v17, v39, v0
	v_fmac_f32_e32 v62, v32, v68
	v_fmac_f32_e32 v63, v33, v69
	v_fmac_f32_e32 v54, v40, v26
	v_fmac_f32_e32 v55, v41, v27
	v_fmac_f32_e32 v18, v36, v22
	v_fmac_f32_e32 v19, v37, v23
	v_mov_b64_e32 v[46:47], v[16:17]
	v_mov_b64_e32 v[44:45], v[14:15]
	v_mov_b64_e32 v[42:43], v[12:13]
	v_mov_b64_e32 v[40:41], v[10:11]
	v_mov_b64_e32 v[38:39], v[8:9]
	v_mov_b64_e32 v[36:37], v[6:7]
	v_mov_b64_e32 v[34:35], v[4:5]
	v_mov_b64_e32 v[32:33], v[2:3]

; __device__ __forceinline__ float bflo(uint32_t u) { return __uint_as_float(u << 16); }
; __device__ __forceinline__ float bfhi(uint32_t u) { return __uint_as_float(u & 0xffff0000u); }
; __device__ __forceinline__ void dn_conv16(const bf16_t* PB, const float* cw, int t0, int i, int col, int ch, float (&o)[16]) {
;     ...
;     for (int tap = 0; tap < 4; ++tap) {
;         const int mm = t0 + i - 3 + tap;
;         if (mm >= 0) {
;             const u32x4 x0 = *(const u32x4*)(PB + (size_t)mm * PBW + col);
;             const u32x4 x1 = *(const u32x4*)(PB + (size_t)mm * PBW + col + 8);
;             const float* w = cw + tap * 1536 + ch;
;             const f32x4 w0 = *(const f32x4*)w, w1 = *(const f32x4*)(w + 4), w2 = *(const f32x4*)(w + 8), w3 = *(const f32x4*)(w + 12);
;             o[0] += w0.x * bflo(x0.x); o[1] += w0.y * bfhi(x0.x); o[2] += w0.z * bflo(x0.y); o[3] += w0.w * bfhi(x0.y);
;             o[4] += w1.x * bflo(x0.z); o[5] += w1.y * bfhi(x0.z); o[6] += w1.z * bflo(x0.w); o[7] += w1.w * bfhi(x0.w);
;             o[8] += w2.x * bflo(x1.x); o[9] += w2.y * bfhi(x1.x); o[10] += w2.z * bflo(x1.y); o[11] += w2.w * bfhi(x1.y);
;             o[12] += w3.x * bflo(x1.z); o[13] += w3.y * bfhi(x1.z); o[14] += w3.z * bflo(x1.w); o[15] += w3.w * bfhi(x1.w);
;         }
;     }
.LBB0_576:
	v_mad_u64_u32 v[40:41], s[6:7], v66, s60, v[34:35]
	global_load_dwordx4 v[36:39], v[40:41], off offset:16
	s_nop 0
	global_load_dwordx4 v[40:43], v[40:41], off
	v_add_co_u32_e32 v64, vcc, 0x4000, v52
	s_mov_b64 s[6:7], 0x4000
	s_nop 0
	v_addc_co_u32_e32 v65, vcc, 0, v53, vcc
	v_lshl_add_u64 v[44:45], v[52:53], 0, s[6:7]
	global_load_dwordx4 v[64:67], v[64:65], off
	s_nop 0
	global_load_dwordx4 v[76:79], v[44:45], off offset:48
	global_load_dwordx4 v[80:83], v[44:45], off offset:32
	global_load_dwordx4 v[84:87], v[44:45], off offset:16
	s_waitcnt vmcnt(4)
	v_lshlrev_b32_e32 v44, 16, v40
	v_and_b32_e32 v45, 0xffff0000, v40
	v_lshlrev_b32_e32 v40, 16, v41
	v_and_b32_e32 v41, 0xffff0000, v41
	s_waitcnt vmcnt(3)
	v_fmac_f32_e32 v24, v66, v40
	v_fmac_f32_e32 v25, v67, v41
	v_lshlrev_b32_e32 v40, 16, v42
	v_and_b32_e32 v41, 0xffff0000, v42
	s_waitcnt vmcnt(0)
	v_fmac_f32_e32 v26, v84, v40
	v_fmac_f32_e32 v27, v85, v41
	v_lshlrev_b32_e32 v40, 16, v43
	v_and_b32_e32 v41, 0xffff0000, v43
	v_fmac_f32_e32 v28, v86, v40
	v_fmac_f32_e32 v29, v87, v41
	v_lshlrev_b32_e32 v40, 16, v36
	v_and_b32_e32 v41, 0xffff0000, v36
	v_lshlrev_b32_e32 v36, 16, v37
	v_and_b32_e32 v37, 0xffff0000, v37
	v_fmac_f32_e32 v70, v82, v36
	v_fmac_f32_e32 v71, v83, v37
	v_lshlrev_b32_e32 v36, 16, v38
	v_and_b32_e32 v37, 0xffff0000, v38
	v_fmac_f32_e32 v72, v76, v36
	v_fmac_f32_e32 v73, v77, v37
	v_lshlrev_b32_e32 v36, 16, v39
	v_and_b32_e32 v37, 0xffff0000, v39
	v_fmac_f32_e32 v22, v64, v44
	v_fmac_f32_e32 v23, v65, v45
	v_fmac_f32_e32 v32, v80, v40
	v_fmac_f32_e32 v33, v81, v41
	v_fmac_f32_e32 v74, v78, v36
	v_fmac_f32_e32 v75, v79, v37
	s_or_b64 exec, exec, s[0:1]
	s_and_saveexec_b64 s[0:1], s[46:47]
	s_cbranch_execnz .LBB0_580
	s_branch .LBB0_581

; __device__ __forceinline__ float bflo(uint32_t u) { return __uint_as_float(u << 16); }
; __device__ __forceinline__ float bfhi(uint32_t u) { return __uint_as_float(u & 0xffff0000u); }
; __device__ __forceinline__ void dn_conv16(const bf16_t* PB, const float* cw, int t0, int i, int col, int ch, float (&o)[16]) {
;     ...
;     for (int tap = 0; tap < 4; ++tap) {
;         const int mm = t0 + i - 3 + tap;
;         if (mm >= 0) {
;             const u32x4 x0 = *(const u32x4*)(PB + (size_t)mm * PBW + col);
;             const u32x4 x1 = *(const u32x4*)(PB + (size_t)mm * PBW + col + 8);
;             const float* w = cw + tap * 1536 + ch;
;             const f32x4 w0 = *(const f32x4*)w, w1 = *(const f32x4*)(w + 4), w2 = *(const f32x4*)(w + 8), w3 = *(const f32x4*)(w + 12);
;             o[0] += w0.x * bflo(x0.x); o[1] += w0.y * bfhi(x0.x); o[2] += w0.z * bflo(x0.y); o[3] += w0.w * bfhi(x0.y);
;             o[4] += w1.x * bflo(x0.z); o[5] += w1.y * bfhi(x0.z); o[6] += w1.z * bflo(x0.w); o[7] += w1.w * bfhi(x0.w);
;             o[8] += w2.x * bflo(x1.x); o[9] += w2.y * bfhi(x1.x); o[10] += w2.z * bflo(x1.y); o[11] += w2.w * bfhi(x1.y);
;             o[12] += w3.x * bflo(x1.z); o[13] += w3.y * bfhi(x1.z); o[14] += w3.z * bflo(x1.w); o[15] += w3.w * bfhi(x1.w);
;         }
;     }
.LBB0_578:
	v_mad_u64_u32 v[40:41], s[6:7], v65, s60, v[34:35]
	global_load_dwordx4 v[36:39], v[40:41], off offset:16
	s_nop 0
	global_load_dwordx4 v[40:43], v[40:41], off
	v_add_co_u32_e32 v64, vcc, 0x2000, v52
	s_mov_b64 s[6:7], 0x2800
	s_nop 0
	v_addc_co_u32_e32 v65, vcc, 0, v53, vcc
	v_lshl_add_u64 v[44:45], v[52:53], 0, s[6:7]
	global_load_dwordx4 v[76:79], v[64:65], off offset:2048
	global_load_dwordx4 v[80:83], v[44:45], off offset:48
	global_load_dwordx4 v[84:87], v[44:45], off offset:32
	global_load_dwordx4 v[88:91], v[44:45], off offset:16
	s_waitcnt vmcnt(4)
	v_lshlrev_b32_e32 v44, 16, v40
	v_and_b32_e32 v45, 0xffff0000, v40
	v_lshlrev_b32_e32 v40, 16, v41
	v_and_b32_e32 v41, 0xffff0000, v41
	s_waitcnt vmcnt(3)
	v_fmac_f32_e32 v24, v78, v40
	v_fmac_f32_e32 v25, v79, v41
	v_lshlrev_b32_e32 v40, 16, v42
	v_and_b32_e32 v41, 0xffff0000, v42
	s_waitcnt vmcnt(0)
	v_fmac_f32_e32 v26, v88, v40
	v_fmac_f32_e32 v27, v89, v41
	v_lshlrev_b32_e32 v40, 16, v43
	v_and_b32_e32 v41, 0xffff0000, v43
	v_fmac_f32_e32 v28, v90, v40
	v_fmac_f32_e32 v29, v91, v41
	v_lshlrev_b32_e32 v40, 16, v36
	v_and_b32_e32 v41, 0xffff0000, v36
	v_lshlrev_b32_e32 v36, 16, v37
	v_and_b32_e32 v37, 0xffff0000, v37
	v_fmac_f32_e32 v70, v86, v36
	v_fmac_f32_e32 v71, v87, v37
	v_lshlrev_b32_e32 v36, 16, v38
	v_and_b32_e32 v37, 0xffff0000, v38
	v_fmac_f32_e32 v72, v80, v36
	v_fmac_f32_e32 v73, v81, v37
	v_lshlrev_b32_e32 v36, 16, v39
	v_and_b32_e32 v37, 0xffff0000, v39
	v_fmac_f32_e32 v22, v76, v44
	v_fmac_f32_e32 v23, v77, v45
	v_fmac_f32_e32 v32, v84, v40
	v_fmac_f32_e32 v33, v85, v41
	v_fmac_f32_e32 v74, v82, v36
	v_fmac_f32_e32 v75, v83, v37
	s_or_b64 exec, exec, s[0:1]
	s_and_saveexec_b64 s[0:1], s[44:45]
	s_cbranch_execnz .LBB0_576

; __device__ __forceinline__ float bflo(uint32_t u) { return __uint_as_float(u << 16); }
; __device__ __forceinline__ float bfhi(uint32_t u) { return __uint_as_float(u & 0xffff0000u); }
; __device__ __forceinline__ float siluf(float x) { return x * __builtin_amdgcn_rcpf(1.f + __expf(-x)); }
; __device__ __forceinline__ void dn_conv16(const bf16_t* PB, const float* cw, int t0, int i, int col, int ch, float (&o)[16]) {
;     ...
;     for (int tap = 0; tap < 4; ++tap) {
;         const int mm = t0 + i - 3 + tap;
;         if (mm >= 0) {
;             const u32x4 x0 = *(const u32x4*)(PB + (size_t)mm * PBW + col);
;             const u32x4 x1 = *(const u32x4*)(PB + (size_t)mm * PBW + col + 8);
;             const float* w = cw + tap * 1536 + ch;
;             const f32x4 w0 = *(const f32x4*)w, w1 = *(const f32x4*)(w + 4), w2 = *(const f32x4*)(w + 8), w3 = *(const f32x4*)(w + 12);
;             o[0] += w0.x * bflo(x0.x); o[1] += w0.y * bfhi(x0.x); o[2] += w0.z * bflo(x0.y); o[3] += w0.w * bfhi(x0.y);
;             o[4] += w1.x * bflo(x0.z); o[5] += w1.y * bfhi(x0.z); o[6] += w1.z * bflo(x0.w); o[7] += w1.w * bfhi(x0.w);
;             o[8] += w2.x * bflo(x1.x); o[9] += w2.y * bfhi(x1.x); o[10] += w2.z * bflo(x1.y); o[11] += w2.w * bfhi(x1.y);
;             o[12] += w3.x * bflo(x1.z); o[13] += w3.y * bfhi(x1.z); o[14] += w3.z * bflo(x1.w); o[15] += w3.w * bfhi(x1.w);
;         }
;     }
; #pragma unroll
;     for (int e = 0; e < 16; ++e) o[e] = siluf(o[e]);
.LBB0_580:
	v_mad_u64_u32 v[38:39], s[6:7], v2, s60, v[34:35]
	global_load_dwordx4 v[34:37], v[38:39], off offset:16
	s_nop 0
	global_load_dwordx4 v[38:41], v[38:39], off
	v_add_co_u32_e32 v42, vcc, 0x5000, v52
	s_mov_b64 s[6:7], 0x5800
	s_nop 0
	v_addc_co_u32_e32 v43, vcc, 0, v53, vcc
	v_lshl_add_u64 v[68:69], v[52:53], 0, s[6:7]
	global_load_dwordx4 v[42:45], v[42:43], off offset:2048
	s_nop 0
	global_load_dwordx4 v[64:67], v[68:69], off offset:48
	global_load_dwordx4 v[76:79], v[68:69], off offset:32
	global_load_dwordx4 v[80:83], v[68:69], off offset:16
	s_waitcnt vmcnt(4)
	v_lshlrev_b32_e32 v52, 16, v38
	v_and_b32_e32 v53, 0xffff0000, v38
	v_lshlrev_b32_e32 v38, 16, v39
	v_and_b32_e32 v39, 0xffff0000, v39
	s_waitcnt vmcnt(3)
	v_fmac_f32_e32 v24, v44, v38
	v_fmac_f32_e32 v25, v45, v39
	v_lshlrev_b32_e32 v38, 16, v40
	v_and_b32_e32 v39, 0xffff0000, v40
	s_waitcnt vmcnt(0)
	v_fmac_f32_e32 v26, v80, v38
	v_fmac_f32_e32 v27, v81, v39
	v_lshlrev_b32_e32 v38, 16, v41
	v_and_b32_e32 v39, 0xffff0000, v41
	v_fmac_f32_e32 v28, v82, v38
	v_fmac_f32_e32 v29, v83, v39
	v_lshlrev_b32_e32 v38, 16, v34
	v_and_b32_e32 v39, 0xffff0000, v34
	v_lshlrev_b32_e32 v34, 16, v35
	v_and_b32_e32 v35, 0xffff0000, v35
	v_fmac_f32_e32 v70, v78, v34
	v_fmac_f32_e32 v71, v79, v35
	v_lshlrev_b32_e32 v34, 16, v36
	v_and_b32_e32 v35, 0xffff0000, v36
	v_fmac_f32_e32 v72, v64, v34
	v_fmac_f32_e32 v73, v65, v35
	v_lshlrev_b32_e32 v34, 16, v37
	v_and_b32_e32 v35, 0xffff0000, v37
	v_fmac_f32_e32 v22, v42, v52
	v_fmac_f32_e32 v23, v43, v53
	v_fmac_f32_e32 v32, v76, v38
	v_fmac_f32_e32 v33, v77, v39
	v_fmac_f32_e32 v74, v66, v34
	v_fmac_f32_e32 v75, v67, v35
.LBB0_581:
	s_or_b64 exec, exec, s[0:1]
	v_mul_f32_e32 v0, 0xbfb8aa3b, v62
	v_exp_f32_e32 v0, v0
	v_mul_f32_e32 v15, 0xbfb8aa3b, v63
	v_exp_f32_e32 v15, v15
	v_mov_b32_e32 v17, v47
	v_add_f32_e32 v0, 1.0, v0
	v_rcp_f32_e32 v34, v0
	v_add_f32_e32 v15, 1.0, v15
	v_mul_f32_e32 v0, 0xbfb8aa3b, v60
	v_rcp_f32_e32 v35, v15
	v_exp_f32_e32 v0, v0
	v_mul_f32_e32 v15, 0xbfb8aa3b, v61
	v_exp_f32_e32 v15, v15
	v_mul_f32_e32 v30, 0xbfb8aa3b, v7
	v_add_f32_e32 v0, 1.0, v0
	v_rcp_f32_e32 v36, v0
	v_add_f32_e32 v0, 1.0, v15
	v_rcp_f32_e32 v37, v0
	v_mul_f32_e32 v0, 0xbfb8aa3b, v58
	v_exp_f32_e32 v0, v0
	v_mul_f32_e32 v15, 0xbfb8aa3b, v59
	v_exp_f32_e32 v15, v15
	v_exp_f32_e32 v30, v30
	v_add_f32_e32 v0, 1.0, v0
	v_rcp_f32_e32 v38, v0
	v_add_f32_e32 v0, 1.0, v15
	v_rcp_f32_e32 v39, v0
	v_mul_f32_e32 v0, 0xbfb8aa3b, v56
	v_exp_f32_e32 v0, v0
	v_mul_f32_e32 v15, 0xbfb8aa3b, v57
	v_exp_f32_e32 v15, v15
	v_pk_mul_f32 v[34:35], v[62:63], v[34:35]
	v_add_f32_e32 v0, 1.0, v0
	v_rcp_f32_e32 v40, v0
	v_add_f32_e32 v0, 1.0, v15
	v_rcp_f32_e32 v41, v0
	v_mul_f32_e32 v0, 0xbfb8aa3b, v54
	v_exp_f32_e32 v0, v0
	v_mul_f32_e32 v15, 0xbfb8aa3b, v55
	v_exp_f32_e32 v15, v15
	v_pk_mul_f32 v[42:43], v[56:57], v[40:41]
	v_add_f32_e32 v0, 1.0, v0
	v_rcp_f32_e32 v40, v0
	v_add_f32_e32 v0, 1.0, v15
	v_rcp_f32_e32 v41, v0
	v_mul_f32_e32 v0, 0xbfb8aa3b, v20
	v_exp_f32_e32 v0, v0
	v_mul_f32_e32 v15, 0xbfb8aa3b, v21
	v_exp_f32_e32 v15, v15
	v_pk_mul_f32 v[52:53], v[54:55], v[40:41]
	v_add_f32_e32 v0, 1.0, v0
	v_rcp_f32_e32 v40, v0
	v_add_f32_e32 v0, 1.0, v15
	v_rcp_f32_e32 v41, v0
	v_mul_f32_e32 v0, 0xbfb8aa3b, v18
	v_exp_f32_e32 v0, v0
	v_mul_f32_e32 v15, 0xbfb8aa3b, v19
	v_exp_f32_e32 v15, v15
	v_pk_mul_f32 v[20:21], v[20:21], v[40:41]
	v_add_f32_e32 v0, 1.0, v0
	v_rcp_f32_e32 v40, v0
	v_add_f32_e32 v0, 1.0, v15
	v_rcp_f32_e32 v41, v0
	v_mul_f32_e32 v0, 0xbfb8aa3b, v16
	v_exp_f32_e32 v0, v0
	v_mul_f32_e32 v15, 0xbfb8aa3b, v47
	v_exp_f32_e32 v15, v15
	v_pk_mul_f32 v[18:19], v[18:19], v[40:41]
	v_add_f32_e32 v0, 1.0, v0
	v_rcp_f32_e32 v40, v0
	v_add_f32_e32 v0, 1.0, v15
	v_rcp_f32_e32 v41, v0
	v_mul_f32_e32 v0, 0xbfb8aa3b, v50
	v_exp_f32_e32 v0, v0
	v_mul_f32_e32 v15, 0xbfb8aa3b, v51
	v_exp_f32_e32 v15, v15
	v_pk_mul_f32 v[16:17], v[16:17], v[40:41]
	v_add_f32_e32 v0, 1.0, v0
	v_rcp_f32_e32 v40, v0
	v_add_f32_e32 v0, 1.0, v15
	v_rcp_f32_e32 v41, v0
	v_mul_f32_e32 v0, 0xbfb8aa3b, v48
	v_exp_f32_e32 v0, v0
	v_mul_f32_e32 v15, 0xbfb8aa3b, v49
	v_exp_f32_e32 v15, v15
	v_pk_mul_f32 v[40:41], v[50:51], v[40:41]
	v_add_f32_e32 v0, 1.0, v0
	v_rcp_f32_e32 v44, v0
	v_add_f32_e32 v0, 1.0, v15
	v_rcp_f32_e32 v45, v0
	v_mul_f32_e32 v0, 0xbfb8aa3b, v12
	v_exp_f32_e32 v0, v0
	v_mul_f32_e32 v15, 0xbfb8aa3b, v13
	v_exp_f32_e32 v15, v15
	v_pk_mul_f32 v[46:47], v[48:49], v[44:45]
	v_add_f32_e32 v0, 1.0, v0
	v_rcp_f32_e32 v44, v0
	v_add_f32_e32 v0, 1.0, v15
	v_rcp_f32_e32 v45, v0
	v_mul_f32_e32 v0, 0xbfb8aa3b, v10
	v_exp_f32_e32 v0, v0
	v_mul_f32_e32 v15, 0xbfb8aa3b, v11
	v_exp_f32_e32 v15, v15
	v_pk_mul_f32 v[12:13], v[12:13], v[44:45]
	v_add_f32_e32 v0, 1.0, v0
	v_rcp_f32_e32 v44, v0
	v_add_f32_e32 v0, 1.0, v15
	v_rcp_f32_e32 v45, v0
	v_mul_f32_e32 v0, 0xbfb8aa3b, v8
	v_exp_f32_e32 v0, v0
	v_mul_f32_e32 v15, 0xbfb8aa3b, v9
	v_exp_f32_e32 v15, v15
	v_pk_mul_f32 v[10:11], v[10:11], v[44:45]
	v_add_f32_e32 v0, 1.0, v0
	v_rcp_f32_e32 v44, v0
	v_add_f32_e32 v0, 1.0, v15
	v_rcp_f32_e32 v45, v0
	v_mul_f32_e32 v0, 0xbfb8aa3b, v4
	v_exp_f32_e32 v0, v0
	v_mul_f32_e32 v15, 0xbfb8aa3b, v5
	v_exp_f32_e32 v15, v15
	v_pk_mul_f32 v[8:9], v[8:9], v[44:45]
	v_add_f32_e32 v0, 1.0, v0
	v_rcp_f32_e32 v44, v0
	v_add_f32_e32 v0, 1.0, v15
	v_mul_f32_e32 v15, 0xbfb8aa3b, v6
	v_exp_f32_e32 v15, v15
	v_rcp_f32_e32 v45, v0
	v_pk_mul_f32 v[36:37], v[60:61], v[36:37]
	v_pk_mul_f32 v[38:39], v[58:59], v[38:39]
	v_add_f32_e32 v0, 1.0, v15
	v_mul_f32_e32 v15, 0xbfb8aa3b, v14
	v_rcp_f32_e32 v48, v0
	v_add_f32_e32 v0, 1.0, v30
	v_exp_f32_e32 v15, v15
	v_mul_f32_e32 v30, 0xbfb8aa3b, v31
	v_exp_f32_e32 v30, v30
; __device__ __forceinline__ float siluf(float x) { return x * __builtin_amdgcn_rcpf(1.f + __expf(-x)); }
; __device__ __forceinline__ void dn_conv16(const bf16_t* PB, const float* cw, int t0, int i, int col, int ch, float (&o)[16]) {
;     ...
;     for (int e = 0; e < 16; ++e) o[e] = siluf(o[e]);
; __device__ __forceinline__ void dn1_item(const Params& p, int l, int item, unsigned char* lds) {
;     ...
;     {
;         float sq = 0.f, sk = 0.f;
; #pragma unroll
;         for (int e = 0; e < 16; ++e) { sq += qn[e] * qn[e]; sk += kn[e] * kn[e]; }
;         sq += __shfl_xor(sq, 1); sq += __shfl_xor(sq, 2);
;         sk += __shfl_xor(sk, 1); sk += __shfl_xor(sk, 2);
;         const float rq = rsqrtf(sq + EPS) * 0.125f, rk = rsqrtf(sk + EPS);
; #pragma unroll
;         for (int e = 0; e < 16; ++e) { qn[e] *= rq; kn[e] *= rk; }
;     }
;     __syncthreads();
; #pragma unroll
;     for (int e = 0; e < 16; ++e) { B0[(d0 + e) * DLD + i] = kn[e]; B1[(d0 + e) * DLD + i] = qn[e]; }
	v_rcp_f32_e32 v49, v0
	v_add_f32_e32 v0, 1.0, v15
	v_rcp_f32_e32 v50, v0
	v_add_f32_e32 v0, 1.0, v30
	v_rcp_f32_e32 v51, v0
	v_pk_mul_f32 v[6:7], v[6:7], v[48:49]
	v_mov_b32_e32 v15, v31
	v_mov_b32_e32 v48, v34
	v_mov_b32_e32 v49, v40
	v_pk_mul_f32 v[14:15], v[14:15], v[50:51]
	v_pk_mul_f32 v[48:49], v[48:49], v[48:49]
	v_mov_b32_e32 v50, v35
	v_mov_b32_e32 v51, v41
	v_fmac_f32_e32 v48, v50, v50
	v_fmac_f32_e32 v49, v51, v51
	v_mov_b32_e32 v50, v36
	v_mov_b32_e32 v51, v46
	v_fmac_f32_e32 v48, v50, v50
	v_fmac_f32_e32 v49, v51, v51
	v_mov_b32_e32 v50, v37
	v_mov_b32_e32 v51, v47
	v_fmac_f32_e32 v48, v50, v50
	v_fmac_f32_e32 v49, v51, v51
	v_mov_b32_e32 v50, v38
	v_mov_b32_e32 v51, v12
	v_pk_mul_f32 v[4:5], v[4:5], v[44:45]
	v_pk_mul_f32 v[30:31], v[10:11], v[10:11]
	v_pk_mul_f32 v[44:45], v[42:43], v[42:43]
	v_fmac_f32_e32 v48, v50, v50
	v_fmac_f32_e32 v49, v51, v51
	v_mov_b32_e32 v50, v39
	v_mov_b32_e32 v51, v13
	v_and_b32_e32 v0, 64, v228
	v_fmac_f32_e32 v48, v50, v50
	v_fmac_f32_e32 v49, v51, v51
	v_mov_b32_e32 v50, v44
	v_mov_b32_e32 v51, v30
	v_xor_b32_e32 v64, 1, v228
	v_add_u32_e32 v66, 64, v0
	v_pk_add_f32 v[48:49], v[50:51], v[48:49]
	v_mov_b32_e32 v30, v45
	v_cmp_lt_i32_e32 vcc, v64, v66
	v_pk_add_f32 v[30:31], v[30:31], v[48:49]
	v_pk_mul_f32 v[44:45], v[8:9], v[8:9]
	v_pk_mul_f32 v[48:49], v[52:53], v[52:53]
	v_cndmask_b32_e32 v64, v228, v64, vcc
	v_lshlrev_b32_e32 v67, 2, v64
	v_mov_b32_e32 v64, v48
	v_mov_b32_e32 v65, v44
	v_pk_mul_f32 v[50:51], v[4:5], v[4:5]
	v_pk_mul_f32 v[54:55], v[20:21], v[20:21]
	v_pk_add_f32 v[30:31], v[64:65], v[30:31]
	v_mov_b32_e32 v44, v49
	v_pk_add_f32 v[30:31], v[44:45], v[30:31]
	v_mov_b32_e32 v44, v54
	v_mov_b32_e32 v45, v50
	v_pk_mul_f32 v[56:57], v[6:7], v[6:7]
	v_pk_mul_f32 v[58:59], v[18:19], v[18:19]
	v_pk_add_f32 v[30:31], v[44:45], v[30:31]
	v_mov_b32_e32 v50, v55
	v_pk_add_f32 v[30:31], v[50:51], v[30:31]
	v_mov_b32_e32 v44, v58
	v_mov_b32_e32 v45, v56
	v_pk_mul_f32 v[60:61], v[14:15], v[14:15]
	v_pk_mul_f32 v[62:63], v[16:17], v[16:17]
	v_pk_add_f32 v[30:31], v[44:45], v[30:31]
	v_mov_b32_e32 v56, v59
	v_pk_add_f32 v[30:31], v[56:57], v[30:31]
	v_mov_b32_e32 v44, v62
	v_mov_b32_e32 v45, v60
	v_pk_add_f32 v[30:31], v[44:45], v[30:31]
	v_mov_b32_e32 v60, v63
	v_pk_add_f32 v[30:31], v[60:61], v[30:31]
	ds_bpermute_b32 v45, v67, v31
	ds_bpermute_b32 v44, v67, v30
	v_xor_b32_e32 v48, 2, v228
	v_cmp_lt_i32_e32 vcc, v48, v66
	s_mov_b32 s0, 0x358637bd
	s_waitcnt lgkmcnt(0)
	v_cndmask_b32_e32 v48, v228, v48, vcc
	v_lshlrev_b32_e32 v48, 2, v48
	v_pk_add_f32 v[30:31], v[30:31], v[44:45]
	ds_bpermute_b32 v45, v48, v31
	ds_bpermute_b32 v44, v48, v30
	s_barrier
	s_waitcnt lgkmcnt(0)
	v_pk_add_f32 v[30:31], v[30:31], v[44:45]
	s_nop 0
	v_pk_add_f32 v[30:31], v[30:31], s[0:1] op_sel_hi:[1,0]
	s_mov_b32 s0, 0x800000
	v_mul_f32_e32 v44, 0x4b800000, v31
	v_cmp_gt_f32_e32 vcc, s0, v31
	v_cmp_gt_f32_e64 s[0:1], s0, v30
	s_nop 0
	v_cndmask_b32_e32 v31, v31, v44, vcc
	v_mul_f32_e32 v44, 0x4b800000, v30
	v_rsq_f32_e32 v31, v31
	v_cndmask_b32_e64 v30, v30, v44, s[0:1]
	v_rsq_f32_e32 v44, v30
	v_mul_f32_e32 v30, 0x45800000, v31
	v_cndmask_b32_e32 v30, v31, v30, vcc
	v_mul_f32_e32 v31, 0x45800000, v44
	v_mul_f32_e32 v30, 0x3e000000, v30
	v_cndmask_b32_e64 v50, v44, v31, s[0:1]
	s_movk_i32 s0, 0x440
	v_pk_mul_f32 v[64:65], v[42:43], v[50:51] op_sel_hi:[1,0]
	v_pk_mul_f32 v[42:43], v[4:5], v[30:31] op_sel_hi:[1,0]
	v_mad_u32_u24 v4, v3, s0, v108
	v_lshl_add_u32 v4, v4, 2, 0
	v_pk_mul_f32 v[44:45], v[40:41], v[30:31] op_sel_hi:[1,0]
	v_pk_mul_f32 v[66:67], v[34:35], v[50:51] op_sel_hi:[1,0]
	v_add_u32_e32 v5, 0x4400, v4
	v_pk_mul_f32 v[48:49], v[46:47], v[30:31] op_sel_hi:[1,0]
	v_pk_mul_f32 v[68:69], v[36:37], v[50:51] op_sel_hi:[1,0]
	v_pk_mul_f32 v[40:41], v[12:13], v[30:31] op_sel_hi:[1,0]
	v_pk_mul_f32 v[62:63], v[38:39], v[50:51] op_sel_hi:[1,0]
	v_pk_mul_f32 v[34:35], v[6:7], v[30:31] op_sel_hi:[1,0]
	ds_write2_b32 v4, v66, v67 offset1:68
	ds_write2_b32 v5, v44, v45 offset1:68
	ds_write2_b32 v4, v68, v69 offset0:136 offset1:204
	ds_write2_b32 v5, v48, v49 offset0:136 offset1:204
	v_add_u32_e32 v5, 0x400, v4
	v_add_u32_e32 v6, 0x4800, v4
	v_pk_mul_f32 v[46:47], v[10:11], v[30:31] op_sel_hi:[1,0]
	v_pk_mul_f32 v[36:37], v[8:9], v[30:31] op_sel_hi:[1,0]
	v_pk_mul_f32 v[58:59], v[52:53], v[50:51] op_sel_hi:[1,0]
	ds_write2_b32 v5, v62, v63 offset0:16 offset1:84
	ds_write2_b32 v6, v40, v41 offset0:16 offset1:84
	ds_write2_b32 v5, v64, v65 offset0:152 offset1:220
	ds_write2_b32 v6, v46, v47 offset0:152 offset1:220
	v_add_u32_e32 v5, 0x800, v4
	v_add_u32_e32 v6, 0x4c00, v4
	v_pk_mul_f32 v[60:61], v[20:21], v[50:51] op_sel_hi:[1,0]
	v_pk_mul_f32 v[54:55], v[18:19], v[50:51] op_sel_hi:[1,0]
	v_pk_mul_f32 v[38:39], v[14:15], v[30:31] op_sel_hi:[1,0]
	v_pk_mul_f32 v[56:57], v[16:17], v[50:51] op_sel_hi:[1,0]
	ds_write2_b32 v5, v58, v59 offset0:32 offset1:100
	ds_write2_b32 v6, v36, v37 offset0:32 offset1:100
	ds_write2_b32 v5, v60, v61 offset0:168 offset1:236
	ds_write2_b32 v6, v42, v43 offset0:168 offset1:236
	v_add_u32_e32 v5, 0xc00, v4
	v_add_u32_e32 v4, 0x5000, v4
	v_cmp_eq_u32_e32 vcc, 0, v3
	ds_write2_b32 v5, v54, v55 offset0:48 offset1:116
	ds_write2_b32 v4, v34, v35 offset0:48 offset1:116
	ds_write2_b32 v5, v56, v57 offset0:184 offset1:252
	ds_write2_b32 v4, v38, v39 offset0:184 offset1:252
	s_and_saveexec_b64 s[0:1], vcc
	s_cbranch_execz .LBB0_585
; __device__ __forceinline__ float sigmf(float x) { return __builtin_amdgcn_rcpf(1.f + __expf(-x)); }
; __device__ __forceinline__ void dn1_item(const Params& p, int l, int item, unsigned char* lds) {
;     ...
;     if (seg == 0) {
;         const float a = S32[(size_t)(t0 + i) * 64 + 16 + hd], bb = S32[(size_t)(t0 + i) * 64 + 8 + hd];
;         const float xx = a + p.dn_dtb[l * 8 + hd];
;         const float sp = (xx > 20.f) ? xx : log1pf(__expf(xx));
;         sgc[i] = -__expf(p.dn_alog[l * 8 + hd]) * sp;
;         sbeta[i] = sigmf(bb);
	s_lshl_b32 s88, s4, 2
	s_or_b32 s4, s4, s11
	v_ashrrev_i32_e32 v3, 31, v2
	s_ashr_i32 s5, s4, 31
	v_readlane_b32 s68, v254, 13
	v_lshlrev_b64 v[2:3], 8, v[2:3]
	s_lshl_b64 s[4:5], s[4:5], 2
	v_readlane_b32 s82, v254, 27
	v_lshl_add_u64 v[2:3], s[48:49], 0, v[2:3]
	v_readlane_b32 s83, v254, 28
	s_add_u32 s6, s82, s4
	v_lshl_add_u64 v[2:3], v[2:3], 0, s[88:89]
	s_addc_u32 s7, s83, s5
	global_load_dword v4, v[2:3], off offset:64
	s_nop 0
	global_load_dword v2, v[2:3], off offset:32
	v_readlane_b32 s69, v254, 14
	global_load_dword v3, v1, s[6:7]
	s_mov_b32 s6, 0x41a00000
	v_readlane_b32 s70, v254, 15
	v_readlane_b32 s71, v254, 16
	v_readlane_b32 s72, v254, 17
	v_readlane_b32 s73, v254, 18
	v_readlane_b32 s74, v254, 19
	v_readlane_b32 s75, v254, 20
	v_readlane_b32 s76, v254, 21
	v_readlane_b32 s77, v254, 22
	v_readlane_b32 s78, v254, 23
	v_readlane_b32 s79, v254, 24
	v_readlane_b32 s80, v254, 25
	v_readlane_b32 s81, v254, 26
	s_waitcnt vmcnt(0)
	v_add_f32_e32 v3, v4, v3
	v_cmp_nlt_f32_e32 vcc, s6, v3
	s_and_saveexec_b64 s[6:7], vcc
	s_cbranch_execz .LBB0_584
	v_mul_f32_e32 v3, 0x3fb8aa3b, v3
	v_exp_f32_e32 v3, v3
	s_nop 0
	v_add_f32_e32 v6, 1.0, v3
	v_frexp_mant_f32_e32 v8, v6
	v_cvt_f64_f32_e32 v[4:5], v6
	v_frexp_exp_i32_f64_e32 v4, v[4:5]
	v_cmp_gt_f32_e32 vcc, s59, v8
	v_add_f32_e32 v7, -1.0, v6
	v_sub_f32_e32 v9, v7, v6
	v_subbrev_co_u32_e32 v12, vcc, 0, v4, vcc
	v_sub_u32_e32 v4, 0, v12
	v_sub_f32_e32 v7, v3, v7
	v_add_f32_e32 v9, 1.0, v9
	v_ldexp_f32 v5, v6, v4
	v_add_f32_e32 v7, v7, v9
	v_add_f32_e32 v6, -1.0, v5
	v_add_f32_e32 v8, 1.0, v5
	v_ldexp_f32 v4, v7, v4
	v_add_f32_e32 v7, 1.0, v6
	v_add_f32_e32 v9, -1.0, v8
	v_sub_f32_e32 v7, v5, v7
	v_sub_f32_e32 v5, v5, v9
	v_add_f32_e32 v7, v4, v7
	v_add_f32_e32 v4, v4, v5
	v_add_f32_e32 v13, v8, v4
	v_rcp_f32_e32 v15, v13
	v_sub_f32_e32 v5, v13, v8
	v_sub_f32_e32 v14, v4, v5
	v_add_f32_e32 v5, v6, v7
	v_mul_f32_e32 v17, v5, v15
	v_sub_f32_e32 v4, v5, v6
	v_mul_f32_e32 v6, v13, v17
	v_fma_f32 v8, v17, v13, -v6
	v_fmac_f32_e32 v8, v17, v14
	v_sub_f32_e32 v16, v7, v4
	v_add_f32_e32 v4, v6, v8
	v_sub_f32_e32 v7, v5, v4
	v_pk_add_f32 v[10:11], v[4:5], v[6:7] neg_lo:[0,1] neg_hi:[0,1]
	v_mov_b32_e32 v9, v4
	v_pk_add_f32 v[4:5], v[10:11], v[8:9] neg_lo:[0,1] neg_hi:[0,1]
	v_cmp_neq_f32_e32 vcc, s97, v3
	v_add_f32_e32 v5, v16, v5
	v_add_f32_e32 v4, v4, v5
	v_add_f32_e32 v5, v7, v4
	v_mul_f32_e32 v16, v15, v5
	v_mul_f32_e32 v6, v13, v16
	v_fma_f32 v8, v16, v13, -v6
	v_fmac_f32_e32 v8, v16, v14
	v_sub_f32_e32 v7, v7, v5
	v_add_f32_e32 v13, v4, v7
	v_add_f32_e32 v4, v6, v8
	v_sub_f32_e32 v7, v5, v4
	v_pk_add_f32 v[10:11], v[4:5], v[6:7] neg_lo:[0,1] neg_hi:[0,1]
	v_mov_b32_e32 v9, v4
	v_pk_add_f32 v[4:5], v[10:11], v[8:9] neg_lo:[0,1] neg_hi:[0,1]
	s_nop 0
	v_add_f32_e32 v5, v13, v5
	v_add_f32_e32 v4, v4, v5
	v_add_f32_e32 v5, v17, v16
	v_add_f32_e32 v4, v7, v4
	v_sub_f32_e32 v6, v5, v17
	v_mul_f32_e32 v4, v15, v4
	v_sub_f32_e32 v6, v16, v6
	v_add_f32_e32 v6, v6, v4
	v_add_f32_e32 v8, v5, v6
	v_mul_f32_e32 v9, v8, v8
	v_fmamk_f32 v4, v9, 0x3e9b6dac, v223
	v_fmaak_f32 v181, v9, v4, 0x3f2aaada
	v_cvt_f32_i32_e32 v4, v12
	v_sub_f32_e32 v5, v8, v5
	v_sub_f32_e32 v5, v6, v5
	v_ldexp_f32 v10, v5, 1
	v_mul_f32_e32 v5, v8, v9
	v_ldexp_f32 v7, v8, 1
	v_pk_mul_f32 v[8:9], v[4:5], v[180:181]
	s_nop 0
	v_fma_f32 v6, v4, s96, -v8
	v_fmac_f32_e32 v6, 0xb102e308, v4
	v_pk_add_f32 v[4:5], v[8:9], v[6:7]
	s_nop 0
	v_sub_f32_e32 v7, v5, v7
	v_sub_f32_e32 v7, v9, v7
	v_add_f32_e32 v11, v10, v7
	v_mov_b32_e32 v10, v8
	v_pk_add_f32 v[8:9], v[4:5], v[8:9] neg_lo:[0,1] neg_hi:[0,1]
	v_pk_add_f32 v[12:13], v[4:5], v[10:11]
	v_mov_b32_e32 v7, v4
	v_mov_b32_e32 v9, v13
	v_pk_add_f32 v[14:15], v[6:7], v[8:9] neg_lo:[0,1] neg_hi:[0,1]
	v_pk_add_f32 v[6:7], v[6:7], v[8:9]
	v_mov_b32_e32 v10, v11
	v_pk_add_f32 v[8:9], v[6:7], v[4:5] op_sel:[1,0] op_sel_hi:[0,1] neg_lo:[0,1] neg_hi:[0,1]
	v_pk_add_f32 v[16:17], v[12:13], v[8:9] op_sel_hi:[1,0] neg_lo:[0,1] neg_hi:[0,1]
	v_mov_b32_e32 v12, v13
	v_mov_b32_e32 v13, v7
	v_pk_mov_b32 v[8:9], v[4:5], v[8:9] op_sel:[1,0]
	v_mov_b32_e32 v11, v4
	v_pk_add_f32 v[8:9], v[12:13], v[8:9] neg_lo:[0,1] neg_hi:[0,1]
	v_mov_b32_e32 v16, v14
	v_pk_add_f32 v[4:5], v[10:11], v[8:9] neg_lo:[0,1] neg_hi:[0,1]
	v_mov_b32_e32 v15, v7
	v_pk_add_f32 v[8:9], v[16:17], v[4:5]
	s_nop 0
	v_pk_add_f32 v[10:11], v[8:9], v[8:9] op_sel:[0,1] op_sel_hi:[1,0]
	s_nop 0
	v_pk_add_f32 v[6:7], v[6:7], v[10:11] op_sel:[1,0] op_sel_hi:[0,1]
	v_mov_b32_e32 v9, v6
	v_pk_add_f32 v[12:13], v[8:9], v[14:15] neg_lo:[0,1] neg_hi:[0,1]
	v_mov_b32_e32 v5, v10
	v_sub_f32_e32 v7, v8, v12
	v_pk_add_f32 v[4:5], v[4:5], v[12:13] neg_lo:[0,1] neg_hi:[0,1]
	v_sub_f32_e32 v7, v14, v7
	v_add_f32_e32 v4, v4, v7
	v_add_f32_e32 v4, v4, v5
	v_add_f32_e32 v4, v6, v4
	v_cndmask_b32_e32 v4, v229, v4, vcc
	v_cmp_ngt_f32_e32 vcc, -1.0, v3
	s_nop 1
	v_cndmask_b32_e32 v4, v230, v4, vcc
	v_cmp_neq_f32_e32 vcc, -1.0, v3
	s_nop 1
	v_cndmask_b32_e32 v4, v222, v4, vcc
	v_cmp_lt_f32_e64 vcc, |v3|, s58
	s_nop 1
	v_cndmask_b32_e32 v3, v4, v3, vcc

; #define ZERO44(a) { _Pragma("unroll") for (int _i = 0; _i < 4; ++_i) { _Pragma("unroll") for (int _j = 0; _j < 4; ++_j) a[_i][_j] = 0.f; } }
; __device__ __forceinline__ void mm64(const float* At, const float* B, float (&acc)[4][4], int ty, int tx) {
;     f32x2 c2[4][2];
; #pragma unroll
;     for (int rr = 0; rr < 4; ++rr) { c2[rr][0] = (f32x2){acc[rr][0], acc[rr][1]}; c2[rr][1] = (f32x2){acc[rr][2], acc[rr][3]}; }
; #pragma unroll 8
;     for (int k = 0; k < 64; ++k) {
;         const f32x4 a = *(const f32x4*)(At + k * DLD + 4 * ty);
;         const f32x4 b = *(const f32x4*)(B + k * DLD + 4 * tx);
;         const f32x2 b01 = {b.x, b.y}, b23 = {b.z, b.w};
; #pragma unroll
;         for (int rr = 0; rr < 4; ++rr) {
;             const f32x2 a2 = {a[rr], a[rr]};
;             c2[rr][0] = __builtin_elementwise_fma(a2, b01, c2[rr][0]);
;             c2[rr][1] = __builtin_elementwise_fma(a2, b23, c2[rr][1]);
;         }
;     }
; #pragma unroll
;     for (int rr = 0; rr < 4; ++rr) { acc[rr][0] = c2[rr][0].x; acc[rr][1] = c2[rr][0].y; acc[rr][2] = c2[rr][1].x; acc[rr][3] = c2[rr][1].y; }
; }
; __device__ __forceinline__ void dn1_item(const Params& p, int l, int item, unsigned char* lds) {
;     ...
;         float a1[4][4], a2[4][4]; ZERO44(a1); ZERO44(a2);
;         mm64(B0, B0, a1, ty, tx);
;         mm64(B1, B0, a2, ty, tx);
.LBB0_588:
	ds_read_b128 v[238:241], v220 offset:816
	ds_read_b128 v[242:245], v221 offset:816
	s_waitcnt lgkmcnt(6)
	v_fmac_f32_e32 v16, v204, v208
	v_fmac_f32_e32 v17, v204, v209
	v_fmac_f32_e32 v14, v204, v210
	v_fmac_f32_e32 v15, v204, v211
	v_fmac_f32_e32 v12, v205, v208
	v_fmac_f32_e32 v13, v205, v209
	v_fmac_f32_e32 v10, v205, v210
	v_fmac_f32_e32 v11, v205, v211
	v_fmac_f32_e32 v8, v206, v208
	v_fmac_f32_e32 v9, v206, v209
	v_fmac_f32_e32 v6, v206, v210
	v_fmac_f32_e32 v7, v206, v211
	v_fmac_f32_e32 v4, v207, v208
	v_fmac_f32_e32 v5, v207, v209
	v_fmac_f32_e32 v2, v207, v210
	v_fmac_f32_e32 v3, v207, v211
	ds_read_b128 v[204:207], v220 offset:1088
	ds_read_b128 v[208:211], v221 offset:1088
	s_waitcnt lgkmcnt(6)
	v_fmac_f32_e32 v16, v212, v216
	v_fmac_f32_e32 v17, v212, v217
	v_fmac_f32_e32 v14, v212, v218
	v_fmac_f32_e32 v15, v212, v219
	v_fmac_f32_e32 v12, v213, v216
	v_fmac_f32_e32 v13, v213, v217
	v_fmac_f32_e32 v10, v213, v218
	v_fmac_f32_e32 v11, v213, v219
	v_fmac_f32_e32 v8, v214, v216
	v_fmac_f32_e32 v9, v214, v217
	v_fmac_f32_e32 v6, v214, v218
	v_fmac_f32_e32 v7, v214, v219
	v_fmac_f32_e32 v4, v215, v216
	v_fmac_f32_e32 v5, v215, v217
	v_fmac_f32_e32 v2, v215, v218
	v_fmac_f32_e32 v3, v215, v219
	ds_read_b128 v[212:215], v220 offset:1360
	ds_read_b128 v[216:219], v221 offset:1360
	s_waitcnt lgkmcnt(6)
	v_fmac_f32_e32 v16, v224, v234
	v_fmac_f32_e32 v17, v224, v235
	v_fmac_f32_e32 v14, v224, v236
	v_fmac_f32_e32 v15, v224, v237
	v_fmac_f32_e32 v12, v225, v234
	v_fmac_f32_e32 v13, v225, v235
	v_fmac_f32_e32 v10, v225, v236
	v_fmac_f32_e32 v11, v225, v237
	v_fmac_f32_e32 v8, v226, v234
	v_fmac_f32_e32 v9, v226, v235
	v_fmac_f32_e32 v6, v226, v236
	v_fmac_f32_e32 v7, v226, v237
	v_fmac_f32_e32 v4, v227, v234
	v_fmac_f32_e32 v5, v227, v235
	v_fmac_f32_e32 v2, v227, v236
	v_fmac_f32_e32 v3, v227, v237
	ds_read_b128 v[224:227], v220 offset:1632
	ds_read_b128 v[234:237], v221 offset:1632
	s_waitcnt lgkmcnt(6)
	v_fmac_f32_e32 v16, v238, v242
	v_fmac_f32_e32 v17, v238, v243
	v_fmac_f32_e32 v14, v238, v244
	v_fmac_f32_e32 v15, v238, v245
	v_fmac_f32_e32 v12, v239, v242
	v_fmac_f32_e32 v13, v239, v243
	v_fmac_f32_e32 v10, v239, v244
	v_fmac_f32_e32 v11, v239, v245
	v_fmac_f32_e32 v8, v240, v242
	v_fmac_f32_e32 v9, v240, v243
	v_fmac_f32_e32 v6, v240, v244
	v_fmac_f32_e32 v7, v240, v245
	v_fmac_f32_e32 v4, v241, v242
	v_fmac_f32_e32 v5, v241, v243
	v_fmac_f32_e32 v2, v241, v244
	v_fmac_f32_e32 v3, v241, v245
	ds_read_b128 v[238:241], v220 offset:1904
	ds_read_b128 v[242:245], v221 offset:1904
	s_waitcnt lgkmcnt(6)
	v_fmac_f32_e32 v16, v204, v208
	v_fmac_f32_e32 v17, v204, v209
	v_fmac_f32_e32 v14, v204, v210
	v_fmac_f32_e32 v15, v204, v211
	v_fmac_f32_e32 v12, v205, v208
	v_fmac_f32_e32 v13, v205, v209
	v_fmac_f32_e32 v10, v205, v210
	v_fmac_f32_e32 v11, v205, v211
	v_fmac_f32_e32 v8, v206, v208
	v_fmac_f32_e32 v9, v206, v209
	v_fmac_f32_e32 v6, v206, v210
	v_fmac_f32_e32 v7, v206, v211
	v_fmac_f32_e32 v4, v207, v208
	v_fmac_f32_e32 v5, v207, v209
	v_fmac_f32_e32 v2, v207, v210
	v_fmac_f32_e32 v3, v207, v211
	s_addk_i32 s0, 0x880
	v_add_u32_e32 v220, s0, v51
	v_add_u32_e32 v221, s0, v76
	ds_read_b128 v[204:207], v220
	ds_read_b128 v[208:211], v221
	s_waitcnt lgkmcnt(6)
	v_fmac_f32_e32 v16, v212, v216
	v_fmac_f32_e32 v17, v212, v217
	v_fmac_f32_e32 v14, v212, v218
	v_fmac_f32_e32 v15, v212, v219
	v_fmac_f32_e32 v12, v213, v216
	v_fmac_f32_e32 v13, v213, v217
	v_fmac_f32_e32 v10, v213, v218
	v_fmac_f32_e32 v11, v213, v219
	v_fmac_f32_e32 v8, v214, v216
	v_fmac_f32_e32 v9, v214, v217
	v_fmac_f32_e32 v6, v214, v218
	v_fmac_f32_e32 v7, v214, v219
	v_fmac_f32_e32 v4, v215, v216
	v_fmac_f32_e32 v5, v215, v217
	v_fmac_f32_e32 v2, v215, v218
	v_fmac_f32_e32 v3, v215, v219
	ds_read_b128 v[212:215], v220 offset:272
	ds_read_b128 v[216:219], v221 offset:272
	s_waitcnt lgkmcnt(6)
	v_fmac_f32_e32 v16, v224, v234
	v_fmac_f32_e32 v17, v224, v235
	v_fmac_f32_e32 v14, v224, v236
	v_fmac_f32_e32 v15, v224, v237
	v_fmac_f32_e32 v12, v225, v234
	v_fmac_f32_e32 v13, v225, v235
	v_fmac_f32_e32 v10, v225, v236
	v_fmac_f32_e32 v11, v225, v237
	v_fmac_f32_e32 v8, v226, v234
	v_fmac_f32_e32 v9, v226, v235
	v_fmac_f32_e32 v6, v226, v236
	v_fmac_f32_e32 v7, v226, v237
	v_fmac_f32_e32 v4, v227, v234
	v_fmac_f32_e32 v5, v227, v235
	v_fmac_f32_e32 v2, v227, v236
	v_fmac_f32_e32 v3, v227, v237
	ds_read_b128 v[224:227], v220 offset:544
	ds_read_b128 v[234:237], v221 offset:544
	s_waitcnt lgkmcnt(6)
	v_fmac_f32_e32 v16, v238, v242
	v_fmac_f32_e32 v17, v238, v243
	v_fmac_f32_e32 v14, v238, v244
	v_fmac_f32_e32 v15, v238, v245
	v_fmac_f32_e32 v12, v239, v242
	v_fmac_f32_e32 v13, v239, v243
	v_fmac_f32_e32 v10, v239, v244
	v_fmac_f32_e32 v11, v239, v245
	v_fmac_f32_e32 v8, v240, v242
	v_fmac_f32_e32 v9, v240, v243
	v_fmac_f32_e32 v6, v240, v244
	v_fmac_f32_e32 v7, v240, v245
	v_fmac_f32_e32 v4, v241, v242
	v_fmac_f32_e32 v5, v241, v243
	v_fmac_f32_e32 v2, v241, v244
	v_fmac_f32_e32 v3, v241, v245
	s_cmpk_lg_i32 s0, 0x4400
	s_cbranch_scc1 .LBB0_588
	s_waitcnt lgkmcnt(0)
	v_lshlrev_b32_e32 v77, 4, v104
	v_readlane_b32 s0, v253, 47
	v_mov_b32_e32 v18, 0
	v_mov_b32_e32 v19, v18
	v_add_u32_e32 v93, s0, v77
	s_mov_b32 s0, 0
	v_mov_b32_e32 v102, v18
	v_mov_b32_e32 v103, v18
	v_mov_b32_e32 v100, v18
	v_mov_b32_e32 v101, v18
	v_mov_b32_e32 v98, v18
	v_mov_b32_e32 v99, v18
	v_mov_b32_e32 v96, v18
	v_mov_b32_e32 v97, v18
	v_mov_b32_e32 v94, v18
	v_mov_b32_e32 v95, v18
	v_mov_b32_e32 v52, v18
	v_mov_b32_e32 v53, v18
	v_mov_b32_e32 v20, v18
	v_mov_b32_e32 v21, v18
	v_add_u32_e32 v220, s0, v93
	v_add_u32_e32 v221, s0, v76
	ds_read_b128 v[204:207], v220
	ds_read_b128 v[208:211], v221
	ds_read_b128 v[212:215], v220 offset:272
	ds_read_b128 v[216:219], v221 offset:272
	ds_read_b128 v[224:227], v220 offset:544
	ds_read_b128 v[234:237], v221 offset:544
; __device__ __forceinline__ void mm64(const float* At, const float* B, float (&acc)[4][4], int ty, int tx) {
;     f32x2 c2[4][2];
; #pragma unroll
;     for (int rr = 0; rr < 4; ++rr) { c2[rr][0] = (f32x2){acc[rr][0], acc[rr][1]}; c2[rr][1] = (f32x2){acc[rr][2], acc[rr][3]}; }
; #pragma unroll 8
;     for (int k = 0; k < 64; ++k) {
;         const f32x4 a = *(const f32x4*)(At + k * DLD + 4 * ty);
;         const f32x4 b = *(const f32x4*)(B + k * DLD + 4 * tx);
;         const f32x2 b01 = {b.x, b.y}, b23 = {b.z, b.w};
; #pragma unroll
;         for (int rr = 0; rr < 4; ++rr) {
;             const f32x2 a2 = {a[rr], a[rr]};
;             c2[rr][0] = __builtin_elementwise_fma(a2, b01, c2[rr][0]);
;             c2[rr][1] = __builtin_elementwise_fma(a2, b23, c2[rr][1]);
;         }
;     }
; #pragma unroll
;     for (int rr = 0; rr < 4; ++rr) { acc[rr][0] = c2[rr][0].x; acc[rr][1] = c2[rr][0].y; acc[rr][2] = c2[rr][1].x; acc[rr][3] = c2[rr][1].y; }
; }
; __device__ __forceinline__ void dn1_item(const Params& p, int l, int item, unsigned char* lds) {
;     ...
;         mm64(B1, B0, a2, ty, tx);
; #pragma unroll
;         for (int rr = 0; rr < 4; ++rr) {
;             const int ii = 4 * ty + rr; const float gi = sgc[ii], bi = sbeta[ii];
; #pragma unroll
;             for (int cc = 0; cc < 4; ++cc) {
;                 const int jj = 4 * tx + cc; const float gj = sgc[jj];
;                 const float dec = (ii >= jj) ? __expf(gi - gj) : 0.f;
.LBB0_590:
	ds_read_b128 v[238:241], v220 offset:816
	ds_read_b128 v[242:245], v221 offset:816
	s_waitcnt lgkmcnt(6)
	v_fmac_f32_e32 v102, v204, v208
	v_fmac_f32_e32 v103, v204, v209
	v_fmac_f32_e32 v100, v204, v210
	v_fmac_f32_e32 v101, v204, v211
	v_fmac_f32_e32 v98, v205, v208
	v_fmac_f32_e32 v99, v205, v209
	v_fmac_f32_e32 v96, v205, v210
	v_fmac_f32_e32 v97, v205, v211
	v_fmac_f32_e32 v94, v206, v208
	v_fmac_f32_e32 v95, v206, v209
	v_fmac_f32_e32 v52, v206, v210
	v_fmac_f32_e32 v53, v206, v211
	v_fmac_f32_e32 v20, v207, v208
	v_fmac_f32_e32 v21, v207, v209
	v_fmac_f32_e32 v18, v207, v210
	v_fmac_f32_e32 v19, v207, v211
	ds_read_b128 v[204:207], v220 offset:1088
	ds_read_b128 v[208:211], v221 offset:1088
	s_waitcnt lgkmcnt(6)
	v_fmac_f32_e32 v102, v212, v216
	v_fmac_f32_e32 v103, v212, v217
	v_fmac_f32_e32 v100, v212, v218
	v_fmac_f32_e32 v101, v212, v219
	v_fmac_f32_e32 v98, v213, v216
	v_fmac_f32_e32 v99, v213, v217
	v_fmac_f32_e32 v96, v213, v218
	v_fmac_f32_e32 v97, v213, v219
	v_fmac_f32_e32 v94, v214, v216
	v_fmac_f32_e32 v95, v214, v217
	v_fmac_f32_e32 v52, v214, v218
	v_fmac_f32_e32 v53, v214, v219
	v_fmac_f32_e32 v20, v215, v216
	v_fmac_f32_e32 v21, v215, v217
	v_fmac_f32_e32 v18, v215, v218
	v_fmac_f32_e32 v19, v215, v219
	ds_read_b128 v[212:215], v220 offset:1360
	ds_read_b128 v[216:219], v221 offset:1360
	s_waitcnt lgkmcnt(6)
	v_fmac_f32_e32 v102, v224, v234
	v_fmac_f32_e32 v103, v224, v235
	v_fmac_f32_e32 v100, v224, v236
	v_fmac_f32_e32 v101, v224, v237
	v_fmac_f32_e32 v98, v225, v234
	v_fmac_f32_e32 v99, v225, v235
	v_fmac_f32_e32 v96, v225, v236
	v_fmac_f32_e32 v97, v225, v237
	v_fmac_f32_e32 v94, v226, v234
	v_fmac_f32_e32 v95, v226, v235
	v_fmac_f32_e32 v52, v226, v236
	v_fmac_f32_e32 v53, v226, v237
	v_fmac_f32_e32 v20, v227, v234
	v_fmac_f32_e32 v21, v227, v235
	v_fmac_f32_e32 v18, v227, v236
	v_fmac_f32_e32 v19, v227, v237
	ds_read_b128 v[224:227], v220 offset:1632
	ds_read_b128 v[234:237], v221 offset:1632
	s_waitcnt lgkmcnt(6)
	v_fmac_f32_e32 v102, v238, v242
	v_fmac_f32_e32 v103, v238, v243
	v_fmac_f32_e32 v100, v238, v244
	v_fmac_f32_e32 v101, v238, v245
	v_fmac_f32_e32 v98, v239, v242
	v_fmac_f32_e32 v99, v239, v243
	v_fmac_f32_e32 v96, v239, v244
	v_fmac_f32_e32 v97, v239, v245
	v_fmac_f32_e32 v94, v240, v242
	v_fmac_f32_e32 v95, v240, v243
	v_fmac_f32_e32 v52, v240, v244
	v_fmac_f32_e32 v53, v240, v245
	v_fmac_f32_e32 v20, v241, v242
	v_fmac_f32_e32 v21, v241, v243
	v_fmac_f32_e32 v18, v241, v244
	v_fmac_f32_e32 v19, v241, v245
	ds_read_b128 v[238:241], v220 offset:1904
	ds_read_b128 v[242:245], v221 offset:1904
	s_waitcnt lgkmcnt(6)
	v_fmac_f32_e32 v102, v204, v208
	v_fmac_f32_e32 v103, v204, v209
	v_fmac_f32_e32 v100, v204, v210
	v_fmac_f32_e32 v101, v204, v211
	v_fmac_f32_e32 v98, v205, v208
	v_fmac_f32_e32 v99, v205, v209
	v_fmac_f32_e32 v96, v205, v210
	v_fmac_f32_e32 v97, v205, v211
	v_fmac_f32_e32 v94, v206, v208
	v_fmac_f32_e32 v95, v206, v209
	v_fmac_f32_e32 v52, v206, v210
	v_fmac_f32_e32 v53, v206, v211
	v_fmac_f32_e32 v20, v207, v208
	v_fmac_f32_e32 v21, v207, v209
	v_fmac_f32_e32 v18, v207, v210
	v_fmac_f32_e32 v19, v207, v211
	s_addk_i32 s0, 0x880
	v_add_u32_e32 v220, s0, v93
	v_add_u32_e32 v221, s0, v76
	ds_read_b128 v[204:207], v220
	ds_read_b128 v[208:211], v221
	s_waitcnt lgkmcnt(6)
	v_fmac_f32_e32 v102, v212, v216
	v_fmac_f32_e32 v103, v212, v217
	v_fmac_f32_e32 v100, v212, v218
	v_fmac_f32_e32 v101, v212, v219
	v_fmac_f32_e32 v98, v213, v216
	v_fmac_f32_e32 v99, v213, v217
	v_fmac_f32_e32 v96, v213, v218
	v_fmac_f32_e32 v97, v213, v219
	v_fmac_f32_e32 v94, v214, v216
	v_fmac_f32_e32 v95, v214, v217
	v_fmac_f32_e32 v52, v214, v218
	v_fmac_f32_e32 v53, v214, v219
	v_fmac_f32_e32 v20, v215, v216
	v_fmac_f32_e32 v21, v215, v217
	v_fmac_f32_e32 v18, v215, v218
	v_fmac_f32_e32 v19, v215, v219
	ds_read_b128 v[212:215], v220 offset:272
	ds_read_b128 v[216:219], v221 offset:272
	s_waitcnt lgkmcnt(6)
	v_fmac_f32_e32 v102, v224, v234
	v_fmac_f32_e32 v103, v224, v235
	v_fmac_f32_e32 v100, v224, v236
	v_fmac_f32_e32 v101, v224, v237
	v_fmac_f32_e32 v98, v225, v234
	v_fmac_f32_e32 v99, v225, v235
	v_fmac_f32_e32 v96, v225, v236
	v_fmac_f32_e32 v97, v225, v237
	v_fmac_f32_e32 v94, v226, v234
	v_fmac_f32_e32 v95, v226, v235
	v_fmac_f32_e32 v52, v226, v236
	v_fmac_f32_e32 v53, v226, v237
	v_fmac_f32_e32 v20, v227, v234
	v_fmac_f32_e32 v21, v227, v235
	v_fmac_f32_e32 v18, v227, v236
	v_fmac_f32_e32 v19, v227, v237
	ds_read_b128 v[224:227], v220 offset:544
	ds_read_b128 v[234:237], v221 offset:544
	s_waitcnt lgkmcnt(6)
	v_fmac_f32_e32 v102, v238, v242
	v_fmac_f32_e32 v103, v238, v243
	v_fmac_f32_e32 v100, v238, v244
	v_fmac_f32_e32 v101, v238, v245
	v_fmac_f32_e32 v98, v239, v242
	v_fmac_f32_e32 v99, v239, v243
	v_fmac_f32_e32 v96, v239, v244
	v_fmac_f32_e32 v97, v239, v245
	v_fmac_f32_e32 v94, v240, v242
	v_fmac_f32_e32 v95, v240, v243
	v_fmac_f32_e32 v52, v240, v244
	v_fmac_f32_e32 v53, v240, v245
	v_fmac_f32_e32 v20, v241, v242
	v_fmac_f32_e32 v21, v241, v243
	v_fmac_f32_e32 v18, v241, v244
	v_fmac_f32_e32 v19, v241, v245
	s_cmpk_lg_i32 s0, 0x4400
	s_cbranch_scc1 .LBB0_590
	s_waitcnt lgkmcnt(0)
	v_lshl_add_u32 v0, v105, 2, 0
	v_add_u32_e32 v113, 0x11000, v0
	v_add_u32_e32 v0, 0x11100, v0
	ds_read_b32 v118, v113
	ds_read_b32 v117, v0
	v_cmp_lt_i32_e64 s[40:41], v105, v50
	v_cmp_ge_i32_e32 vcc, v105, v50
	v_mov_b32_e32 v115, 0
	v_lshl_add_u32 v113, v50, 2, 0
	v_mov_b32_e32 v114, 0
	s_and_saveexec_b64 s[0:1], vcc
	s_cbranch_execz .LBB0_593
	v_add_u32_e32 v0, 0x11000, v113
	ds_read_b32 v0, v0
	s_waitcnt lgkmcnt(0)
	v_sub_f32_e32 v0, v118, v0
	v_mul_f32_e32 v0, 0x3fb8aa3b, v0
	v_exp_f32_e32 v114, v0

; __device__ __forceinline__ void dn1_item(const Params& p, int l, int item, unsigned char* lds) {
;     ...
; #pragma unroll 1
;                 for (int bk = bj; bk < bi; ++bk) {
;                     const float* mp = B2 + (16 * bi + br) * DLD + 16 * bk;
;                     const float* tp = B0 + (16 * bj + bc) * DLD + 16 * bk;
; #pragma unroll
;                     for (int m = 0; m < 16; m += 4) {
;                         const f32x4 a = *(const f32x4*)(mp + m), t4 = *(const f32x4*)(tp + m);
;                         x += a.x * t4.x + a.y * t4.y + a.z * t4.z + a.w * t4.w;
;                     }
;                 }
;                 Xs[bj * 256 + br * 16 + bc] = x;
;             }
;             __syncthreads();
.LBB0_628:
	ds_read_b128 v[12:15], v11
	ds_read_b128 v[16:19], v11 offset:16
	ds_read_b128 v[98:101], v11 offset:32
	ds_read_b128 v[112:115], v11 offset:48
	ds_read_b128 v[116:119], v9
	ds_read_b128 v[120:123], v9 offset:16
	ds_read_b128 v[124:127], v9 offset:32
	ds_read_b128 v[128:131], v9 offset:48
	s_waitcnt lgkmcnt(5)
	v_mov_b32_e32 v21, v98
	s_waitcnt lgkmcnt(3)
	v_pk_mul_f32 v[12:13], v[12:13], v[116:117]
	v_mov_b32_e32 v98, v17
	s_waitcnt lgkmcnt(1)
	v_mov_b32_e32 v95, v124
	v_mov_b32_e32 v124, v121
	v_pk_mul_f32 v[14:15], v[14:15], v[118:119]
	v_mov_b32_e32 v20, v16
	v_mov_b32_e32 v94, v120
	v_add_f32_e32 v97, v12, v13
	v_pk_mul_f32 v[12:13], v[98:99], v[124:125]
	v_mov_b32_e32 v16, v18
	v_mov_b32_e32 v17, v100
	v_mov_b32_e32 v116, v122
	v_mov_b32_e32 v117, v126
	v_add_f32_e32 v14, v14, v97
	v_fmac_f32_e32 v12, v20, v94
	v_fmac_f32_e32 v13, v21, v95
	v_mov_b32_e32 v100, v19
	v_mov_b32_e32 v126, v123
	s_waitcnt lgkmcnt(0)
	v_pk_mul_f32 v[112:113], v[112:113], v[128:129]
	v_add_f32_e32 v14, v15, v14
	v_fmac_f32_e32 v12, v16, v116
	v_fmac_f32_e32 v13, v17, v117
	v_pk_mul_f32 v[18:19], v[114:115], v[130:131]
	v_add_f32_e32 v98, v112, v113
	v_add_f32_e32 v10, v10, v14
	v_fmac_f32_e32 v12, v100, v126
	v_fmac_f32_e32 v13, v101, v127
	v_add_f32_e32 v18, v18, v98
	v_add_f32_e32 v10, v10, v12
	s_add_i32 s5, s5, -1
	v_add_f32_e32 v15, v19, v18
	v_add_f32_e32 v10, v10, v13
	v_add_u32_e32 v11, 64, v11
	v_add_u32_e32 v9, 64, v9
	s_cmp_eq_u32 s5, 0
	v_add_f32_e32 v10, v10, v15
	s_cbranch_scc0 .LBB0_628
	v_lshl_add_u32 v9, s1, 10, v2
	s_add_i32 s1, s1, 1
	s_add_i32 s4, s4, -1
	v_add_u32_e32 v8, 64, v8
	s_cmp_eq_u32 s1, s0
	v_add_u32_e32 v7, 0x1140, v7
	ds_write_b32 v9, v10
	s_cbranch_scc0 .LBB0_627
	v_lshl_add_u32 v7, s0, 6, v3
	s_mul_i32 s1, s0, 0x1100
	v_add_u32_e32 v7, s1, v7
	v_mov_b32_e32 v8, v50
	v_mov_b32_e32 v9, v6
	s_mov_b32 s1, s0
	s_waitcnt lgkmcnt(0)
	s_barrier

; #define ZERO44(a) { _Pragma("unroll") for (int _i = 0; _i < 4; ++_i) { _Pragma("unroll") for (int _j = 0; _j < 4; ++_j) a[_i][_j] = 0.f; } }
; __device__ __forceinline__ void mm64(const float* At, const float* B, float (&acc)[4][4], int ty, int tx) {
;     f32x2 c2[4][2];
; #pragma unroll
;     for (int rr = 0; rr < 4; ++rr) { c2[rr][0] = (f32x2){acc[rr][0], acc[rr][1]}; c2[rr][1] = (f32x2){acc[rr][2], acc[rr][3]}; }
; #pragma unroll 8
;     for (int k = 0; k < 64; ++k) {
;         const f32x4 a = *(const f32x4*)(At + k * DLD + 4 * ty);
;         const f32x4 b = *(const f32x4*)(B + k * DLD + 4 * tx);
;         const f32x2 b01 = {b.x, b.y}, b23 = {b.z, b.w};
; #pragma unroll
;         for (int rr = 0; rr < 4; ++rr) {
;             const f32x2 a2 = {a[rr], a[rr]};
;             c2[rr][0] = __builtin_elementwise_fma(a2, b01, c2[rr][0]);
;             c2[rr][1] = __builtin_elementwise_fma(a2, b23, c2[rr][1]);
;         }
;     }
; #pragma unroll
;     for (int rr = 0; rr < 4; ++rr) { acc[rr][0] = c2[rr][0].x; acc[rr][1] = c2[rr][0].y; acc[rr][2] = c2[rr][1].x; acc[rr][3] = c2[rr][1].y; }
; }
; __device__ __forceinline__ void dn1_item(const Params& p, int l, int item, unsigned char* lds) {
;     ...
;     float wacc[4][4], uacc[4][4]; ZERO44(wacc); ZERO44(uacc);
;     mm64(B0, B1, wacc, ty, tx);
; #pragma unroll
;     for (int e = 0; e < 16; e += 4) { f32x4 w = {vv[e] * beti, vv[e + 1] * beti, vv[e + 2] * beti, vv[e + 3] * beti}; *(f32x4*)(B2 + i * DLD + d0 + e) = w; }
;     __syncthreads();
;     mm64(B0, B2, uacc, ty, tx);
.LBB0_634:
	ds_read_b128 v[238:241], v220 offset:816
	ds_read_b128 v[242:245], v221 offset:816
	s_waitcnt lgkmcnt(6)
	v_fmac_f32_e32 v14, v204, v208
	v_fmac_f32_e32 v15, v204, v209
	v_fmac_f32_e32 v16, v204, v210
	v_fmac_f32_e32 v17, v204, v211
	v_fmac_f32_e32 v10, v205, v208
	v_fmac_f32_e32 v11, v205, v209
	v_fmac_f32_e32 v12, v205, v210
	v_fmac_f32_e32 v13, v205, v211
	v_fmac_f32_e32 v6, v206, v208
	v_fmac_f32_e32 v7, v206, v209
	v_fmac_f32_e32 v8, v206, v210
	v_fmac_f32_e32 v9, v206, v211
	v_fmac_f32_e32 v2, v207, v208
	v_fmac_f32_e32 v3, v207, v209
	v_fmac_f32_e32 v4, v207, v210
	v_fmac_f32_e32 v5, v207, v211
	ds_read_b128 v[204:207], v220 offset:1088
	ds_read_b128 v[208:211], v221 offset:1088
	s_waitcnt lgkmcnt(6)
	v_fmac_f32_e32 v14, v212, v216
	v_fmac_f32_e32 v15, v212, v217
	v_fmac_f32_e32 v16, v212, v218
	v_fmac_f32_e32 v17, v212, v219
	v_fmac_f32_e32 v10, v213, v216
	v_fmac_f32_e32 v11, v213, v217
	v_fmac_f32_e32 v12, v213, v218
	v_fmac_f32_e32 v13, v213, v219
	v_fmac_f32_e32 v6, v214, v216
	v_fmac_f32_e32 v7, v214, v217
	v_fmac_f32_e32 v8, v214, v218
	v_fmac_f32_e32 v9, v214, v219
	v_fmac_f32_e32 v2, v215, v216
	v_fmac_f32_e32 v3, v215, v217
	v_fmac_f32_e32 v4, v215, v218
	v_fmac_f32_e32 v5, v215, v219
	ds_read_b128 v[212:215], v220 offset:1360
	ds_read_b128 v[216:219], v221 offset:1360
	s_waitcnt lgkmcnt(6)
	v_fmac_f32_e32 v14, v224, v234
	v_fmac_f32_e32 v15, v224, v235
	v_fmac_f32_e32 v16, v224, v236
	v_fmac_f32_e32 v17, v224, v237
	v_fmac_f32_e32 v10, v225, v234
	v_fmac_f32_e32 v11, v225, v235
	v_fmac_f32_e32 v12, v225, v236
	v_fmac_f32_e32 v13, v225, v237
	v_fmac_f32_e32 v6, v226, v234
	v_fmac_f32_e32 v7, v226, v235
	v_fmac_f32_e32 v8, v226, v236
	v_fmac_f32_e32 v9, v226, v237
	v_fmac_f32_e32 v2, v227, v234
	v_fmac_f32_e32 v3, v227, v235
	v_fmac_f32_e32 v4, v227, v236
	v_fmac_f32_e32 v5, v227, v237
	ds_read_b128 v[224:227], v220 offset:1632
	ds_read_b128 v[234:237], v221 offset:1632
	s_waitcnt lgkmcnt(6)
	v_fmac_f32_e32 v14, v238, v242
	v_fmac_f32_e32 v15, v238, v243
	v_fmac_f32_e32 v16, v238, v244
	v_fmac_f32_e32 v17, v238, v245
	v_fmac_f32_e32 v10, v239, v242
	v_fmac_f32_e32 v11, v239, v243
	v_fmac_f32_e32 v12, v239, v244
	v_fmac_f32_e32 v13, v239, v245
	v_fmac_f32_e32 v6, v240, v242
	v_fmac_f32_e32 v7, v240, v243
	v_fmac_f32_e32 v8, v240, v244
	v_fmac_f32_e32 v9, v240, v245
	v_fmac_f32_e32 v2, v241, v242
	v_fmac_f32_e32 v3, v241, v243
	v_fmac_f32_e32 v4, v241, v244
	v_fmac_f32_e32 v5, v241, v245
	ds_read_b128 v[238:241], v220 offset:1904
	ds_read_b128 v[242:245], v221 offset:1904
	s_waitcnt lgkmcnt(6)
	v_fmac_f32_e32 v14, v204, v208
	v_fmac_f32_e32 v15, v204, v209
	v_fmac_f32_e32 v16, v204, v210
	v_fmac_f32_e32 v17, v204, v211
	v_fmac_f32_e32 v10, v205, v208
	v_fmac_f32_e32 v11, v205, v209
	v_fmac_f32_e32 v12, v205, v210
	v_fmac_f32_e32 v13, v205, v211
	v_fmac_f32_e32 v6, v206, v208
	v_fmac_f32_e32 v7, v206, v209
	v_fmac_f32_e32 v8, v206, v210
	v_fmac_f32_e32 v9, v206, v211
	v_fmac_f32_e32 v2, v207, v208
	v_fmac_f32_e32 v3, v207, v209
	v_fmac_f32_e32 v4, v207, v210
	v_fmac_f32_e32 v5, v207, v211
	s_addk_i32 s0, 0x880
	v_add_u32_e32 v220, s0, v51
	v_add_u32_e32 v221, s0, v95
	ds_read_b128 v[204:207], v220
	ds_read_b128 v[208:211], v221
	s_waitcnt lgkmcnt(6)
	v_fmac_f32_e32 v14, v212, v216
	v_fmac_f32_e32 v15, v212, v217
	v_fmac_f32_e32 v16, v212, v218
	v_fmac_f32_e32 v17, v212, v219
	v_fmac_f32_e32 v10, v213, v216
	v_fmac_f32_e32 v11, v213, v217
	v_fmac_f32_e32 v12, v213, v218
	v_fmac_f32_e32 v13, v213, v219
	v_fmac_f32_e32 v6, v214, v216
	v_fmac_f32_e32 v7, v214, v217
	v_fmac_f32_e32 v8, v214, v218
	v_fmac_f32_e32 v9, v214, v219
	v_fmac_f32_e32 v2, v215, v216
	v_fmac_f32_e32 v3, v215, v217
	v_fmac_f32_e32 v4, v215, v218
	v_fmac_f32_e32 v5, v215, v219
	ds_read_b128 v[212:215], v220 offset:272
	ds_read_b128 v[216:219], v221 offset:272
	s_waitcnt lgkmcnt(6)
	v_fmac_f32_e32 v14, v224, v234
	v_fmac_f32_e32 v15, v224, v235
	v_fmac_f32_e32 v16, v224, v236
	v_fmac_f32_e32 v17, v224, v237
	v_fmac_f32_e32 v10, v225, v234
	v_fmac_f32_e32 v11, v225, v235
	v_fmac_f32_e32 v12, v225, v236
	v_fmac_f32_e32 v13, v225, v237
	v_fmac_f32_e32 v6, v226, v234
	v_fmac_f32_e32 v7, v226, v235
	v_fmac_f32_e32 v8, v226, v236
	v_fmac_f32_e32 v9, v226, v237
	v_fmac_f32_e32 v2, v227, v234
	v_fmac_f32_e32 v3, v227, v235
	v_fmac_f32_e32 v4, v227, v236
	v_fmac_f32_e32 v5, v227, v237
	ds_read_b128 v[224:227], v220 offset:544
	ds_read_b128 v[234:237], v221 offset:544
	s_waitcnt lgkmcnt(6)
	v_fmac_f32_e32 v14, v238, v242
	v_fmac_f32_e32 v15, v238, v243
	v_fmac_f32_e32 v16, v238, v244
	v_fmac_f32_e32 v17, v238, v245
	v_fmac_f32_e32 v10, v239, v242
	v_fmac_f32_e32 v11, v239, v243
	v_fmac_f32_e32 v12, v239, v244
	v_fmac_f32_e32 v13, v239, v245
	v_fmac_f32_e32 v6, v240, v242
	v_fmac_f32_e32 v7, v240, v243
	v_fmac_f32_e32 v8, v240, v244
	v_fmac_f32_e32 v9, v240, v245
	v_fmac_f32_e32 v2, v241, v242
	v_fmac_f32_e32 v3, v241, v243
	v_fmac_f32_e32 v4, v241, v244
	v_fmac_f32_e32 v5, v241, v245
	s_cmpk_lg_i32 s0, 0x4400
	s_cbranch_scc1 .LBB0_634
	s_waitcnt lgkmcnt(0)
	v_pk_mul_f32 v[18:19], v[22:23], v[30:31]
	v_pk_mul_f32 v[20:21], v[24:25], v[78:79]
	v_pk_mul_f32 v[18:19], v[18:19], v[92:93] op_sel_hi:[1,0]
	v_pk_mul_f32 v[20:21], v[20:21], v[92:93] op_sel_hi:[1,0]
	ds_write_b128 v53, v[18:21] offset:34816
	v_pk_mul_f32 v[18:19], v[26:27], v[80:81]
	v_pk_mul_f32 v[20:21], v[28:29], v[82:83]
	v_pk_mul_f32 v[18:19], v[18:19], v[92:93] op_sel_hi:[1,0]
	v_pk_mul_f32 v[20:21], v[20:21], v[92:93] op_sel_hi:[1,0]
	ds_write_b128 v53, v[18:21] offset:34832
	v_pk_mul_f32 v[18:19], v[32:33], v[84:85]
	v_pk_mul_f32 v[20:21], v[70:71], v[86:87]
	v_pk_mul_f32 v[18:19], v[18:19], v[92:93] op_sel_hi:[1,0]
	v_pk_mul_f32 v[20:21], v[20:21], v[92:93] op_sel_hi:[1,0]
	ds_write_b128 v53, v[18:21] offset:34848
	v_pk_mul_f32 v[18:19], v[72:73], v[88:89]
	v_pk_mul_f32 v[20:21], v[74:75], v[90:91]
	v_pk_mul_f32 v[18:19], v[18:19], v[92:93] op_sel_hi:[1,0]
	v_pk_mul_f32 v[20:21], v[20:21], v[92:93] op_sel_hi:[1,0]
	ds_write_b128 v53, v[18:21] offset:34864
	v_readlane_b32 s0, v253, 51
	v_mov_b32_e32 v20, 0
	v_mov_b32_e32 v21, v20
	v_add_u32_e32 v70, s0, v94
	s_mov_b32 s0, 0
	v_mov_b32_e32 v30, v20
	v_mov_b32_e32 v31, v20
	v_mov_b32_e32 v32, v20
	v_mov_b32_e32 v33, v20
	v_mov_b32_e32 v26, v20
	v_mov_b32_e32 v27, v20
	v_mov_b32_e32 v28, v20
	v_mov_b32_e32 v29, v20
	v_mov_b32_e32 v22, v20
	v_mov_b32_e32 v23, v20
	v_mov_b32_e32 v24, v20
	v_mov_b32_e32 v25, v20
	v_mov_b32_e32 v18, v20
	v_mov_b32_e32 v19, v20
	s_waitcnt lgkmcnt(0)
	s_barrier
	v_add_u32_e32 v220, s0, v51
	v_add_u32_e32 v221, s0, v70
	ds_read_b128 v[204:207], v220
	ds_read_b128 v[208:211], v221
	ds_read_b128 v[212:215], v220 offset:272
	ds_read_b128 v[216:219], v221 offset:272
	ds_read_b128 v[224:227], v220 offset:544
	ds_read_b128 v[234:237], v221 offset:544
; #define ZERO44(a) { _Pragma("unroll") for (int _i = 0; _i < 4; ++_i) { _Pragma("unroll") for (int _j = 0; _j < 4; ++_j) a[_i][_j] = 0.f; } }
; __device__ __forceinline__ void mm64(const float* At, const float* B, float (&acc)[4][4], int ty, int tx) {
;     f32x2 c2[4][2];
; #pragma unroll
;     for (int rr = 0; rr < 4; ++rr) { c2[rr][0] = (f32x2){acc[rr][0], acc[rr][1]}; c2[rr][1] = (f32x2){acc[rr][2], acc[rr][3]}; }
; #pragma unroll 8
;     for (int k = 0; k < 64; ++k) {
;         const f32x4 a = *(const f32x4*)(At + k * DLD + 4 * ty);
;         const f32x4 b = *(const f32x4*)(B + k * DLD + 4 * tx);
;         const f32x2 b01 = {b.x, b.y}, b23 = {b.z, b.w};
; #pragma unroll
;         for (int rr = 0; rr < 4; ++rr) {
;             const f32x2 a2 = {a[rr], a[rr]};
;             c2[rr][0] = __builtin_elementwise_fma(a2, b01, c2[rr][0]);
;             c2[rr][1] = __builtin_elementwise_fma(a2, b23, c2[rr][1]);
;         }
;     }
; #pragma unroll
;     for (int rr = 0; rr < 4; ++rr) { acc[rr][0] = c2[rr][0].x; acc[rr][1] = c2[rr][0].y; acc[rr][2] = c2[rr][1].x; acc[rr][3] = c2[rr][1].y; }
; }
; __device__ __forceinline__ void dn1_item(const Params& p, int l, int item, unsigned char* lds) {
;     ...
;     mm64(B0, B2, uacc, ty, tx);
;     __syncthreads();
; #pragma unroll
;     for (int rr = 0; rr < 4; ++rr) {
;         f32x4 w = {wacc[rr][0], wacc[rr][1], wacc[rr][2], wacc[rr][3]}; *(f32x4*)(B1 + (4 * ty + rr) * DLD + 4 * tx) = w;
;         f32x4 u = {uacc[rr][0], uacc[rr][1], uacc[rr][2], uacc[rr][3]}; *(f32x4*)(B2 + (4 * ty + rr) * DLD + 4 * tx) = u;
;     }
;     {
;         const float s = __expf(gcl - gci);
; #pragma unroll
;         for (int e = 0; e < 16; e += 4) { f32x4 w = {kn[e] * s, kn[e + 1] * s, kn[e + 2] * s, kn[e + 3] * s}; *(f32x4*)(B0 + i * DLD + d0 + e) = w; }
;     }
;     __syncthreads();
;     {
;         float a1[4][4]; ZERO44(a1);
;         mm64(B0, B1, a1, ty, tx);
.LBB0_636:
	ds_read_b128 v[238:241], v220 offset:816
	ds_read_b128 v[242:245], v221 offset:816
	s_waitcnt lgkmcnt(6)
	v_fmac_f32_e32 v30, v204, v208
	v_fmac_f32_e32 v31, v204, v209
	v_fmac_f32_e32 v32, v204, v210
	v_fmac_f32_e32 v33, v204, v211
	v_fmac_f32_e32 v26, v205, v208
	v_fmac_f32_e32 v27, v205, v209
	v_fmac_f32_e32 v28, v205, v210
	v_fmac_f32_e32 v29, v205, v211
	v_fmac_f32_e32 v22, v206, v208
	v_fmac_f32_e32 v23, v206, v209
	v_fmac_f32_e32 v24, v206, v210
	v_fmac_f32_e32 v25, v206, v211
	v_fmac_f32_e32 v18, v207, v208
	v_fmac_f32_e32 v19, v207, v209
	v_fmac_f32_e32 v20, v207, v210
	v_fmac_f32_e32 v21, v207, v211
	ds_read_b128 v[204:207], v220 offset:1088
	ds_read_b128 v[208:211], v221 offset:1088
	s_waitcnt lgkmcnt(6)
	v_fmac_f32_e32 v30, v212, v216
	v_fmac_f32_e32 v31, v212, v217
	v_fmac_f32_e32 v32, v212, v218
	v_fmac_f32_e32 v33, v212, v219
	v_fmac_f32_e32 v26, v213, v216
	v_fmac_f32_e32 v27, v213, v217
	v_fmac_f32_e32 v28, v213, v218
	v_fmac_f32_e32 v29, v213, v219
	v_fmac_f32_e32 v22, v214, v216
	v_fmac_f32_e32 v23, v214, v217
	v_fmac_f32_e32 v24, v214, v218
	v_fmac_f32_e32 v25, v214, v219
	v_fmac_f32_e32 v18, v215, v216
	v_fmac_f32_e32 v19, v215, v217
	v_fmac_f32_e32 v20, v215, v218
	v_fmac_f32_e32 v21, v215, v219
	ds_read_b128 v[212:215], v220 offset:1360
	ds_read_b128 v[216:219], v221 offset:1360
	s_waitcnt lgkmcnt(6)
	v_fmac_f32_e32 v30, v224, v234
	v_fmac_f32_e32 v31, v224, v235
	v_fmac_f32_e32 v32, v224, v236
	v_fmac_f32_e32 v33, v224, v237
	v_fmac_f32_e32 v26, v225, v234
	v_fmac_f32_e32 v27, v225, v235
	v_fmac_f32_e32 v28, v225, v236
	v_fmac_f32_e32 v29, v225, v237
	v_fmac_f32_e32 v22, v226, v234
	v_fmac_f32_e32 v23, v226, v235
	v_fmac_f32_e32 v24, v226, v236
	v_fmac_f32_e32 v25, v226, v237
	v_fmac_f32_e32 v18, v227, v234
	v_fmac_f32_e32 v19, v227, v235
	v_fmac_f32_e32 v20, v227, v236
	v_fmac_f32_e32 v21, v227, v237
	ds_read_b128 v[224:227], v220 offset:1632
	ds_read_b128 v[234:237], v221 offset:1632
	s_waitcnt lgkmcnt(6)
	v_fmac_f32_e32 v30, v238, v242
	v_fmac_f32_e32 v31, v238, v243
	v_fmac_f32_e32 v32, v238, v244
	v_fmac_f32_e32 v33, v238, v245
	v_fmac_f32_e32 v26, v239, v242
	v_fmac_f32_e32 v27, v239, v243
	v_fmac_f32_e32 v28, v239, v244
	v_fmac_f32_e32 v29, v239, v245
	v_fmac_f32_e32 v22, v240, v242
	v_fmac_f32_e32 v23, v240, v243
	v_fmac_f32_e32 v24, v240, v244
	v_fmac_f32_e32 v25, v240, v245
	v_fmac_f32_e32 v18, v241, v242
	v_fmac_f32_e32 v19, v241, v243
	v_fmac_f32_e32 v20, v241, v244
	v_fmac_f32_e32 v21, v241, v245
	ds_read_b128 v[238:241], v220 offset:1904
	ds_read_b128 v[242:245], v221 offset:1904
	s_waitcnt lgkmcnt(6)
	v_fmac_f32_e32 v30, v204, v208
	v_fmac_f32_e32 v31, v204, v209
	v_fmac_f32_e32 v32, v204, v210
	v_fmac_f32_e32 v33, v204, v211
	v_fmac_f32_e32 v26, v205, v208
	v_fmac_f32_e32 v27, v205, v209
	v_fmac_f32_e32 v28, v205, v210
	v_fmac_f32_e32 v29, v205, v211
	v_fmac_f32_e32 v22, v206, v208
	v_fmac_f32_e32 v23, v206, v209
	v_fmac_f32_e32 v24, v206, v210
	v_fmac_f32_e32 v25, v206, v211
	v_fmac_f32_e32 v18, v207, v208
	v_fmac_f32_e32 v19, v207, v209
	v_fmac_f32_e32 v20, v207, v210
	v_fmac_f32_e32 v21, v207, v211
	s_addk_i32 s0, 0x880
	v_add_u32_e32 v220, s0, v51
	v_add_u32_e32 v221, s0, v70
	ds_read_b128 v[204:207], v220
	ds_read_b128 v[208:211], v221
	s_waitcnt lgkmcnt(6)
	v_fmac_f32_e32 v30, v212, v216
	v_fmac_f32_e32 v31, v212, v217
	v_fmac_f32_e32 v32, v212, v218
	v_fmac_f32_e32 v33, v212, v219
	v_fmac_f32_e32 v26, v213, v216
	v_fmac_f32_e32 v27, v213, v217
	v_fmac_f32_e32 v28, v213, v218
	v_fmac_f32_e32 v29, v213, v219
	v_fmac_f32_e32 v22, v214, v216
	v_fmac_f32_e32 v23, v214, v217
	v_fmac_f32_e32 v24, v214, v218
	v_fmac_f32_e32 v25, v214, v219
	v_fmac_f32_e32 v18, v215, v216
	v_fmac_f32_e32 v19, v215, v217
	v_fmac_f32_e32 v20, v215, v218
	v_fmac_f32_e32 v21, v215, v219
	ds_read_b128 v[212:215], v220 offset:272
	ds_read_b128 v[216:219], v221 offset:272
	s_waitcnt lgkmcnt(6)
	v_fmac_f32_e32 v30, v224, v234
	v_fmac_f32_e32 v31, v224, v235
	v_fmac_f32_e32 v32, v224, v236
	v_fmac_f32_e32 v33, v224, v237
	v_fmac_f32_e32 v26, v225, v234
	v_fmac_f32_e32 v27, v225, v235
	v_fmac_f32_e32 v28, v225, v236
	v_fmac_f32_e32 v29, v225, v237
	v_fmac_f32_e32 v22, v226, v234
	v_fmac_f32_e32 v23, v226, v235
	v_fmac_f32_e32 v24, v226, v236
	v_fmac_f32_e32 v25, v226, v237
	v_fmac_f32_e32 v18, v227, v234
	v_fmac_f32_e32 v19, v227, v235
	v_fmac_f32_e32 v20, v227, v236
	v_fmac_f32_e32 v21, v227, v237
	ds_read_b128 v[224:227], v220 offset:544
	ds_read_b128 v[234:237], v221 offset:544
	s_waitcnt lgkmcnt(6)
	v_fmac_f32_e32 v30, v238, v242
	v_fmac_f32_e32 v31, v238, v243
	v_fmac_f32_e32 v32, v238, v244
	v_fmac_f32_e32 v33, v238, v245
	v_fmac_f32_e32 v26, v239, v242
	v_fmac_f32_e32 v27, v239, v243
	v_fmac_f32_e32 v28, v239, v244
	v_fmac_f32_e32 v29, v239, v245
	v_fmac_f32_e32 v22, v240, v242
	v_fmac_f32_e32 v23, v240, v243
	v_fmac_f32_e32 v24, v240, v244
	v_fmac_f32_e32 v25, v240, v245
	v_fmac_f32_e32 v18, v241, v242
	v_fmac_f32_e32 v19, v241, v243
	v_fmac_f32_e32 v20, v241, v244
	v_fmac_f32_e32 v21, v241, v245
	s_cmpk_lg_i32 s0, 0x4400
	s_cbranch_scc1 .LBB0_636
	s_waitcnt lgkmcnt(0)
	v_lshl_add_u32 v71, v96, 2, v76
	s_movk_i32 s0, 0x110
	s_barrier
	ds_write_b128 v71, v[14:17] offset:17408
	ds_write_b128 v71, v[30:33] offset:34816
	v_mad_u64_u32 v[14:15], s[0:1], v103, s0, v[76:77]
	ds_write_b128 v14, v[10:13] offset:17408
	ds_write_b128 v14, v[26:29] offset:34816
	ds_write_b128 v14, v[6:9] offset:17680
	v_sub_f32_e32 v6, v106, v109
	v_mul_f32_e32 v6, 0x3fb8aa3b, v6
	v_exp_f32_e32 v6, v6
	ds_write_b128 v14, v[22:25] offset:35088
	ds_write_b128 v14, v[2:5] offset:17952
	ds_write_b128 v14, v[18:21] offset:35360
	s_mov_b32 s0, 0
	v_pk_mul_f32 v[4:5], v[68:69], v[6:7] op_sel_hi:[1,0]
	v_pk_mul_f32 v[2:3], v[66:67], v[6:7] op_sel_hi:[1,0]
	ds_write_b128 v53, v[2:5]
	v_pk_mul_f32 v[4:5], v[64:65], v[6:7] op_sel_hi:[1,0]
	v_pk_mul_f32 v[2:3], v[62:63], v[6:7] op_sel_hi:[1,0]
	ds_write_b128 v53, v[2:5] offset:16
	v_pk_mul_f32 v[4:5], v[60:61], v[6:7] op_sel_hi:[1,0]
	v_pk_mul_f32 v[2:3], v[58:59], v[6:7] op_sel_hi:[1,0]
	ds_write_b128 v53, v[2:5] offset:32
	v_pk_mul_f32 v[4:5], v[56:57], v[6:7] op_sel_hi:[1,0]
	v_pk_mul_f32 v[2:3], v[54:55], v[6:7] op_sel_hi:[1,0]
	ds_write_b128 v53, v[2:5] offset:48
	v_mov_b32_e32 v2, 0
	v_mov_b32_e32 v3, v2
	v_mov_b32_e32 v14, v2
	v_mov_b32_e32 v15, v2
	v_mov_b32_e32 v16, v2
	v_mov_b32_e32 v17, v2
	v_mov_b32_e32 v10, v2
	v_mov_b32_e32 v11, v2
	v_mov_b32_e32 v12, v2
	v_mov_b32_e32 v13, v2
	v_mov_b32_e32 v6, v2
	v_mov_b32_e32 v7, v2
	v_mov_b32_e32 v8, v2
	v_mov_b32_e32 v9, v2
	v_mov_b32_e32 v4, v2
	v_mov_b32_e32 v5, v2
	s_waitcnt lgkmcnt(0)
	s_barrier
	v_add_u32_e32 v220, s0, v51
	v_add_u32_e32 v221, s0, v95
	ds_read_b128 v[204:207], v220
	ds_read_b128 v[208:211], v221
	ds_read_b128 v[212:215], v220 offset:272
	ds_read_b128 v[216:219], v221 offset:272
	ds_read_b128 v[224:227], v220 offset:544
	ds_read_b128 v[234:237], v221 offset:544
; #define ZERO44(a) { _Pragma("unroll") for (int _i = 0; _i < 4; ++_i) { _Pragma("unroll") for (int _j = 0; _j < 4; ++_j) a[_i][_j] = 0.f; } }
; __device__ __forceinline__ void mm64(const float* At, const float* B, float (&acc)[4][4], int ty, int tx) {
;     f32x2 c2[4][2];
; #pragma unroll
;     for (int rr = 0; rr < 4; ++rr) { c2[rr][0] = (f32x2){acc[rr][0], acc[rr][1]}; c2[rr][1] = (f32x2){acc[rr][2], acc[rr][3]}; }
; #pragma unroll 8
;     for (int k = 0; k < 64; ++k) {
;         const f32x4 a = *(const f32x4*)(At + k * DLD + 4 * ty);
;         const f32x4 b = *(const f32x4*)(B + k * DLD + 4 * tx);
;         const f32x2 b01 = {b.x, b.y}, b23 = {b.z, b.w};
; #pragma unroll
;         for (int rr = 0; rr < 4; ++rr) {
;             const f32x2 a2 = {a[rr], a[rr]};
;             c2[rr][0] = __builtin_elementwise_fma(a2, b01, c2[rr][0]);
;             c2[rr][1] = __builtin_elementwise_fma(a2, b23, c2[rr][1]);
;         }
;     }
; #pragma unroll
;     for (int rr = 0; rr < 4; ++rr) { acc[rr][0] = c2[rr][0].x; acc[rr][1] = c2[rr][0].y; acc[rr][2] = c2[rr][1].x; acc[rr][3] = c2[rr][1].y; }
; }
; __device__ __forceinline__ void dn1_item(const Params& p, int l, int item, unsigned char* lds) {
;     ...
;         mm64(B0, B1, a1, ty, tx);
; #pragma unroll
;         for (int rr = 0; rr < 4; ++rr) {
;             f32x4 w;
; #pragma unroll
;             for (int cc = 0; cc < 4; ++cc) w[cc] = ((4 * ty + rr) == (4 * tx + cc) ? gl : 0.f) - a1[rr][cc];
;             *(f32x4*)(DNA + (4 * ty + rr) * 64 + 4 * tx) = w;
;         }
;         ZERO44(a1);
;         mm64(B0, B2, a1, ty, tx);
; #pragma unroll
;         for (int rr = 0; rr < 4; ++rr) { f32x4 w = {a1[rr][0], a1[rr][1], a1[rr][2], a1[rr][3]}; *(f32x4*)(DNB + (4 * ty + rr) * 64 + 4 * tx) = w; }
.LBB0_638:
	ds_read_b128 v[238:241], v220 offset:816
	ds_read_b128 v[242:245], v221 offset:816
	s_waitcnt lgkmcnt(6)
	v_fmac_f32_e32 v14, v204, v208
	v_fmac_f32_e32 v15, v204, v209
	v_fmac_f32_e32 v16, v204, v210
	v_fmac_f32_e32 v17, v204, v211
	v_fmac_f32_e32 v10, v205, v208
	v_fmac_f32_e32 v11, v205, v209
	v_fmac_f32_e32 v12, v205, v210
	v_fmac_f32_e32 v13, v205, v211
	v_fmac_f32_e32 v6, v206, v208
	v_fmac_f32_e32 v7, v206, v209
	v_fmac_f32_e32 v8, v206, v210
	v_fmac_f32_e32 v9, v206, v211
	v_fmac_f32_e32 v4, v207, v208
	v_fmac_f32_e32 v5, v207, v209
	v_fmac_f32_e32 v2, v207, v210
	v_fmac_f32_e32 v3, v207, v211
	ds_read_b128 v[204:207], v220 offset:1088
	ds_read_b128 v[208:211], v221 offset:1088
	s_waitcnt lgkmcnt(6)
	v_fmac_f32_e32 v14, v212, v216
	v_fmac_f32_e32 v15, v212, v217
	v_fmac_f32_e32 v16, v212, v218
	v_fmac_f32_e32 v17, v212, v219
	v_fmac_f32_e32 v10, v213, v216
	v_fmac_f32_e32 v11, v213, v217
	v_fmac_f32_e32 v12, v213, v218
	v_fmac_f32_e32 v13, v213, v219
	v_fmac_f32_e32 v6, v214, v216
	v_fmac_f32_e32 v7, v214, v217
	v_fmac_f32_e32 v8, v214, v218
	v_fmac_f32_e32 v9, v214, v219
	v_fmac_f32_e32 v4, v215, v216
	v_fmac_f32_e32 v5, v215, v217
	v_fmac_f32_e32 v2, v215, v218
	v_fmac_f32_e32 v3, v215, v219
	ds_read_b128 v[212:215], v220 offset:1360
	ds_read_b128 v[216:219], v221 offset:1360
	s_waitcnt lgkmcnt(6)
	v_fmac_f32_e32 v14, v224, v234
	v_fmac_f32_e32 v15, v224, v235
	v_fmac_f32_e32 v16, v224, v236
	v_fmac_f32_e32 v17, v224, v237
	v_fmac_f32_e32 v10, v225, v234
	v_fmac_f32_e32 v11, v225, v235
	v_fmac_f32_e32 v12, v225, v236
	v_fmac_f32_e32 v13, v225, v237
	v_fmac_f32_e32 v6, v226, v234
	v_fmac_f32_e32 v7, v226, v235
	v_fmac_f32_e32 v8, v226, v236
	v_fmac_f32_e32 v9, v226, v237
	v_fmac_f32_e32 v4, v227, v234
	v_fmac_f32_e32 v5, v227, v235
	v_fmac_f32_e32 v2, v227, v236
	v_fmac_f32_e32 v3, v227, v237
	ds_read_b128 v[224:227], v220 offset:1632
	ds_read_b128 v[234:237], v221 offset:1632
	s_waitcnt lgkmcnt(6)
	v_fmac_f32_e32 v14, v238, v242
	v_fmac_f32_e32 v15, v238, v243
	v_fmac_f32_e32 v16, v238, v244
	v_fmac_f32_e32 v17, v238, v245
	v_fmac_f32_e32 v10, v239, v242
	v_fmac_f32_e32 v11, v239, v243
	v_fmac_f32_e32 v12, v239, v244
	v_fmac_f32_e32 v13, v239, v245
	v_fmac_f32_e32 v6, v240, v242
	v_fmac_f32_e32 v7, v240, v243
	v_fmac_f32_e32 v8, v240, v244
	v_fmac_f32_e32 v9, v240, v245
	v_fmac_f32_e32 v4, v241, v242
	v_fmac_f32_e32 v5, v241, v243
	v_fmac_f32_e32 v2, v241, v244
	v_fmac_f32_e32 v3, v241, v245
	ds_read_b128 v[238:241], v220 offset:1904
	ds_read_b128 v[242:245], v221 offset:1904
	s_waitcnt lgkmcnt(6)
	v_fmac_f32_e32 v14, v204, v208
	v_fmac_f32_e32 v15, v204, v209
	v_fmac_f32_e32 v16, v204, v210
	v_fmac_f32_e32 v17, v204, v211
	v_fmac_f32_e32 v10, v205, v208
	v_fmac_f32_e32 v11, v205, v209
	v_fmac_f32_e32 v12, v205, v210
	v_fmac_f32_e32 v13, v205, v211
	v_fmac_f32_e32 v6, v206, v208
	v_fmac_f32_e32 v7, v206, v209
	v_fmac_f32_e32 v8, v206, v210
	v_fmac_f32_e32 v9, v206, v211
	v_fmac_f32_e32 v4, v207, v208
	v_fmac_f32_e32 v5, v207, v209
	v_fmac_f32_e32 v2, v207, v210
	v_fmac_f32_e32 v3, v207, v211
	s_addk_i32 s0, 0x880
	v_add_u32_e32 v220, s0, v51
	v_add_u32_e32 v221, s0, v95
	ds_read_b128 v[204:207], v220
	ds_read_b128 v[208:211], v221
	s_waitcnt lgkmcnt(6)
	v_fmac_f32_e32 v14, v212, v216
	v_fmac_f32_e32 v15, v212, v217
	v_fmac_f32_e32 v16, v212, v218
	v_fmac_f32_e32 v17, v212, v219
	v_fmac_f32_e32 v10, v213, v216
	v_fmac_f32_e32 v11, v213, v217
	v_fmac_f32_e32 v12, v213, v218
	v_fmac_f32_e32 v13, v213, v219
	v_fmac_f32_e32 v6, v214, v216
	v_fmac_f32_e32 v7, v214, v217
	v_fmac_f32_e32 v8, v214, v218
	v_fmac_f32_e32 v9, v214, v219
	v_fmac_f32_e32 v4, v215, v216
	v_fmac_f32_e32 v5, v215, v217
	v_fmac_f32_e32 v2, v215, v218
	v_fmac_f32_e32 v3, v215, v219
	ds_read_b128 v[212:215], v220 offset:272
	ds_read_b128 v[216:219], v221 offset:272
	s_waitcnt lgkmcnt(6)
	v_fmac_f32_e32 v14, v224, v234
	v_fmac_f32_e32 v15, v224, v235
	v_fmac_f32_e32 v16, v224, v236
	v_fmac_f32_e32 v17, v224, v237
	v_fmac_f32_e32 v10, v225, v234
	v_fmac_f32_e32 v11, v225, v235
	v_fmac_f32_e32 v12, v225, v236
	v_fmac_f32_e32 v13, v225, v237
	v_fmac_f32_e32 v6, v226, v234
	v_fmac_f32_e32 v7, v226, v235
	v_fmac_f32_e32 v8, v226, v236
	v_fmac_f32_e32 v9, v226, v237
	v_fmac_f32_e32 v4, v227, v234
	v_fmac_f32_e32 v5, v227, v235
	v_fmac_f32_e32 v2, v227, v236
	v_fmac_f32_e32 v3, v227, v237
	ds_read_b128 v[224:227], v220 offset:544
	ds_read_b128 v[234:237], v221 offset:544
	s_waitcnt lgkmcnt(6)
	v_fmac_f32_e32 v14, v238, v242
	v_fmac_f32_e32 v15, v238, v243
	v_fmac_f32_e32 v16, v238, v244
	v_fmac_f32_e32 v17, v238, v245
	v_fmac_f32_e32 v10, v239, v242
	v_fmac_f32_e32 v11, v239, v243
	v_fmac_f32_e32 v12, v239, v244
	v_fmac_f32_e32 v13, v239, v245
	v_fmac_f32_e32 v6, v240, v242
	v_fmac_f32_e32 v7, v240, v243
	v_fmac_f32_e32 v8, v240, v244
	v_fmac_f32_e32 v9, v240, v245
	v_fmac_f32_e32 v4, v241, v242
	v_fmac_f32_e32 v5, v241, v243
	v_fmac_f32_e32 v2, v241, v244
	v_fmac_f32_e32 v3, v241, v245
	s_cmpk_lg_i32 s0, 0x4400
	s_cbranch_scc1 .LBB0_638
	s_waitcnt lgkmcnt(0)
	v_mul_f32_e32 v18, 0x3fb8aa3b, v106
	v_exp_f32_e32 v19, v18
	s_lshl_b32 s88, s21, 12
	s_lshl_b64 s[0:1], s[88:89], 2
	s_add_u32 s4, s3, s0
	s_addc_u32 s5, s8, s1
	v_lshlrev_b32_e32 v18, 8, v104
	v_cmp_eq_u32_e32 vcc, v105, v50
	v_lshl_add_u64 v[20:21], s[4:5], 0, v[0:1]
	v_pk_add_f32 v[16:17], v[16:17], 0 op_sel_hi:[1,0] neg_lo:[1,0] neg_hi:[1,0]
	v_cndmask_b32_e32 v0, 0, v19, vcc
	v_ashrrev_i32_e32 v19, 31, v18
	v_pk_add_f32 v[14:15], v[0:1], v[14:15] neg_lo:[0,1] neg_hi:[0,1]
	v_lshl_add_u64 v[20:21], v[18:19], 2, v[20:21]
	global_store_dwordx4 v[20:21], v[14:17], off
	v_pk_add_f32 v[6:7], v[6:7], 0 op_sel_hi:[1,0] neg_lo:[1,0] neg_hi:[1,0]
	v_pk_add_f32 v[8:9], v[0:1], v[8:9] neg_lo:[0,1] neg_hi:[0,1]
	v_mov_b32_e32 v14, v1
	v_mov_b32_e32 v15, v0
	global_store_dwordx4 v[20:21], v[6:9], off offset:512
	v_pk_add_f32 v[4:5], v[4:5], 0 op_sel_hi:[1,0] neg_lo:[1,0] neg_hi:[1,0]
	v_pk_add_f32 v[10:11], v[14:15], v[10:11] neg_lo:[0,1] neg_hi:[0,1]
	v_pk_add_f32 v[6:7], v[14:15], v[2:3] neg_lo:[0,1] neg_hi:[0,1]
	v_pk_add_f32 v[12:13], v[12:13], 0 op_sel_hi:[1,0] neg_lo:[1,0] neg_hi:[1,0]
	global_store_dwordx4 v[20:21], v[4:7], off offset:768
	s_mov_b32 s4, 0
	global_store_dwordx4 v[20:21], v[10:13], off offset:256
	v_mov_b32_e32 v4, 0
	v_mov_b32_e32 v5, v4
	v_mov_b32_e32 v14, v4
	v_mov_b32_e32 v15, v4
	v_mov_b32_e32 v16, v4
	v_mov_b32_e32 v17, v4
	v_mov_b32_e32 v10, v4
	v_mov_b32_e32 v11, v4
	v_mov_b32_e32 v12, v4
	v_mov_b32_e32 v13, v4
	v_mov_b32_e32 v6, v4
	v_mov_b32_e32 v7, v4
	v_mov_b32_e32 v8, v4
	v_mov_b32_e32 v9, v4
	v_mov_b32_e32 v2, v4
	v_mov_b32_e32 v3, v4
	v_add_u32_e32 v220, s4, v51
	v_add_u32_e32 v221, s4, v70
	ds_read_b128 v[204:207], v220
	ds_read_b128 v[208:211], v221
	ds_read_b128 v[212:215], v220 offset:272
	ds_read_b128 v[216:219], v221 offset:272
	ds_read_b128 v[224:227], v220 offset:544
	ds_read_b128 v[234:237], v221 offset:544
; #define ZERO44(a) { _Pragma("unroll") for (int _i = 0; _i < 4; ++_i) { _Pragma("unroll") for (int _j = 0; _j < 4; ++_j) a[_i][_j] = 0.f; } }
; __device__ __forceinline__ void mm64(const float* At, const float* B, float (&acc)[4][4], int ty, int tx) {
;     f32x2 c2[4][2];
; #pragma unroll
;     for (int rr = 0; rr < 4; ++rr) { c2[rr][0] = (f32x2){acc[rr][0], acc[rr][1]}; c2[rr][1] = (f32x2){acc[rr][2], acc[rr][3]}; }
; #pragma unroll 8
;     for (int k = 0; k < 64; ++k) {
;         const f32x4 a = *(const f32x4*)(At + k * DLD + 4 * ty);
;         const f32x4 b = *(const f32x4*)(B + k * DLD + 4 * tx);
;         const f32x2 b01 = {b.x, b.y}, b23 = {b.z, b.w};
; #pragma unroll
;         for (int rr = 0; rr < 4; ++rr) {
;             const f32x2 a2 = {a[rr], a[rr]};
;             c2[rr][0] = __builtin_elementwise_fma(a2, b01, c2[rr][0]);
;             c2[rr][1] = __builtin_elementwise_fma(a2, b23, c2[rr][1]);
;         }
;     }
; #pragma unroll
;     for (int rr = 0; rr < 4; ++rr) { acc[rr][0] = c2[rr][0].x; acc[rr][1] = c2[rr][0].y; acc[rr][2] = c2[rr][1].x; acc[rr][3] = c2[rr][1].y; }
; }
; __device__ __forceinline__ void dn1_item(const Params& p, int l, int item, unsigned char* lds) {
;     ...
;         mm64(B0, B2, a1, ty, tx);
; #pragma unroll
;         for (int rr = 0; rr < 4; ++rr) { f32x4 w = {a1[rr][0], a1[rr][1], a1[rr][2], a1[rr][3]}; *(f32x4*)(DNB + (4 * ty + rr) * 64 + 4 * tx) = w; }
;     }
;     float hacc[4][4]; ZERO44(hacc);
;     mm64(B1, B3, hacc, ty, tx);
.LBB0_640:
	ds_read_b128 v[238:241], v220 offset:816
	ds_read_b128 v[242:245], v221 offset:816
	s_waitcnt lgkmcnt(6)
	v_fmac_f32_e32 v14, v204, v208
	v_fmac_f32_e32 v15, v204, v209
	v_fmac_f32_e32 v16, v204, v210
	v_fmac_f32_e32 v17, v204, v211
	v_fmac_f32_e32 v10, v205, v208
	v_fmac_f32_e32 v11, v205, v209
	v_fmac_f32_e32 v12, v205, v210
	v_fmac_f32_e32 v13, v205, v211
	v_fmac_f32_e32 v6, v206, v208
	v_fmac_f32_e32 v7, v206, v209
	v_fmac_f32_e32 v8, v206, v210
	v_fmac_f32_e32 v9, v206, v211
	v_fmac_f32_e32 v2, v207, v208
	v_fmac_f32_e32 v3, v207, v209
	v_fmac_f32_e32 v4, v207, v210
	v_fmac_f32_e32 v5, v207, v211
	ds_read_b128 v[204:207], v220 offset:1088
	ds_read_b128 v[208:211], v221 offset:1088
	s_waitcnt lgkmcnt(6)
	v_fmac_f32_e32 v14, v212, v216
	v_fmac_f32_e32 v15, v212, v217
	v_fmac_f32_e32 v16, v212, v218
	v_fmac_f32_e32 v17, v212, v219
	v_fmac_f32_e32 v10, v213, v216
	v_fmac_f32_e32 v11, v213, v217
	v_fmac_f32_e32 v12, v213, v218
	v_fmac_f32_e32 v13, v213, v219
	v_fmac_f32_e32 v6, v214, v216
	v_fmac_f32_e32 v7, v214, v217
	v_fmac_f32_e32 v8, v214, v218
	v_fmac_f32_e32 v9, v214, v219
	v_fmac_f32_e32 v2, v215, v216
	v_fmac_f32_e32 v3, v215, v217
	v_fmac_f32_e32 v4, v215, v218
	v_fmac_f32_e32 v5, v215, v219
	ds_read_b128 v[212:215], v220 offset:1360
	ds_read_b128 v[216:219], v221 offset:1360
	s_waitcnt lgkmcnt(6)
	v_fmac_f32_e32 v14, v224, v234
	v_fmac_f32_e32 v15, v224, v235
	v_fmac_f32_e32 v16, v224, v236
	v_fmac_f32_e32 v17, v224, v237
	v_fmac_f32_e32 v10, v225, v234
	v_fmac_f32_e32 v11, v225, v235
	v_fmac_f32_e32 v12, v225, v236
	v_fmac_f32_e32 v13, v225, v237
	v_fmac_f32_e32 v6, v226, v234
	v_fmac_f32_e32 v7, v226, v235
	v_fmac_f32_e32 v8, v226, v236
	v_fmac_f32_e32 v9, v226, v237
	v_fmac_f32_e32 v2, v227, v234
	v_fmac_f32_e32 v3, v227, v235
	v_fmac_f32_e32 v4, v227, v236
	v_fmac_f32_e32 v5, v227, v237
	ds_read_b128 v[224:227], v220 offset:1632
	ds_read_b128 v[234:237], v221 offset:1632
	s_waitcnt lgkmcnt(6)
	v_fmac_f32_e32 v14, v238, v242
	v_fmac_f32_e32 v15, v238, v243
	v_fmac_f32_e32 v16, v238, v244
	v_fmac_f32_e32 v17, v238, v245
	v_fmac_f32_e32 v10, v239, v242
	v_fmac_f32_e32 v11, v239, v243
	v_fmac_f32_e32 v12, v239, v244
	v_fmac_f32_e32 v13, v239, v245
	v_fmac_f32_e32 v6, v240, v242
	v_fmac_f32_e32 v7, v240, v243
	v_fmac_f32_e32 v8, v240, v244
	v_fmac_f32_e32 v9, v240, v245
	v_fmac_f32_e32 v2, v241, v242
	v_fmac_f32_e32 v3, v241, v243
	v_fmac_f32_e32 v4, v241, v244
	v_fmac_f32_e32 v5, v241, v245
	ds_read_b128 v[238:241], v220 offset:1904
	ds_read_b128 v[242:245], v221 offset:1904
	s_waitcnt lgkmcnt(6)
	v_fmac_f32_e32 v14, v204, v208
	v_fmac_f32_e32 v15, v204, v209
	v_fmac_f32_e32 v16, v204, v210
	v_fmac_f32_e32 v17, v204, v211
	v_fmac_f32_e32 v10, v205, v208
	v_fmac_f32_e32 v11, v205, v209
	v_fmac_f32_e32 v12, v205, v210
	v_fmac_f32_e32 v13, v205, v211
	v_fmac_f32_e32 v6, v206, v208
	v_fmac_f32_e32 v7, v206, v209
	v_fmac_f32_e32 v8, v206, v210
	v_fmac_f32_e32 v9, v206, v211
	v_fmac_f32_e32 v2, v207, v208
	v_fmac_f32_e32 v3, v207, v209
	v_fmac_f32_e32 v4, v207, v210
	v_fmac_f32_e32 v5, v207, v211
	s_addk_i32 s4, 0x880
	v_add_u32_e32 v220, s4, v51
	v_add_u32_e32 v221, s4, v70
	ds_read_b128 v[204:207], v220
	ds_read_b128 v[208:211], v221
	s_waitcnt lgkmcnt(6)
	v_fmac_f32_e32 v14, v212, v216
	v_fmac_f32_e32 v15, v212, v217
	v_fmac_f32_e32 v16, v212, v218
	v_fmac_f32_e32 v17, v212, v219
	v_fmac_f32_e32 v10, v213, v216
	v_fmac_f32_e32 v11, v213, v217
	v_fmac_f32_e32 v12, v213, v218
	v_fmac_f32_e32 v13, v213, v219
	v_fmac_f32_e32 v6, v214, v216
	v_fmac_f32_e32 v7, v214, v217
	v_fmac_f32_e32 v8, v214, v218
	v_fmac_f32_e32 v9, v214, v219
	v_fmac_f32_e32 v2, v215, v216
	v_fmac_f32_e32 v3, v215, v217
	v_fmac_f32_e32 v4, v215, v218
	v_fmac_f32_e32 v5, v215, v219
	ds_read_b128 v[212:215], v220 offset:272
	ds_read_b128 v[216:219], v221 offset:272
	s_waitcnt lgkmcnt(6)
	v_fmac_f32_e32 v14, v224, v234
	v_fmac_f32_e32 v15, v224, v235
	v_fmac_f32_e32 v16, v224, v236
	v_fmac_f32_e32 v17, v224, v237
	v_fmac_f32_e32 v10, v225, v234
	v_fmac_f32_e32 v11, v225, v235
	v_fmac_f32_e32 v12, v225, v236
	v_fmac_f32_e32 v13, v225, v237
	v_fmac_f32_e32 v6, v226, v234
	v_fmac_f32_e32 v7, v226, v235
	v_fmac_f32_e32 v8, v226, v236
	v_fmac_f32_e32 v9, v226, v237
	v_fmac_f32_e32 v2, v227, v234
	v_fmac_f32_e32 v3, v227, v235
	v_fmac_f32_e32 v4, v227, v236
	v_fmac_f32_e32 v5, v227, v237
	ds_read_b128 v[224:227], v220 offset:544
	ds_read_b128 v[234:237], v221 offset:544
	s_waitcnt lgkmcnt(6)
	v_fmac_f32_e32 v14, v238, v242
	v_fmac_f32_e32 v15, v238, v243
	v_fmac_f32_e32 v16, v238, v244
	v_fmac_f32_e32 v17, v238, v245
	v_fmac_f32_e32 v10, v239, v242
	v_fmac_f32_e32 v11, v239, v243
	v_fmac_f32_e32 v12, v239, v244
	v_fmac_f32_e32 v13, v239, v245
	v_fmac_f32_e32 v6, v240, v242
	v_fmac_f32_e32 v7, v240, v243
	v_fmac_f32_e32 v8, v240, v244
	v_fmac_f32_e32 v9, v240, v245
	v_fmac_f32_e32 v2, v241, v242
	v_fmac_f32_e32 v3, v241, v243
	v_fmac_f32_e32 v4, v241, v244
	v_fmac_f32_e32 v5, v241, v245
	s_cmpk_lg_i32 s4, 0x4400
	s_cbranch_scc1 .LBB0_640
	s_waitcnt lgkmcnt(0)
	s_add_u32 s4, s9, s0
	s_addc_u32 s5, s10, s1
	v_lshlrev_b32_e32 v0, 2, v50
	v_lshl_add_u64 v[20:21], s[4:5], 0, v[0:1]
	v_lshl_add_u64 v[20:21], v[18:19], 2, v[20:21]
	global_store_dwordx4 v[20:21], v[14:17], off
	global_store_dwordx4 v[20:21], v[10:13], off offset:256
	global_store_dwordx4 v[20:21], v[6:9], off offset:512
	global_store_dwordx4 v[20:21], v[2:5], off offset:768
	v_readlane_b32 s4, v253, 52
	v_mov_b32_e32 v20, 0
	v_mov_b32_e32 v21, v20
	v_add_u32_e32 v2, s4, v94
	s_mov_b32 s4, 0
	v_mov_b32_e32 v32, v20
	v_mov_b32_e32 v33, v20
	v_mov_b32_e32 v50, v20
	v_mov_b32_e32 v51, v20
	v_mov_b32_e32 v28, v20
	v_mov_b32_e32 v29, v20
	v_mov_b32_e32 v30, v20
	v_mov_b32_e32 v31, v20
	v_mov_b32_e32 v24, v20
	v_mov_b32_e32 v25, v20
	v_mov_b32_e32 v26, v20
	v_mov_b32_e32 v27, v20
	v_mov_b32_e32 v22, v20
	v_mov_b32_e32 v23, v20
	v_add_u32_e32 v220, s4, v93
	v_add_u32_e32 v221, s4, v2
	ds_read_b128 v[204:207], v220
	ds_read_b128 v[208:211], v221
	ds_read_b128 v[212:215], v220 offset:272
	ds_read_b128 v[216:219], v221 offset:272
	ds_read_b128 v[224:227], v220 offset:544
	ds_read_b128 v[234:237], v221 offset:544
; #define ZERO44(a) { _Pragma("unroll") for (int _i = 0; _i < 4; ++_i) { _Pragma("unroll") for (int _j = 0; _j < 4; ++_j) a[_i][_j] = 0.f; } }
; __device__ __forceinline__ void mm64(const float* At, const float* B, float (&acc)[4][4], int ty, int tx) {
;     f32x2 c2[4][2];
; #pragma unroll
;     for (int rr = 0; rr < 4; ++rr) { c2[rr][0] = (f32x2){acc[rr][0], acc[rr][1]}; c2[rr][1] = (f32x2){acc[rr][2], acc[rr][3]}; }
; #pragma unroll 8
;     for (int k = 0; k < 64; ++k) {
;         const f32x4 a = *(const f32x4*)(At + k * DLD + 4 * ty);
;         const f32x4 b = *(const f32x4*)(B + k * DLD + 4 * tx);
;         const f32x2 b01 = {b.x, b.y}, b23 = {b.z, b.w};
; #pragma unroll
;         for (int rr = 0; rr < 4; ++rr) {
;             const f32x2 a2 = {a[rr], a[rr]};
;             c2[rr][0] = __builtin_elementwise_fma(a2, b01, c2[rr][0]);
;             c2[rr][1] = __builtin_elementwise_fma(a2, b23, c2[rr][1]);
;         }
;     }
; #pragma unroll
;     for (int rr = 0; rr < 4; ++rr) { acc[rr][0] = c2[rr][0].x; acc[rr][1] = c2[rr][0].y; acc[rr][2] = c2[rr][1].x; acc[rr][3] = c2[rr][1].y; }
; }
; __device__ __forceinline__ void dn1_item(const Params& p, int l, int item, unsigned char* lds) {
;     ...
;     float hacc[4][4]; ZERO44(hacc);
;     mm64(B1, B3, hacc, ty, tx);
;     {
;         float a1[4][4]; ZERO44(a1);
;         mm64(B3, B2, a1, ty, tx);
.LBB0_642:
	ds_read_b128 v[238:241], v220 offset:816
	ds_read_b128 v[242:245], v221 offset:816
	s_waitcnt lgkmcnt(6)
	v_fmac_f32_e32 v32, v204, v208
	v_fmac_f32_e32 v33, v204, v209
	v_fmac_f32_e32 v50, v204, v210
	v_fmac_f32_e32 v51, v204, v211
	v_fmac_f32_e32 v28, v205, v208
	v_fmac_f32_e32 v29, v205, v209
	v_fmac_f32_e32 v30, v205, v210
	v_fmac_f32_e32 v31, v205, v211
	v_fmac_f32_e32 v24, v206, v208
	v_fmac_f32_e32 v25, v206, v209
	v_fmac_f32_e32 v26, v206, v210
	v_fmac_f32_e32 v27, v206, v211
	v_fmac_f32_e32 v22, v207, v208
	v_fmac_f32_e32 v23, v207, v209
	v_fmac_f32_e32 v20, v207, v210
	v_fmac_f32_e32 v21, v207, v211
	ds_read_b128 v[204:207], v220 offset:1088
	ds_read_b128 v[208:211], v221 offset:1088
	s_waitcnt lgkmcnt(6)
	v_fmac_f32_e32 v32, v212, v216
	v_fmac_f32_e32 v33, v212, v217
	v_fmac_f32_e32 v50, v212, v218
	v_fmac_f32_e32 v51, v212, v219
	v_fmac_f32_e32 v28, v213, v216
	v_fmac_f32_e32 v29, v213, v217
	v_fmac_f32_e32 v30, v213, v218
	v_fmac_f32_e32 v31, v213, v219
	v_fmac_f32_e32 v24, v214, v216
	v_fmac_f32_e32 v25, v214, v217
	v_fmac_f32_e32 v26, v214, v218
	v_fmac_f32_e32 v27, v214, v219
	v_fmac_f32_e32 v22, v215, v216
	v_fmac_f32_e32 v23, v215, v217
	v_fmac_f32_e32 v20, v215, v218
	v_fmac_f32_e32 v21, v215, v219
	ds_read_b128 v[212:215], v220 offset:1360
	ds_read_b128 v[216:219], v221 offset:1360
	s_waitcnt lgkmcnt(6)
	v_fmac_f32_e32 v32, v224, v234
	v_fmac_f32_e32 v33, v224, v235
	v_fmac_f32_e32 v50, v224, v236
	v_fmac_f32_e32 v51, v224, v237
	v_fmac_f32_e32 v28, v225, v234
	v_fmac_f32_e32 v29, v225, v235
	v_fmac_f32_e32 v30, v225, v236
	v_fmac_f32_e32 v31, v225, v237
	v_fmac_f32_e32 v24, v226, v234
	v_fmac_f32_e32 v25, v226, v235
	v_fmac_f32_e32 v26, v226, v236
	v_fmac_f32_e32 v27, v226, v237
	v_fmac_f32_e32 v22, v227, v234
	v_fmac_f32_e32 v23, v227, v235
	v_fmac_f32_e32 v20, v227, v236
	v_fmac_f32_e32 v21, v227, v237
	ds_read_b128 v[224:227], v220 offset:1632
	ds_read_b128 v[234:237], v221 offset:1632
	s_waitcnt lgkmcnt(6)
	v_fmac_f32_e32 v32, v238, v242
	v_fmac_f32_e32 v33, v238, v243
	v_fmac_f32_e32 v50, v238, v244
	v_fmac_f32_e32 v51, v238, v245
	v_fmac_f32_e32 v28, v239, v242
	v_fmac_f32_e32 v29, v239, v243
	v_fmac_f32_e32 v30, v239, v244
	v_fmac_f32_e32 v31, v239, v245
	v_fmac_f32_e32 v24, v240, v242
	v_fmac_f32_e32 v25, v240, v243
	v_fmac_f32_e32 v26, v240, v244
	v_fmac_f32_e32 v27, v240, v245
	v_fmac_f32_e32 v22, v241, v242
	v_fmac_f32_e32 v23, v241, v243
	v_fmac_f32_e32 v20, v241, v244
	v_fmac_f32_e32 v21, v241, v245
	ds_read_b128 v[238:241], v220 offset:1904
	ds_read_b128 v[242:245], v221 offset:1904
	s_waitcnt lgkmcnt(6)
	v_fmac_f32_e32 v32, v204, v208
	v_fmac_f32_e32 v33, v204, v209
	v_fmac_f32_e32 v50, v204, v210
	v_fmac_f32_e32 v51, v204, v211
	v_fmac_f32_e32 v28, v205, v208
	v_fmac_f32_e32 v29, v205, v209
	v_fmac_f32_e32 v30, v205, v210
	v_fmac_f32_e32 v31, v205, v211
	v_fmac_f32_e32 v24, v206, v208
	v_fmac_f32_e32 v25, v206, v209
	v_fmac_f32_e32 v26, v206, v210
	v_fmac_f32_e32 v27, v206, v211
	v_fmac_f32_e32 v22, v207, v208
	v_fmac_f32_e32 v23, v207, v209
	v_fmac_f32_e32 v20, v207, v210
	v_fmac_f32_e32 v21, v207, v211
	s_addk_i32 s4, 0x880
	v_add_u32_e32 v220, s4, v93
	v_add_u32_e32 v221, s4, v2
	ds_read_b128 v[204:207], v220
	ds_read_b128 v[208:211], v221
	s_waitcnt lgkmcnt(6)
	v_fmac_f32_e32 v32, v212, v216
	v_fmac_f32_e32 v33, v212, v217
	v_fmac_f32_e32 v50, v212, v218
	v_fmac_f32_e32 v51, v212, v219
	v_fmac_f32_e32 v28, v213, v216
	v_fmac_f32_e32 v29, v213, v217
	v_fmac_f32_e32 v30, v213, v218
	v_fmac_f32_e32 v31, v213, v219
	v_fmac_f32_e32 v24, v214, v216
	v_fmac_f32_e32 v25, v214, v217
	v_fmac_f32_e32 v26, v214, v218
	v_fmac_f32_e32 v27, v214, v219
	v_fmac_f32_e32 v22, v215, v216
	v_fmac_f32_e32 v23, v215, v217
	v_fmac_f32_e32 v20, v215, v218
	v_fmac_f32_e32 v21, v215, v219
	ds_read_b128 v[212:215], v220 offset:272
	ds_read_b128 v[216:219], v221 offset:272
	s_waitcnt lgkmcnt(6)
	v_fmac_f32_e32 v32, v224, v234
	v_fmac_f32_e32 v33, v224, v235
	v_fmac_f32_e32 v50, v224, v236
	v_fmac_f32_e32 v51, v224, v237
	v_fmac_f32_e32 v28, v225, v234
	v_fmac_f32_e32 v29, v225, v235
	v_fmac_f32_e32 v30, v225, v236
	v_fmac_f32_e32 v31, v225, v237
	v_fmac_f32_e32 v24, v226, v234
	v_fmac_f32_e32 v25, v226, v235
	v_fmac_f32_e32 v26, v226, v236
	v_fmac_f32_e32 v27, v226, v237
	v_fmac_f32_e32 v22, v227, v234
	v_fmac_f32_e32 v23, v227, v235
	v_fmac_f32_e32 v20, v227, v236
	v_fmac_f32_e32 v21, v227, v237
	ds_read_b128 v[224:227], v220 offset:544
	ds_read_b128 v[234:237], v221 offset:544
	s_waitcnt lgkmcnt(6)
	v_fmac_f32_e32 v32, v238, v242
	v_fmac_f32_e32 v33, v238, v243
	v_fmac_f32_e32 v50, v238, v244
	v_fmac_f32_e32 v51, v238, v245
	v_fmac_f32_e32 v28, v239, v242
	v_fmac_f32_e32 v29, v239, v243
	v_fmac_f32_e32 v30, v239, v244
	v_fmac_f32_e32 v31, v239, v245
	v_fmac_f32_e32 v24, v240, v242
	v_fmac_f32_e32 v25, v240, v243
	v_fmac_f32_e32 v26, v240, v244
	v_fmac_f32_e32 v27, v240, v245
	v_fmac_f32_e32 v22, v241, v242
	v_fmac_f32_e32 v23, v241, v243
	v_fmac_f32_e32 v20, v241, v244
	v_fmac_f32_e32 v21, v241, v245
	s_cmpk_lg_i32 s4, 0x4400
	s_cbranch_scc1 .LBB0_642
	s_waitcnt lgkmcnt(0)
	v_readlane_b32 s4, v253, 52
	v_mov_b32_e32 v4, 0
	v_mov_b32_e32 v5, v4
	v_add_u32_e32 v54, s4, v77
	s_mov_b32 s4, 0
	v_mov_b32_e32 v14, v4
	v_mov_b32_e32 v15, v4
	v_mov_b32_e32 v16, v4
	v_mov_b32_e32 v17, v4
	v_mov_b32_e32 v10, v4
	v_mov_b32_e32 v11, v4
	v_mov_b32_e32 v12, v4
	v_mov_b32_e32 v13, v4
	v_mov_b32_e32 v6, v4
	v_mov_b32_e32 v7, v4
	v_mov_b32_e32 v8, v4
	v_mov_b32_e32 v9, v4
	v_mov_b32_e32 v2, v4
	v_mov_b32_e32 v3, v4
	v_add_u32_e32 v220, s4, v54
	v_add_u32_e32 v221, s4, v70
	ds_read_b128 v[204:207], v220
	ds_read_b128 v[208:211], v221
	ds_read_b128 v[212:215], v220 offset:272
	ds_read_b128 v[216:219], v221 offset:272
	ds_read_b128 v[224:227], v220 offset:544
	ds_read_b128 v[234:237], v221 offset:544
; #define ZERO44(a) { _Pragma("unroll") for (int _i = 0; _i < 4; ++_i) { _Pragma("unroll") for (int _j = 0; _j < 4; ++_j) a[_i][_j] = 0.f; } }
; __device__ __forceinline__ void mm64(const float* At, const float* B, float (&acc)[4][4], int ty, int tx) {
;     f32x2 c2[4][2];
; #pragma unroll
;     for (int rr = 0; rr < 4; ++rr) { c2[rr][0] = (f32x2){acc[rr][0], acc[rr][1]}; c2[rr][1] = (f32x2){acc[rr][2], acc[rr][3]}; }
; #pragma unroll 8
;     for (int k = 0; k < 64; ++k) {
;         const f32x4 a = *(const f32x4*)(At + k * DLD + 4 * ty);
;         const f32x4 b = *(const f32x4*)(B + k * DLD + 4 * tx);
;         const f32x2 b01 = {b.x, b.y}, b23 = {b.z, b.w};
; #pragma unroll
;         for (int rr = 0; rr < 4; ++rr) {
;             const f32x2 a2 = {a[rr], a[rr]};
;             c2[rr][0] = __builtin_elementwise_fma(a2, b01, c2[rr][0]);
;             c2[rr][1] = __builtin_elementwise_fma(a2, b23, c2[rr][1]);
;         }
;     }
; #pragma unroll
;     for (int rr = 0; rr < 4; ++rr) { acc[rr][0] = c2[rr][0].x; acc[rr][1] = c2[rr][0].y; acc[rr][2] = c2[rr][1].x; acc[rr][3] = c2[rr][1].y; }
; }
; __device__ __forceinline__ void dn1_item(const Params& p, int l, int item, unsigned char* lds) {
;     ...
;         float a1[4][4]; ZERO44(a1);
;         mm64(B3, B2, a1, ty, tx);
; #pragma unroll
;         for (int rr = 0; rr < 4; ++rr) { f32x4 w = {a1[rr][0], a1[rr][1], a1[rr][2], a1[rr][3]}; *(f32x4*)(DNO + (4 * ty + rr) * 64 + 4 * tx) = w; }
.LBB0_644:
	ds_read_b128 v[238:241], v220 offset:816
	ds_read_b128 v[242:245], v221 offset:816
	s_waitcnt lgkmcnt(6)
	v_fmac_f32_e32 v14, v204, v208
	v_fmac_f32_e32 v15, v204, v209
	v_fmac_f32_e32 v16, v204, v210
	v_fmac_f32_e32 v17, v204, v211
	v_fmac_f32_e32 v10, v205, v208
	v_fmac_f32_e32 v11, v205, v209
	v_fmac_f32_e32 v12, v205, v210
	v_fmac_f32_e32 v13, v205, v211
	v_fmac_f32_e32 v6, v206, v208
	v_fmac_f32_e32 v7, v206, v209
	v_fmac_f32_e32 v8, v206, v210
	v_fmac_f32_e32 v9, v206, v211
	v_fmac_f32_e32 v2, v207, v208
	v_fmac_f32_e32 v3, v207, v209
	v_fmac_f32_e32 v4, v207, v210
	v_fmac_f32_e32 v5, v207, v211
	ds_read_b128 v[204:207], v220 offset:1088
	ds_read_b128 v[208:211], v221 offset:1088
	s_waitcnt lgkmcnt(6)
	v_fmac_f32_e32 v14, v212, v216
	v_fmac_f32_e32 v15, v212, v217
	v_fmac_f32_e32 v16, v212, v218
	v_fmac_f32_e32 v17, v212, v219
	v_fmac_f32_e32 v10, v213, v216
	v_fmac_f32_e32 v11, v213, v217
	v_fmac_f32_e32 v12, v213, v218
	v_fmac_f32_e32 v13, v213, v219
	v_fmac_f32_e32 v6, v214, v216
	v_fmac_f32_e32 v7, v214, v217
	v_fmac_f32_e32 v8, v214, v218
	v_fmac_f32_e32 v9, v214, v219
	v_fmac_f32_e32 v2, v215, v216
	v_fmac_f32_e32 v3, v215, v217
	v_fmac_f32_e32 v4, v215, v218
	v_fmac_f32_e32 v5, v215, v219
	ds_read_b128 v[212:215], v220 offset:1360
	ds_read_b128 v[216:219], v221 offset:1360
	s_waitcnt lgkmcnt(6)
	v_fmac_f32_e32 v14, v224, v234
	v_fmac_f32_e32 v15, v224, v235
	v_fmac_f32_e32 v16, v224, v236
	v_fmac_f32_e32 v17, v224, v237
	v_fmac_f32_e32 v10, v225, v234
	v_fmac_f32_e32 v11, v225, v235
	v_fmac_f32_e32 v12, v225, v236
	v_fmac_f32_e32 v13, v225, v237
	v_fmac_f32_e32 v6, v226, v234
	v_fmac_f32_e32 v7, v226, v235
	v_fmac_f32_e32 v8, v226, v236
	v_fmac_f32_e32 v9, v226, v237
	v_fmac_f32_e32 v2, v227, v234
	v_fmac_f32_e32 v3, v227, v235
	v_fmac_f32_e32 v4, v227, v236
	v_fmac_f32_e32 v5, v227, v237
	ds_read_b128 v[224:227], v220 offset:1632
	ds_read_b128 v[234:237], v221 offset:1632
	s_waitcnt lgkmcnt(6)
	v_fmac_f32_e32 v14, v238, v242
	v_fmac_f32_e32 v15, v238, v243
	v_fmac_f32_e32 v16, v238, v244
	v_fmac_f32_e32 v17, v238, v245
	v_fmac_f32_e32 v10, v239, v242
	v_fmac_f32_e32 v11, v239, v243
	v_fmac_f32_e32 v12, v239, v244
	v_fmac_f32_e32 v13, v239, v245
	v_fmac_f32_e32 v6, v240, v242
	v_fmac_f32_e32 v7, v240, v243
	v_fmac_f32_e32 v8, v240, v244
	v_fmac_f32_e32 v9, v240, v245
	v_fmac_f32_e32 v2, v241, v242
	v_fmac_f32_e32 v3, v241, v243
	v_fmac_f32_e32 v4, v241, v244
	v_fmac_f32_e32 v5, v241, v245
	ds_read_b128 v[238:241], v220 offset:1904
	ds_read_b128 v[242:245], v221 offset:1904
	s_waitcnt lgkmcnt(6)
	v_fmac_f32_e32 v14, v204, v208
	v_fmac_f32_e32 v15, v204, v209
	v_fmac_f32_e32 v16, v204, v210
	v_fmac_f32_e32 v17, v204, v211
	v_fmac_f32_e32 v10, v205, v208
	v_fmac_f32_e32 v11, v205, v209
	v_fmac_f32_e32 v12, v205, v210
	v_fmac_f32_e32 v13, v205, v211
	v_fmac_f32_e32 v6, v206, v208
	v_fmac_f32_e32 v7, v206, v209
	v_fmac_f32_e32 v8, v206, v210
	v_fmac_f32_e32 v9, v206, v211
	v_fmac_f32_e32 v2, v207, v208
	v_fmac_f32_e32 v3, v207, v209
	v_fmac_f32_e32 v4, v207, v210
	v_fmac_f32_e32 v5, v207, v211
	s_addk_i32 s4, 0x880
	v_add_u32_e32 v220, s4, v54
	v_add_u32_e32 v221, s4, v70
	ds_read_b128 v[204:207], v220
	ds_read_b128 v[208:211], v221
	s_waitcnt lgkmcnt(6)
	v_fmac_f32_e32 v14, v212, v216
	v_fmac_f32_e32 v15, v212, v217
	v_fmac_f32_e32 v16, v212, v218
	v_fmac_f32_e32 v17, v212, v219
	v_fmac_f32_e32 v10, v213, v216
	v_fmac_f32_e32 v11, v213, v217
	v_fmac_f32_e32 v12, v213, v218
	v_fmac_f32_e32 v13, v213, v219
	v_fmac_f32_e32 v6, v214, v216
	v_fmac_f32_e32 v7, v214, v217
	v_fmac_f32_e32 v8, v214, v218
	v_fmac_f32_e32 v9, v214, v219
	v_fmac_f32_e32 v2, v215, v216
	v_fmac_f32_e32 v3, v215, v217
	v_fmac_f32_e32 v4, v215, v218
	v_fmac_f32_e32 v5, v215, v219
	ds_read_b128 v[212:215], v220 offset:272
	ds_read_b128 v[216:219], v221 offset:272
	s_waitcnt lgkmcnt(6)
	v_fmac_f32_e32 v14, v224, v234
	v_fmac_f32_e32 v15, v224, v235
	v_fmac_f32_e32 v16, v224, v236
	v_fmac_f32_e32 v17, v224, v237
	v_fmac_f32_e32 v10, v225, v234
	v_fmac_f32_e32 v11, v225, v235
	v_fmac_f32_e32 v12, v225, v236
	v_fmac_f32_e32 v13, v225, v237
	v_fmac_f32_e32 v6, v226, v234
	v_fmac_f32_e32 v7, v226, v235
	v_fmac_f32_e32 v8, v226, v236
	v_fmac_f32_e32 v9, v226, v237
	v_fmac_f32_e32 v2, v227, v234
	v_fmac_f32_e32 v3, v227, v235
	v_fmac_f32_e32 v4, v227, v236
	v_fmac_f32_e32 v5, v227, v237
	ds_read_b128 v[224:227], v220 offset:544
	ds_read_b128 v[234:237], v221 offset:544
	s_waitcnt lgkmcnt(6)
	v_fmac_f32_e32 v14, v238, v242
	v_fmac_f32_e32 v15, v238, v243
	v_fmac_f32_e32 v16, v238, v244
	v_fmac_f32_e32 v17, v238, v245
	v_fmac_f32_e32 v10, v239, v242
	v_fmac_f32_e32 v11, v239, v243
	v_fmac_f32_e32 v12, v239, v244
	v_fmac_f32_e32 v13, v239, v245
	v_fmac_f32_e32 v6, v240, v242
	v_fmac_f32_e32 v7, v240, v243
	v_fmac_f32_e32 v8, v240, v244
	v_fmac_f32_e32 v9, v240, v245
	v_fmac_f32_e32 v2, v241, v242
	v_fmac_f32_e32 v3, v241, v243
	v_fmac_f32_e32 v4, v241, v244
	v_fmac_f32_e32 v5, v241, v245
	s_cmpk_lg_i32 s4, 0x4400
	s_cbranch_scc1 .LBB0_644
; __device__ __forceinline__ void dn1_item(const Params& p, int l, int item, unsigned char* lds) {
;     ...
;         mm64(B3, B2, a1, ty, tx);
; #pragma unroll
;         for (int rr = 0; rr < 4; ++rr) { f32x4 w = {a1[rr][0], a1[rr][1], a1[rr][2], a1[rr][3]}; *(f32x4*)(DNO + (4 * ty + rr) * 64 + 4 * tx) = w; }
;     }
;     __syncthreads();
;     {
;         const float s = __expf(gci);
; #pragma unroll
;         for (int e = 0; e < 16; e += 4) { f32x4 w = {qn[e] * s, qn[e + 1] * s, qn[e + 2] * s, qn[e + 3] * s}; *(f32x4*)(B0 + i * DLD + d0 + e) = w; }
;     }
;     __syncthreads();
; #pragma unroll
;     for (int rr = 0; rr < 4; ++rr) {
;         f32x4 w;
; #pragma unroll
;         for (int cc = 0; cc < 4; ++cc) w[cc] = B0[(4 * tx + cc) * DLD + 4 * ty + rr] - hacc[rr][cc];
;         *(f32x4*)(DNQ + (4 * ty + rr) * 64 + 4 * tx) = w;
;     }
;     __syncthreads();
	s_waitcnt lgkmcnt(0)
	s_add_u32 s4, s12, s0
	s_addc_u32 s5, s13, s1
	v_lshl_add_u64 v[54:55], s[4:5], 0, v[0:1]
	v_lshlrev_b64 v[18:19], 2, v[18:19]
	v_lshl_add_u64 v[54:55], v[54:55], 0, v[18:19]
	global_store_dwordx4 v[54:55], v[14:17], off
	global_store_dwordx4 v[54:55], v[10:13], off offset:256
	global_store_dwordx4 v[54:55], v[6:9], off offset:512
	global_store_dwordx4 v[54:55], v[2:5], off offset:768
	s_barrier
	s_nop 0
	v_pk_mul_f32 v[4:5], v[48:49], v[52:53] op_sel_hi:[1,0]
	v_pk_mul_f32 v[2:3], v[44:45], v[52:53] op_sel_hi:[1,0]
	ds_write_b128 v53, v[2:5]
	v_pk_mul_f32 v[4:5], v[46:47], v[52:53] op_sel_hi:[1,0]
	v_pk_mul_f32 v[2:3], v[40:41], v[52:53] op_sel_hi:[1,0]
	ds_write_b128 v53, v[2:5] offset:16
	v_pk_mul_f32 v[4:5], v[42:43], v[52:53] op_sel_hi:[1,0]
	v_pk_mul_f32 v[2:3], v[36:37], v[52:53] op_sel_hi:[1,0]
	ds_write_b128 v53, v[2:5] offset:32
	v_pk_mul_f32 v[4:5], v[38:39], v[52:53] op_sel_hi:[1,0]
	v_pk_mul_f32 v[2:3], v[34:35], v[52:53] op_sel_hi:[1,0]
	ds_write_b128 v53, v[2:5] offset:48
	s_waitcnt lgkmcnt(0)
	s_barrier
	ds_read_b128 v[2:5], v102
	ds_read_b128 v[6:9], v102 offset:272
	ds_read_b128 v[10:13], v102 offset:544
	ds_read_b128 v[14:17], v102 offset:816
	s_add_u32 s0, s14, s0
	s_addc_u32 s1, s15, s1
	s_waitcnt lgkmcnt(2)
	v_mov_b32_e32 v35, v6
	v_mov_b32_e32 v6, v3
	v_lshl_add_u64 v[36:37], s[0:1], 0, v[0:1]
	v_mov_b32_e32 v34, v2
	s_waitcnt lgkmcnt(1)
	v_mov_b32_e32 v38, v10
	s_waitcnt lgkmcnt(0)
	v_mov_b32_e32 v39, v14
	v_mov_b32_e32 v14, v11
	v_pk_add_f32 v[28:29], v[6:7], v[28:29] neg_lo:[0,1] neg_hi:[0,1]
	v_mov_b32_e32 v2, v4
	v_mov_b32_e32 v3, v8
	v_mov_b32_e32 v6, v12
	v_mov_b32_e32 v7, v16
	v_mov_b32_e32 v8, v5
	v_mov_b32_e32 v16, v13
	v_pk_add_f32 v[32:33], v[34:35], v[32:33] neg_lo:[0,1] neg_hi:[0,1]
	v_pk_add_f32 v[34:35], v[38:39], v[50:51] neg_lo:[0,1] neg_hi:[0,1]
	v_lshl_add_u64 v[18:19], v[36:37], 0, v[18:19]
	v_pk_add_f32 v[30:31], v[14:15], v[30:31] neg_lo:[0,1] neg_hi:[0,1]
	v_pk_add_f32 v[24:25], v[2:3], v[24:25] neg_lo:[0,1] neg_hi:[0,1]
	v_pk_add_f32 v[26:27], v[6:7], v[26:27] neg_lo:[0,1] neg_hi:[0,1]
	v_pk_add_f32 v[2:3], v[8:9], v[22:23] neg_lo:[0,1] neg_hi:[0,1]
	v_pk_add_f32 v[4:5], v[16:17], v[20:21] neg_lo:[0,1] neg_hi:[0,1]
	global_store_dwordx4 v[18:19], v[32:35], off
	global_store_dwordx4 v[18:19], v[28:31], off offset:256
	global_store_dwordx4 v[18:19], v[24:27], off offset:512
	global_store_dwordx4 v[18:19], v[2:5], off offset:768
	s_barrier
	s_mov_b64 s[0:1], 0

; __device__ __forceinline__ void mla_rows_item(const Params& p, int b, int item, unsigned* nrm) {
;     ...
;     for (int e = 0; e < 16; ++e) {
;         const int m = item * 64 + wave * 16 + e;
;         u32x2 cq = *(const u32x2*)(PB + (size_t)m * PBW + PB_CQ + lane * 4);
;         uint32_t ck = *(const uint32_t*)(PB + (size_t)m * PBW + PB_CKV + lane * 2);
;         float s1 = bflo(cq.x) * bflo(cq.x) + bfhi(cq.x) * bfhi(cq.x) + bflo(cq.y) * bflo(cq.y) + bfhi(cq.y) * bfhi(cq.y);
;         float s2 = bflo(ck) * bflo(ck) + bfhi(ck) * bfhi(ck);
;         s1 = wave_sum(s1); s2 = wave_sum(s2);
;         if (lane == 0) { RQ[m] = rsqrtf(s1 * (1.f / 256.f) + EPS); RKV[m] = rsqrtf(s2 * (1.f / 128.f) + EPS); }
;         {
;             const u32x4 fq = *(const u32x4*)(PB + (size_t)m * PBW + lane * 8);
;             const u32x4 fk = *(const u32x4*)(PB + (size_t)m * PBW + 512 + lane * 8);
;             float a = bflo(fq.x) * bflo(fq.x) + bfhi(fq.x) * bfhi(fq.x) + bflo(fq.y) * bflo(fq.y) + bfhi(fq.y) * bfhi(fq.y)
;                     + bflo(fq.z) * bflo(fq.z) + bfhi(fq.z) * bfhi(fq.z) + bflo(fq.w) * bflo(fq.w) + bfhi(fq.w) * bfhi(fq.w);
;             float c = bflo(fk.x) * bflo(fk.x) + bfhi(fk.x) * bfhi(fk.x) + bflo(fk.y) * bflo(fk.y) + bfhi(fk.y) * bfhi(fk.y)
;                     + bflo(fk.z) * bflo(fk.z) + bfhi(fk.z) * bfhi(fk.z) + bflo(fk.w) * bflo(fk.w) + bfhi(fk.w) * bfhi(fk.w);
;             a += __shfl_xor(a, 1); a += __shfl_xor(a, 2); a += __shfl_xor(a, 4);
;             c += __shfl_xor(c, 1); c += __shfl_xor(c, 2); c += __shfl_xor(c, 4);
;             qmx = fmaxf(qmx, a); kmx = fmaxf(kmx, c);
;         }
;         const int hd = lane >> 3, j0 = (lane & 7) * 2;
;         const float* rp = rope + (size_t)(b * TH + m) * 32;
;         const float* kr = S32 + (size_t)m * 64 + 32;
;         float x1a = kr[j0], x1b = kr[j0 + 1], x2a = kr[16 + j0], x2b = kr[16 + j0 + 1];
;         float ca = rp[j0], cb = rp[j0 + 1], sa = rp[16 + j0], sb = rp[16 + j0 + 1];
;         bf16_t* dst = KM + ((size_t)m * 8 + hd) * 96 + 64;
;         *(uint32_t*)(dst + j0) = pk2(x1a * ca - x2a * sa, x1b * cb - x2b * sb);
;         *(uint32_t*)(dst + 16 + j0) = pk2(x2a * ca + x1a * sa, x2b * cb + x1b * sb);
;     }
;     if ((lane & 7) == 0) { atomicMax(&nrm[lane >> 3], __float_as_uint(qmx)); atomicMax(&nrm[8 + (lane >> 3)], __float_as_uint(kmx)); }
.LBB0_648:
	s_or_b64 exec, exec, s[4:5]
	v_lshl_add_u64 v[16:17], v[14:15], 0, s[24:25]
	v_add_co_u32_e32 v30, vcc, 0x78a8000, v16
	s_mov_b32 s0, 0xf4a8000
	s_nop 0
	v_addc_co_u32_e32 v31, vcc, 0, v17, vcc
	s_waitcnt lgkmcnt(0)
	global_load_dwordx4 v[16:19], v[30:31], off
	s_nop 0
	global_load_dwordx4 v[30:33], v[30:31], off offset:1024
	s_add_i32 s6, s6, -1
	v_lshl_add_u64 v[4:5], v[4:5], 0, 4
	s_cmp_eq_u32 s6, 0
	s_waitcnt vmcnt(1)
	v_lshlrev_b32_e32 v34, 16, v16
	v_and_b32_e32 v35, 0xffff0000, v16
	v_pk_mul_f32 v[34:35], v[34:35], v[34:35]
	v_and_b32_e32 v16, 0xffff0000, v17
	v_lshlrev_b32_e32 v17, 16, v17
	v_pk_mul_f32 v[16:17], v[16:17], v[16:17]
	v_add_f32_e32 v29, v34, v35
	v_and_b32_e32 v36, 0xffff0000, v18
	v_lshlrev_b32_e32 v37, 16, v18
	v_add_f32_e32 v17, v17, v29
	v_pk_mul_f32 v[36:37], v[36:37], v[36:37]
	v_add_f32_e32 v16, v16, v17
	v_and_b32_e32 v18, 0xffff0000, v19
	v_lshlrev_b32_e32 v19, 16, v19
	v_add_f32_e32 v16, v37, v16
	v_pk_mul_f32 v[18:19], v[18:19], v[18:19]
	v_add_f32_e32 v16, v36, v16
	v_add_f32_e32 v16, v19, v16
	v_add_f32_e32 v29, v18, v16
	s_waitcnt vmcnt(0)
	v_lshlrev_b32_e32 v16, 16, v30
	v_and_b32_e32 v17, 0xffff0000, v30
	v_pk_mul_f32 v[16:17], v[16:17], v[16:17]
	v_and_b32_e32 v18, 0xffff0000, v31
	v_add_f32_e32 v16, v16, v17
	ds_bpermute_b32 v17, v20, v29
	v_lshlrev_b32_e32 v19, 16, v31
	v_pk_mul_f32 v[18:19], v[18:19], v[18:19]
	v_and_b32_e32 v30, 0xffff0000, v32
	v_add_f32_e32 v16, v19, v16
	s_waitcnt lgkmcnt(0)
	v_add_f32_e32 v17, v29, v17
	v_add_f32_e32 v16, v18, v16
	ds_bpermute_b32 v18, v21, v17
	v_lshlrev_b32_e32 v31, 16, v32
	v_pk_mul_f32 v[30:31], v[30:31], v[30:31]
	v_and_b32_e32 v32, 0xffff0000, v33
	v_lshlrev_b32_e32 v33, 16, v33
	s_waitcnt lgkmcnt(0)
	v_add_f32_e32 v17, v17, v18
	ds_bpermute_b32 v18, v22, v17
	v_add_f32_e32 v16, v31, v16
	v_pk_mul_f32 v[32:33], v[32:33], v[32:33]
	v_add_f32_e32 v16, v30, v16
	v_add_f32_e32 v16, v33, v16
	v_add_f32_e32 v16, v32, v16
	s_waitcnt lgkmcnt(0)
	v_add_f32_e32 v17, v17, v18
	ds_bpermute_b32 v18, v20, v16
	s_waitcnt lgkmcnt(0)
	v_add_f32_e32 v16, v16, v18
	ds_bpermute_b32 v18, v21, v16
	s_waitcnt lgkmcnt(0)
	v_add_f32_e32 v16, v16, v18
	ds_bpermute_b32 v18, v22, v16
	s_waitcnt lgkmcnt(0)
	v_add_f32_e32 v16, v16, v18
	v_max_f32_e32 v18, v27, v27
	v_max_f32_e32 v27, v18, v17
	v_max_f32_e32 v17, v28, v28
	v_max_f32_e32 v28, v17, v16
	v_lshl_add_u64 v[16:17], v[8:9], 0, s[24:25]
	v_add_co_u32_e32 v16, vcc, s0, v16
	v_lshl_add_u64 v[18:19], v[2:3], 0, s[24:25]
	s_nop 0
	v_addc_co_u32_e32 v17, vcc, 0, v17, vcc
	s_mov_b32 s0, 0x8000
	v_add_co_u32_e32 v18, vcc, s0, v18
	global_load_dwordx2 v[30:31], v[16:17], off offset:128
	s_nop 0
	global_load_dwordx2 v[16:17], v[16:17], off offset:192
	v_addc_co_u32_e32 v19, vcc, 0, v19, vcc
	global_load_dwordx2 v[32:33], v[18:19], off
	s_nop 0
	global_load_dwordx2 v[18:19], v[18:19], off offset:64
	s_mov_b32 s0, 0x120a8000
	v_lshl_add_u64 v[2:3], v[2:3], 0, s[16:17]
	v_lshl_add_u64 v[8:9], v[8:9], 0, s[92:93]
	s_waitcnt vmcnt(0)
	v_pk_mul_f32 v[34:35], v[16:17], v[18:19]
	s_nop 0
	v_pk_fma_f32 v[34:35], v[30:31], v[32:33], v[34:35] neg_lo:[0,0,1] neg_hi:[0,0,1]
	v_pk_mul_f32 v[18:19], v[30:31], v[18:19]
	v_cvt_pk_bf16_f32 v29, v34, v35
	v_lshl_add_u64 v[34:35], v[6:7], 0, s[24:25]
	v_add_co_u32_e32 v34, vcc, s0, v34
	s_mov_b64 s[0:1], 0x600
	v_fma_f32 v16, v16, v32, v18
	v_fma_f32 v17, v17, v33, v19
	v_lshl_add_u64 v[6:7], v[6:7], 0, s[0:1]
	s_mov_b64 s[0:1], 0x1f00
	v_addc_co_u32_e32 v35, vcc, 0, v35, vcc
	v_cvt_pk_bf16_f32 v16, v16, v17
	v_lshl_add_u64 v[10:11], v[10:11], 0, s[0:1]
	v_lshl_add_u64 v[12:13], v[12:13], 0, s[0:1]
	v_lshl_add_u64 v[14:15], v[14:15], 0, s[0:1]
	global_store_dword v[34:35], v29, off offset:128
	global_store_dword v[34:35], v16, off offset:160
	s_cbranch_scc1 .LBB0_651
.LBB0_649:
	v_lshl_add_u64 v[16:17], v[12:13], 0, s[24:25]
	global_load_dwordx2 v[16:17], v[16:17], off
	v_lshl_add_u64 v[18:19], v[10:11], 0, s[24:25]
	global_load_dword v29, v[18:19], off
	s_waitcnt vmcnt(1)
	v_lshlrev_b32_e32 v19, 16, v17
	v_lshlrev_b32_e32 v18, 16, v16
	v_and_b32_e32 v30, 0xffff0000, v16
	v_pk_mul_f32 v[18:19], v[18:19], v[18:19]
	v_and_b32_e32 v17, 0xffff0000, v17
	v_fma_f32 v16, v30, v30, v18
	s_waitcnt vmcnt(0)
	v_and_b32_e32 v18, 0xffff0000, v29
	v_add_f32_e32 v19, v19, v16
	v_lshlrev_b32_e32 v16, 16, v29
	v_mul_f32_e32 v18, v18, v18
	v_fma_f32 v16, v16, v16, v18
	v_fma_f32 v17, v17, v17, v19
	ds_bpermute_b32 v19, v20, v17
	ds_bpermute_b32 v18, v20, v16
	s_waitcnt lgkmcnt(0)
	v_pk_add_f32 v[16:17], v[16:17], v[18:19]
	ds_bpermute_b32 v19, v21, v17
	ds_bpermute_b32 v18, v21, v16
	s_waitcnt lgkmcnt(0)
	v_pk_add_f32 v[16:17], v[16:17], v[18:19]
	ds_bpermute_b32 v19, v22, v17
	ds_bpermute_b32 v18, v22, v16
	s_waitcnt lgkmcnt(0)
	v_pk_add_f32 v[16:17], v[16:17], v[18:19]
	ds_bpermute_b32 v19, v23, v17
	ds_bpermute_b32 v18, v23, v16
	s_waitcnt lgkmcnt(0)
	v_pk_add_f32 v[16:17], v[16:17], v[18:19]
	ds_bpermute_b32 v19, v24, v17
	ds_bpermute_b32 v18, v24, v16
	s_waitcnt lgkmcnt(0)
	v_pk_add_f32 v[16:17], v[16:17], v[18:19]
	ds_bpermute_b32 v19, v25, v17
	ds_bpermute_b32 v18, v25, v16
	s_and_saveexec_b64 s[4:5], s[40:41]
	s_cbranch_execz .LBB0_648
	s_brev_b32 s0, 60
	s_waitcnt lgkmcnt(0)
	v_pk_add_f32 v[16:17], v[16:17], v[18:19]
	s_mov_b32 s1, 0x3b800000
	v_pk_fma_f32 v[16:17], v[16:17], s[0:1], v[178:179] op_sel_hi:[1,1,0]
	s_mov_b32 s0, 0x800000
	v_mul_f32_e32 v18, 0x4b800000, v17
	v_cmp_gt_f32_e32 vcc, s0, v17
	v_cmp_gt_f32_e64 s[0:1], s0, v16
	s_nop 0
	v_cndmask_b32_e32 v17, v17, v18, vcc
	v_rsq_f32_e32 v17, v17
	v_lshl_add_u64 v[18:19], v[4:5], 0, s[24:25]
	v_mul_f32_e32 v29, 0x45800000, v17
	v_cndmask_b32_e32 v17, v17, v29, vcc
	v_mul_f32_e32 v29, 0x4b800000, v16
	v_cndmask_b32_e64 v16, v16, v29, s[0:1]
	v_rsq_f32_e32 v16, v16
	v_add_co_u32_e32 v30, vcc, 0x14928000, v18
	s_nop 1
	v_addc_co_u32_e32 v31, vcc, 0, v19, vcc
	global_store_dword v[30:31], v17, off
	v_mul_f32_e32 v17, 0x45800000, v16
	v_cndmask_b32_e64 v29, v16, v17, s[0:1]
	v_add_co_u32_e32 v16, vcc, 0x14938000, v18
	s_nop 1
	v_addc_co_u32_e32 v17, vcc, 0, v19, vcc
	global_store_dword v[16:17], v29, off
	s_branch .LBB0_648
